# peeled first K-iteration (C=0) in zero-init GEMM phases + K/V fragment-major + scan
# speedup vs baseline: 1.0157x; 1.0081x over previous
; __global__ void __launch_bounds__(NT, 2) hymba_fwd(Args args) {
;     ...
;         if (bid == 0) { const float* lg = args.in[7]; LBv[tid] = 1.0f / (1.0f + __expf(lg[512 + tid] - lg[tid])); }
.LBB0_148:
	s_cmp_eq_u32 s68, 0
	s_cbranch_scc0 .LBB0_150
	s_waitcnt vmcnt(31)
	v_lshlrev_b32_e32 v0, 2, v179
	global_load_dword v1, v0, s[26:27] offset:2048
	global_load_dword v2, v0, s[26:27]
	s_waitcnt vmcnt(0)
	v_sub_f32_e32 v1, v1, v2
	v_mul_f32_e32 v1, 0x3fb8aa3b, v1
	v_exp_f32_e32 v1, v1
	s_nop 0
	v_add_f32_e32 v1, 1.0, v1
	v_div_scale_f32 v2, s[4:5], v1, v1, 1.0
	v_rcp_f32_e32 v3, v2
	v_div_scale_f32 v4, vcc, 1.0, v1, 1.0
	s_load_dwordx2 s[4:5], s[0:1], 0x80
	s_waitcnt lgkmcnt(0)
	v_fma_f32 v5, -v2, v3, 1.0
	v_fmac_f32_e32 v3, v5, v3
	v_mul_f32_e32 v5, v4, v3
	v_fma_f32 v6, -v2, v5, v4
	v_fmac_f32_e32 v5, v6, v3
	v_fma_f32 v2, -v2, v5, v4
	v_div_fmas_f32 v2, v2, v3, v5
	v_div_fixup_f32 v1, v2, v1, 1.0
	global_store_dword v0, v1, s[4:5]
	v_lshrrev_b32_e32 v2, 4, v179
	v_lshrrev_b32_e32 v3, 2, v2
	v_mul_u32_u24_e32 v6, 0x204000, v3
	v_and_b32_e32 v2, 3, v2
	v_lshl_add_u32 v6, v2, 10, v6
	v_and_b32_e32 v2, 15, v179
	v_lshl_add_u32 v6, v2, 5, v6
	v_add_u32_e32 v6, 0xce83000, v6
	v_mov_b32_e32 v2, 0
	v_mov_b32_e32 v3, 0
	v_mov_b32_e32 v4, 0
	v_mov_b32_e32 v5, 0
	global_store_dwordx4 v6, v[2:5], s[4:5]
	global_store_dwordx4 v6, v[2:5], s[4:5] offset:16

; #define PG8_STAGE(bufoff, gbase, voff) do { _Pragma("unroll") for (int _i = 0; _i < 2; ++_i) \
;         __builtin_amdgcn_global_load_lds((const unsigned*)((const char*)(gbase) + (voff)[_i]), (PG8_LAS unsigned*)(lds + (bufoff) + ldsw + _i * 8192), 16, 0, 0); } while (0)
; template <class Epi, class Sched, bool ALIGN_EPI = false, bool SP2 = false>
; __device__ __forceinline__ void gemm_phase(PG8_LAS unsigned char* lds, const Gemm g, const Sched& S, const Epi& E) {
;     ...
; #pragma unroll
;     for (int a = 0; a < 2; ++a)
; #pragma unroll
;         for (int b = 0; b < 2; ++b)
; #pragma unroll
;             for (int m = 0; m < 4; ++m)
; #pragma unroll
;                 for (int n = 0; n < 2; ++n) acc[a][b][m][n] = (f32x4){0.f, 0.f, 0.f, 0.f};
;     ...
;         const char* nA = has_next ? (const char*)g.A + (size_t)nxt.pm * tstep : cA; const char* nB = has_next ? (const char*)g.Bt + (size_t)nxt.pn * tstep : cB;
;         for (int t = 0; t < nt; t += 2) {
;             const bool last = (t == nt - 2);
;             const char* a1 = cA + (size_t)(t + 1) * kstep;
;             const char* a2 = last ? nA : cA + (size_t)(t + 2) * kstep; const char* b2 = last ? nB : cB + (size_t)(t + 2) * kstep;
;             const char* a3 = a2 + kstep; const char* b3 = b2 + kstep;
;             if (last && has_next) S.a_ready(nxt);
;             if constexpr (SP2) {
;             PG8_LDB(B0, 0, 0); PG8_LDB(B1, 0, 1); PG8_SCHED; PG8_LDA(At, 0, 0); PG8_STAGE(PG8_SA(1, 1), a1 + hstep, voffA);
;             PG8_WAIT_V(8); PG8_WAIT_L(0); PG8_BAR; PG8_MMA(0, 0, At, B0); PG8_MMA(0, 1, At, B1); PG8_BAR; PG8_SCHED;
;             PG8_LDA(At, 0, 1); PG8_STAGE(PG8_SB(0, 0), b2, voffB); PG8_STAGE(PG8_SB(0, 1), b2 + hstep, voffB); PG8_STAGE(PG8_SA(0, 0), a2, voffA);
;             PG8_WAIT_V(8); PG8_WAIT_L(0); PG8_BAR; PG8_MMA(1, 0, At, B0); PG8_MMA(1, 1, At, B1); PG8_BAR; PG8_SCHED;
;             PG8_LDB(B0, 1, 0); PG8_LDB(B1, 1, 1); PG8_SCHED; PG8_LDA(At, 1, 0); PG8_STAGE(PG8_SA(0, 1), a2 + hstep, voffA);
;             PG8_WAIT_V(8); PG8_WAIT_L(0); PG8_BAR; PG8_MMA(0, 0, At, B0); PG8_MMA(0, 1, At, B1); PG8_BAR; PG8_SCHED;
;             PG8_LDA(At, 1, 1); PG8_STAGE(PG8_SB(1, 0), b3, voffB); PG8_STAGE(PG8_SB(1, 1), b3 + hstep, voffB); PG8_STAGE(PG8_SA(1, 0), a3, voffA);
;             PG8_WAIT_V(8); PG8_WAIT_L(0); PG8_BAR; PG8_MMA(1, 0, At, B0); PG8_MMA(1, 1, At, B1); PG8_BAR; PG8_SCHED;
.LBB0_232:
	s_ashr_i32 s29, s28, 31
	s_lshl_b64 s[30:31], s[28:29], 19
	s_add_u32 s30, s80, s30
	s_addc_u32 s31, s81, s31
	s_and_b64 s[34:35], s[6:7], exec
	s_cselect_b32 s29, s31, s39
	s_cselect_b32 s59, s30, s38
	s_ashr_i32 s27, s26, 31
	s_lshl_b64 s[34:35], s[26:27], 19
	s_add_u32 s34, s10, s34
	s_addc_u32 s35, s11, s35
	s_and_b64 s[44:45], s[6:7], exec
	s_cselect_b32 s27, s35, s41
	s_cselect_b32 s60, s34, s40
	s_add_u32 s38, s38, 0x40080
	s_addc_u32 s39, s39, 0
	s_add_u32 s61, s40, 0x100
	s_addc_u32 s62, s41, 0
	s_mov_b32 s63, -2
	ds_read_b128 v[144:147], v154
	ds_read_b128 v[158:161], v154 offset:1024
	ds_read_b128 v[162:165], v154 offset:2048
	ds_read_b128 v[166:169], v154 offset:3072
	ds_read_b128 v[170:173], v155
	ds_read_b128 v[174:177], v155 offset:1024
	ds_read_b128 v[180:183], v155 offset:2048
	ds_read_b128 v[184:187], v155 offset:3072
	s_add_u32 s40, s38, 0xfffc0080
	s_addc_u32 s41, s39, -1
	s_cmp_eq_u32 s63, 12
	s_cselect_b32 s45, s29, s41
	s_cselect_b32 s44, s59, s40
	s_cselect_b32 s41, s27, s62
	s_cselect_b32 s40, s60, s61
	v_lshl_add_u64 v[148:149], s[38:39], 0, v[136:137]
	s_add_i32 m0, s37, 0xc000
	ds_read_b128 v[188:191], v156
	ds_read_b128 v[192:195], v156 offset:1024
	ds_read_b128 v[196:199], v156 offset:2048
	ds_read_b128 v[200:203], v156 offset:3072
	ds_read_b128 v[204:207], v156 offset:4096
	ds_read_b128 v[208:211], v156 offset:5120
	ds_read_b128 v[212:215], v156 offset:6144
	ds_read_b128 v[216:219], v156 offset:7168
	global_load_lds_dwordx4 v[148:149], off
	v_lshl_add_u64 v[148:149], s[38:39], 0, v[138:139]
	s_add_i32 m0, s37, 0xe000
	s_nop 0
	global_load_lds_dwordx4 v[148:149], off
	s_waitcnt vmcnt(8)
	s_waitcnt lgkmcnt(0)
	s_barrier
	s_setprio 1
	s_waitcnt lgkmcnt(0)
	v_mfma_f32_16x16x32_bf16 v[124:127], v[144:147], v[188:191], 0
	v_mfma_f32_16x16x32_bf16 v[116:119], v[162:165], v[188:191], 0
	v_mfma_f32_16x16x32_bf16 v[108:111], v[144:147], v[196:199], 0
	v_mfma_f32_16x16x32_bf16 v[100:103], v[162:165], v[196:199], 0
	v_mfma_f32_16x16x32_bf16 v[92:95], v[144:147], v[204:207], 0
	v_mfma_f32_16x16x32_bf16 v[84:87], v[162:165], v[204:207], 0
	v_mfma_f32_16x16x32_bf16 v[76:79], v[144:147], v[212:215], 0
	v_mfma_f32_16x16x32_bf16 v[68:71], v[162:165], v[212:215], 0
	v_mfma_f32_16x16x32_bf16 v[124:127], v[158:161], v[192:195], v[124:127]
	v_mfma_f32_16x16x32_bf16 v[116:119], v[166:169], v[192:195], v[116:119]
	v_mfma_f32_16x16x32_bf16 v[108:111], v[158:161], v[200:203], v[108:111]
	v_mfma_f32_16x16x32_bf16 v[100:103], v[166:169], v[200:203], v[100:103]
	v_mfma_f32_16x16x32_bf16 v[92:95], v[158:161], v[208:211], v[92:95]
	v_mfma_f32_16x16x32_bf16 v[84:87], v[166:169], v[208:211], v[84:87]
	v_mfma_f32_16x16x32_bf16 v[76:79], v[158:161], v[216:219], v[76:79]
	v_mfma_f32_16x16x32_bf16 v[68:71], v[166:169], v[216:219], v[68:71]
	s_setprio 0
	s_setprio 1
	v_mfma_f32_16x16x32_bf16 v[120:123], v[170:173], v[188:191], 0
	v_mfma_f32_16x16x32_bf16 v[112:115], v[180:183], v[188:191], 0
	v_mfma_f32_16x16x32_bf16 v[104:107], v[170:173], v[196:199], 0
	v_mfma_f32_16x16x32_bf16 v[96:99], v[180:183], v[196:199], 0
	v_mfma_f32_16x16x32_bf16 v[88:91], v[170:173], v[204:207], 0
	v_mfma_f32_16x16x32_bf16 v[80:83], v[180:183], v[204:207], 0
	v_mfma_f32_16x16x32_bf16 v[72:75], v[170:173], v[212:215], 0
	v_mfma_f32_16x16x32_bf16 v[64:67], v[180:183], v[212:215], 0
	v_mfma_f32_16x16x32_bf16 v[120:123], v[174:177], v[192:195], v[120:123]
	v_mfma_f32_16x16x32_bf16 v[112:115], v[184:187], v[192:195], v[112:115]
	v_mfma_f32_16x16x32_bf16 v[104:107], v[174:177], v[200:203], v[104:107]
	v_mfma_f32_16x16x32_bf16 v[96:99], v[184:187], v[200:203], v[96:99]
	v_mfma_f32_16x16x32_bf16 v[88:91], v[174:177], v[208:211], v[88:91]
	v_mfma_f32_16x16x32_bf16 v[80:83], v[184:187], v[208:211], v[80:83]
	v_mfma_f32_16x16x32_bf16 v[72:75], v[174:177], v[216:219], v[72:75]
	v_mfma_f32_16x16x32_bf16 v[64:67], v[184:187], v[216:219], v[64:67]
	s_setprio 0
	s_barrier
	s_add_i32 s64, s53, s33
	v_lshl_add_u64 v[148:149], s[40:41], 0, v[130:131]
	s_mov_b32 m0, s64
	ds_read_b128 v[188:191], v156 offset:16384
	ds_read_b128 v[192:195], v156 offset:17408
	ds_read_b128 v[196:199], v156 offset:18432
	ds_read_b128 v[200:203], v156 offset:19456
	ds_read_b128 v[204:207], v156 offset:20480
	ds_read_b128 v[208:211], v156 offset:21504
	ds_read_b128 v[212:215], v156 offset:22528
	ds_read_b128 v[216:219], v156 offset:23552
	global_load_lds_dwordx4 v[148:149], off
	s_add_i32 m0, s64, 0x2000
	s_add_u32 s64, s40, 0x40000
	v_lshl_add_u64 v[220:221], s[40:41], 0, v[134:135]
	s_addc_u32 s65, s41, 0
	s_add_i32 s66, s54, s33
	global_load_lds_dwordx4 v[220:221], off
	v_lshl_add_u64 v[222:223], s[64:65], 0, v[130:131]
	s_mov_b32 m0, s66
	v_lshl_add_u64 v[224:225], s[44:45], 0, v[132:133]
	global_load_lds_dwordx4 v[222:223], off
	v_lshl_add_u64 v[222:223], s[64:65], 0, v[134:135]
	s_add_i32 m0, s66, 0x2000
	s_nop 0
	global_load_lds_dwordx4 v[222:223], off
	v_lshl_add_u64 v[222:223], s[44:45], 0, v[128:129]
	s_mov_b32 m0, s37
	s_nop 0
	global_load_lds_dwordx4 v[222:223], off
	s_mov_b32 m0, s46
	s_nop 0
	global_load_lds_dwordx4 v[224:225], off
	s_waitcnt vmcnt(8)
	s_waitcnt lgkmcnt(0)
	s_barrier
; #define PG8_STAGE(bufoff, gbase, voff) do { _Pragma("unroll") for (int _i = 0; _i < 2; ++_i) \
;         __builtin_amdgcn_global_load_lds((const unsigned*)((const char*)(gbase) + (voff)[_i]), (PG8_LAS unsigned*)(lds + (bufoff) + ldsw + _i * 8192), 16, 0, 0); } while (0)
; #define PG8_LDA(dst, b, h) do { _Pragma("unroll") for (int m = 0; m < 4; ++m) _Pragma("unroll") for (int k = 0; k < 2; ++k) dst[m][k] = *(const PG8_LAS bf16x8*)(lds + PG8_SA(b, h) + aoff + m * 2048 + k * 1024); } while (0)
; #define PG8_LDB(dst, b, h) do { _Pragma("unroll") for (int n = 0; n < 2; ++n) _Pragma("unroll") for (int k = 0; k < 2; ++k) dst[n][k] = *(const PG8_LAS bf16x8*)(lds + PG8_SB(b, h) + boff + n * 2048 + k * 1024); } while (0)
; #define PG8_MMA(ai, bj, At, Bt) do { __builtin_amdgcn_s_setprio(1); _Pragma("unroll") for (int m = 0; m < 4; ++m) _Pragma("unroll") for (int n = 0; n < 2; ++n) _Pragma("unroll") for (int k = 0; k < 2; ++k) \
;         acc[ai][bj][m][n] = __builtin_amdgcn_mfma_f32_16x16x32_bf16(Bt[n][k], At[m][k], acc[ai][bj][m][n], 0, 0, 0); __builtin_amdgcn_s_setprio(0); } while (0)
; #define PG8_WAIT_V(n) asm volatile("s_waitcnt vmcnt(" #n ")" ::: "memory")
; template <class Epi, class Sched, bool ALIGN_EPI = false, bool SP2 = false>
; __device__ __forceinline__ void gemm_phase(PG8_LAS unsigned char* lds, const Gemm g, const Sched& S, const Epi& E) {
;     ...
;             PG8_LDB(B0, 0, 0); PG8_LDB(B1, 0, 1); PG8_SCHED; PG8_LDA(At, 0, 0); PG8_STAGE(PG8_SA(1, 1), a1 + hstep, voffA);
;             PG8_WAIT_V(8); PG8_WAIT_L(0); PG8_BAR; PG8_MMA(0, 0, At, B0); PG8_MMA(0, 1, At, B1); PG8_BAR; PG8_SCHED;
;             PG8_LDA(At, 0, 1); PG8_STAGE(PG8_SB(0, 0), b2, voffB); PG8_STAGE(PG8_SB(0, 1), b2 + hstep, voffB); PG8_STAGE(PG8_SA(0, 0), a2, voffA);
;             PG8_WAIT_V(8); PG8_WAIT_L(0); PG8_BAR; PG8_MMA(1, 0, At, B0); PG8_MMA(1, 1, At, B1); PG8_BAR; PG8_SCHED;
;             PG8_LDB(B0, 1, 0); PG8_LDB(B1, 1, 1); PG8_SCHED; PG8_LDA(At, 1, 0); PG8_STAGE(PG8_SA(0, 1), a2 + hstep, voffA);
;             PG8_WAIT_V(8); PG8_WAIT_L(0); PG8_BAR; PG8_MMA(0, 0, At, B0); PG8_MMA(0, 1, At, B1); PG8_BAR; PG8_SCHED;
;             PG8_LDA(At, 1, 1); PG8_STAGE(PG8_SB(1, 0), b3, voffB); PG8_STAGE(PG8_SB(1, 1), b3 + hstep, voffB); PG8_STAGE(PG8_SA(1, 0), a3, voffA);
;             PG8_WAIT_V(8); PG8_WAIT_L(0); PG8_BAR; PG8_MMA(1, 0, At, B0); PG8_MMA(1, 1, At, B1); PG8_BAR; PG8_SCHED;
	s_setprio 1
	s_waitcnt lgkmcnt(0)
	v_mfma_f32_16x16x32_bf16 v[60:63], v[144:147], v[188:191], 0
	v_mfma_f32_16x16x32_bf16 v[52:55], v[162:165], v[188:191], 0
	v_mfma_f32_16x16x32_bf16 v[44:47], v[144:147], v[196:199], 0
	v_mfma_f32_16x16x32_bf16 v[36:39], v[162:165], v[196:199], 0
	v_mfma_f32_16x16x32_bf16 v[28:31], v[144:147], v[204:207], 0
	v_mfma_f32_16x16x32_bf16 v[20:23], v[162:165], v[204:207], 0
	v_mfma_f32_16x16x32_bf16 v[12:15], v[144:147], v[212:215], 0
	v_mfma_f32_16x16x32_bf16 v[4:7], v[162:165], v[212:215], 0
	v_mfma_f32_16x16x32_bf16 v[60:63], v[158:161], v[192:195], v[60:63]
	v_mfma_f32_16x16x32_bf16 v[52:55], v[166:169], v[192:195], v[52:55]
	v_mfma_f32_16x16x32_bf16 v[44:47], v[158:161], v[200:203], v[44:47]
	v_mfma_f32_16x16x32_bf16 v[36:39], v[166:169], v[200:203], v[36:39]
	v_mfma_f32_16x16x32_bf16 v[28:31], v[158:161], v[208:211], v[28:31]
	v_mfma_f32_16x16x32_bf16 v[20:23], v[166:169], v[208:211], v[20:23]
	v_mfma_f32_16x16x32_bf16 v[12:15], v[158:161], v[216:219], v[12:15]
	v_mfma_f32_16x16x32_bf16 v[4:7], v[166:169], v[216:219], v[4:7]
	s_setprio 0
	s_setprio 1
	v_mfma_f32_16x16x32_bf16 v[56:59], v[170:173], v[188:191], 0
	v_mfma_f32_16x16x32_bf16 v[48:51], v[180:183], v[188:191], 0
	v_mfma_f32_16x16x32_bf16 v[40:43], v[170:173], v[196:199], 0
	v_mfma_f32_16x16x32_bf16 v[32:35], v[180:183], v[196:199], 0
	v_mfma_f32_16x16x32_bf16 v[24:27], v[170:173], v[204:207], 0
	v_mfma_f32_16x16x32_bf16 v[16:19], v[180:183], v[204:207], 0
	v_mfma_f32_16x16x32_bf16 v[8:11], v[170:173], v[212:215], 0
	v_mfma_f32_16x16x32_bf16 v[0:3], v[180:183], v[212:215], 0
	v_mfma_f32_16x16x32_bf16 v[56:59], v[174:177], v[192:195], v[56:59]
	v_mfma_f32_16x16x32_bf16 v[48:51], v[184:187], v[192:195], v[48:51]
	v_mfma_f32_16x16x32_bf16 v[40:43], v[174:177], v[200:203], v[40:43]
	v_mfma_f32_16x16x32_bf16 v[32:35], v[184:187], v[200:203], v[32:35]
	v_mfma_f32_16x16x32_bf16 v[24:27], v[174:177], v[208:211], v[24:27]
	v_mfma_f32_16x16x32_bf16 v[16:19], v[184:187], v[208:211], v[16:19]
	v_mfma_f32_16x16x32_bf16 v[8:11], v[174:177], v[216:219], v[8:11]
	v_mfma_f32_16x16x32_bf16 v[0:3], v[184:187], v[216:219], v[0:3]
	s_setprio 0
	s_barrier
	s_add_i32 s64, 0, 0x18000
	v_add_u32_e32 v157, s64, v151
	s_add_i32 s65, 0, 0x1c000
	ds_read_b128 v[144:147], v157
	ds_read_b128 v[158:161], v157 offset:1024
	ds_read_b128 v[162:165], v157 offset:2048
	ds_read_b128 v[166:169], v157 offset:3072
	v_add_u32_e32 v157, s65, v151
	ds_read_b128 v[170:173], v157
	ds_read_b128 v[174:177], v157 offset:1024
	ds_read_b128 v[180:183], v157 offset:2048
	ds_read_b128 v[184:187], v157 offset:3072
	s_add_u32 s44, s44, 0x40000
	s_addc_u32 s45, s45, 0
	s_mov_b32 m0, s47
	v_lshl_add_u64 v[226:227], s[44:45], 0, v[128:129]
	ds_read_b128 v[188:191], v156 offset:32768
	ds_read_b128 v[192:195], v156 offset:33792
	ds_read_b128 v[196:199], v156 offset:34816
	ds_read_b128 v[200:203], v156 offset:35840
	ds_read_b128 v[204:207], v156 offset:36864
	ds_read_b128 v[208:211], v156 offset:37888
	ds_read_b128 v[212:215], v156 offset:38912
	ds_read_b128 v[216:219], v156 offset:39936
	global_load_lds_dwordx4 v[226:227], off
	v_lshl_add_u64 v[226:227], s[44:45], 0, v[132:133]
	s_mov_b32 m0, s48
	s_nop 0
	global_load_lds_dwordx4 v[226:227], off
	s_waitcnt vmcnt(8)
	s_waitcnt lgkmcnt(0)
	s_barrier
	s_setprio 1
	s_waitcnt lgkmcnt(0)
	v_mfma_f32_16x16x32_bf16 v[124:127], v[144:147], v[188:191], v[124:127]
	v_mfma_f32_16x16x32_bf16 v[116:119], v[162:165], v[188:191], v[116:119]
	v_mfma_f32_16x16x32_bf16 v[108:111], v[144:147], v[196:199], v[108:111]
	v_mfma_f32_16x16x32_bf16 v[100:103], v[162:165], v[196:199], v[100:103]
	v_mfma_f32_16x16x32_bf16 v[92:95], v[144:147], v[204:207], v[92:95]
	v_mfma_f32_16x16x32_bf16 v[84:87], v[162:165], v[204:207], v[84:87]
	v_mfma_f32_16x16x32_bf16 v[76:79], v[144:147], v[212:215], v[76:79]
	v_mfma_f32_16x16x32_bf16 v[68:71], v[162:165], v[212:215], v[68:71]
	v_mfma_f32_16x16x32_bf16 v[124:127], v[158:161], v[192:195], v[124:127]
	v_mfma_f32_16x16x32_bf16 v[116:119], v[166:169], v[192:195], v[116:119]
	v_mfma_f32_16x16x32_bf16 v[108:111], v[158:161], v[200:203], v[108:111]
	v_mfma_f32_16x16x32_bf16 v[100:103], v[166:169], v[200:203], v[100:103]
	v_mfma_f32_16x16x32_bf16 v[92:95], v[158:161], v[208:211], v[92:95]
	v_mfma_f32_16x16x32_bf16 v[84:87], v[166:169], v[208:211], v[84:87]
	v_mfma_f32_16x16x32_bf16 v[76:79], v[158:161], v[216:219], v[76:79]
	v_mfma_f32_16x16x32_bf16 v[68:71], v[166:169], v[216:219], v[68:71]
	s_setprio 0
	s_setprio 1
	v_mfma_f32_16x16x32_bf16 v[120:123], v[170:173], v[188:191], v[120:123]
	v_mfma_f32_16x16x32_bf16 v[112:115], v[180:183], v[188:191], v[112:115]
	v_mfma_f32_16x16x32_bf16 v[104:107], v[170:173], v[196:199], v[104:107]
	v_mfma_f32_16x16x32_bf16 v[96:99], v[180:183], v[196:199], v[96:99]
	v_mfma_f32_16x16x32_bf16 v[88:91], v[170:173], v[204:207], v[88:91]
	v_mfma_f32_16x16x32_bf16 v[80:83], v[180:183], v[204:207], v[80:83]
	v_mfma_f32_16x16x32_bf16 v[72:75], v[170:173], v[212:215], v[72:75]
	v_mfma_f32_16x16x32_bf16 v[64:67], v[180:183], v[212:215], v[64:67]
	v_mfma_f32_16x16x32_bf16 v[120:123], v[174:177], v[192:195], v[120:123]
	v_mfma_f32_16x16x32_bf16 v[112:115], v[184:187], v[192:195], v[112:115]
	v_mfma_f32_16x16x32_bf16 v[104:107], v[174:177], v[200:203], v[104:107]
	v_mfma_f32_16x16x32_bf16 v[96:99], v[184:187], v[200:203], v[96:99]
	v_mfma_f32_16x16x32_bf16 v[88:91], v[174:177], v[208:211], v[88:91]
	v_mfma_f32_16x16x32_bf16 v[80:83], v[184:187], v[208:211], v[80:83]
	v_mfma_f32_16x16x32_bf16 v[72:75], v[174:177], v[216:219], v[72:75]
	v_mfma_f32_16x16x32_bf16 v[64:67], v[184:187], v[216:219], v[64:67]
	s_setprio 0
	s_barrier
; #define PG8_STAGE(bufoff, gbase, voff) do { _Pragma("unroll") for (int _i = 0; _i < 2; ++_i) \
;         __builtin_amdgcn_global_load_lds((const unsigned*)((const char*)(gbase) + (voff)[_i]), (PG8_LAS unsigned*)(lds + (bufoff) + ldsw + _i * 8192), 16, 0, 0); } while (0)
; #define PG8_LDA(dst, b, h) do { _Pragma("unroll") for (int m = 0; m < 4; ++m) _Pragma("unroll") for (int k = 0; k < 2; ++k) dst[m][k] = *(const PG8_LAS bf16x8*)(lds + PG8_SA(b, h) + aoff + m * 2048 + k * 1024); } while (0)
; #define PG8_LDB(dst, b, h) do { _Pragma("unroll") for (int n = 0; n < 2; ++n) _Pragma("unroll") for (int k = 0; k < 2; ++k) dst[n][k] = *(const PG8_LAS bf16x8*)(lds + PG8_SB(b, h) + boff + n * 2048 + k * 1024); } while (0)
; template <class Epi, class Sched, bool ALIGN_EPI = false, bool SP2 = false>
; __device__ __forceinline__ void gemm_phase(PG8_LAS unsigned char* lds, const Gemm g, const Sched& S, const Epi& E) {
;     ...
;         for (int t = 0; t < nt; t += 2) {
;             const bool last = (t == nt - 2);
;             const char* a1 = cA + (size_t)(t + 1) * kstep;
;             const char* a2 = last ? nA : cA + (size_t)(t + 2) * kstep; const char* b2 = last ? nB : cB + (size_t)(t + 2) * kstep;
;             const char* a3 = a2 + kstep; const char* b3 = b2 + kstep;
;             if (last && has_next) S.a_ready(nxt);
;             if constexpr (SP2) {
;             PG8_LDB(B0, 0, 0); PG8_LDB(B1, 0, 1); PG8_SCHED; PG8_LDA(At, 0, 0); PG8_STAGE(PG8_SA(1, 1), a1 + hstep, voffA);
;             PG8_WAIT_V(8); PG8_WAIT_L(0); PG8_BAR; PG8_MMA(0, 0, At, B0); PG8_MMA(0, 1, At, B1); PG8_BAR; PG8_SCHED;
;             PG8_LDA(At, 0, 1); PG8_STAGE(PG8_SB(0, 0), b2, voffB); PG8_STAGE(PG8_SB(0, 1), b2 + hstep, voffB); PG8_STAGE(PG8_SA(0, 0), a2, voffA);
;             PG8_WAIT_V(8); PG8_WAIT_L(0); PG8_BAR; PG8_MMA(1, 0, At, B0); PG8_MMA(1, 1, At, B1); PG8_BAR; PG8_SCHED;
;             PG8_LDB(B0, 1, 0); PG8_LDB(B1, 1, 1); PG8_SCHED; PG8_LDA(At, 1, 0); PG8_STAGE(PG8_SA(0, 1), a2 + hstep, voffA);
;             PG8_WAIT_V(8); PG8_WAIT_L(0); PG8_BAR; PG8_MMA(0, 0, At, B0); PG8_MMA(0, 1, At, B1); PG8_BAR; PG8_SCHED;
;             PG8_LDA(At, 1, 1); PG8_STAGE(PG8_SB(1, 0), b3, voffB); PG8_STAGE(PG8_SB(1, 1), b3 + hstep, voffB); PG8_STAGE(PG8_SA(1, 0), a3, voffA);
;             PG8_WAIT_V(8); PG8_WAIT_L(0); PG8_BAR; PG8_MMA(1, 0, At, B0); PG8_MMA(1, 1, At, B1); PG8_BAR; PG8_SCHED;
	s_add_i32 s44, s64, s33
	v_lshl_add_u64 v[148:149], v[148:149], 0, s[16:17]
	s_mov_b32 m0, s44
	ds_read_b128 v[188:191], v156 offset:49152
	ds_read_b128 v[192:195], v156 offset:50176
	ds_read_b128 v[196:199], v156 offset:51200
	ds_read_b128 v[200:203], v156 offset:52224
	ds_read_b128 v[204:207], v156 offset:53248
	ds_read_b128 v[208:211], v156 offset:54272
	ds_read_b128 v[212:215], v156 offset:55296
	ds_read_b128 v[216:219], v156 offset:56320
	global_load_lds_dwordx4 v[148:149], off
	s_add_i32 m0, s44, 0x2000
	s_add_u32 s40, s40, 0x40080
	v_lshl_add_u64 v[148:149], v[220:221], 0, s[16:17]
	s_addc_u32 s41, s41, 0
	s_add_i32 s44, s65, s33
	global_load_lds_dwordx4 v[148:149], off
	v_lshl_add_u64 v[148:149], s[40:41], 0, v[130:131]
	s_mov_b32 m0, s44
	s_nop 0
	global_load_lds_dwordx4 v[148:149], off
	v_lshl_add_u64 v[148:149], s[40:41], 0, v[134:135]
	s_add_i32 m0, s44, 0x2000
	s_nop 0
	global_load_lds_dwordx4 v[148:149], off
	v_lshl_add_u64 v[148:149], v[222:223], 0, s[16:17]
	s_mov_b32 m0, s51
	s_nop 0
	global_load_lds_dwordx4 v[148:149], off
	v_lshl_add_u64 v[148:149], v[224:225], 0, s[16:17]
	s_mov_b32 m0, s52
	s_nop 0
	global_load_lds_dwordx4 v[148:149], off
	s_waitcnt vmcnt(8)
	s_waitcnt lgkmcnt(0)
	s_barrier
	s_setprio 1
	s_waitcnt lgkmcnt(0)
	v_mfma_f32_16x16x32_bf16 v[60:63], v[144:147], v[188:191], v[60:63]
	v_mfma_f32_16x16x32_bf16 v[52:55], v[162:165], v[188:191], v[52:55]
	v_mfma_f32_16x16x32_bf16 v[44:47], v[144:147], v[196:199], v[44:47]
	v_mfma_f32_16x16x32_bf16 v[36:39], v[162:165], v[196:199], v[36:39]
	v_mfma_f32_16x16x32_bf16 v[28:31], v[144:147], v[204:207], v[28:31]
	v_mfma_f32_16x16x32_bf16 v[20:23], v[162:165], v[204:207], v[20:23]
	v_mfma_f32_16x16x32_bf16 v[12:15], v[144:147], v[212:215], v[12:15]
	v_mfma_f32_16x16x32_bf16 v[4:7], v[162:165], v[212:215], v[4:7]
	v_mfma_f32_16x16x32_bf16 v[60:63], v[158:161], v[192:195], v[60:63]
	v_mfma_f32_16x16x32_bf16 v[52:55], v[166:169], v[192:195], v[52:55]
	v_mfma_f32_16x16x32_bf16 v[44:47], v[158:161], v[200:203], v[44:47]
	v_mfma_f32_16x16x32_bf16 v[36:39], v[166:169], v[200:203], v[36:39]
	v_mfma_f32_16x16x32_bf16 v[28:31], v[158:161], v[208:211], v[28:31]
	v_mfma_f32_16x16x32_bf16 v[20:23], v[166:169], v[208:211], v[20:23]
	v_mfma_f32_16x16x32_bf16 v[12:15], v[158:161], v[216:219], v[12:15]
	v_mfma_f32_16x16x32_bf16 v[4:7], v[166:169], v[216:219], v[4:7]
	s_setprio 0
	s_setprio 1
	v_mfma_f32_16x16x32_bf16 v[56:59], v[170:173], v[188:191], v[56:59]
	v_mfma_f32_16x16x32_bf16 v[48:51], v[180:183], v[188:191], v[48:51]
	v_mfma_f32_16x16x32_bf16 v[40:43], v[170:173], v[196:199], v[40:43]
	v_mfma_f32_16x16x32_bf16 v[32:35], v[180:183], v[196:199], v[32:35]
	v_mfma_f32_16x16x32_bf16 v[24:27], v[170:173], v[204:207], v[24:27]
	v_mfma_f32_16x16x32_bf16 v[16:19], v[180:183], v[204:207], v[16:19]
	v_mfma_f32_16x16x32_bf16 v[8:11], v[170:173], v[212:215], v[8:11]
	v_mfma_f32_16x16x32_bf16 v[0:3], v[180:183], v[212:215], v[0:3]
	v_mfma_f32_16x16x32_bf16 v[56:59], v[174:177], v[192:195], v[56:59]
	v_mfma_f32_16x16x32_bf16 v[48:51], v[184:187], v[192:195], v[48:51]
	v_mfma_f32_16x16x32_bf16 v[40:43], v[174:177], v[200:203], v[40:43]
	v_mfma_f32_16x16x32_bf16 v[32:35], v[184:187], v[200:203], v[32:35]
	v_mfma_f32_16x16x32_bf16 v[24:27], v[174:177], v[208:211], v[24:27]
	v_mfma_f32_16x16x32_bf16 v[16:19], v[184:187], v[208:211], v[16:19]
	v_mfma_f32_16x16x32_bf16 v[8:11], v[174:177], v[216:219], v[8:11]
	v_mfma_f32_16x16x32_bf16 v[0:3], v[184:187], v[216:219], v[0:3]
	s_setprio 0
	s_barrier
	s_add_i32 s63, s63, 2
	s_add_u32 s38, s38, 0x100
	s_addc_u32 s39, s39, 0
	s_add_u32 s61, s61, 0x100
	s_addc_u32 s62, s62, 0
	s_cmp_gt_u32 s63, 13
	s_cbranch_scc0 .LBB0_233

; #define PG8_STAGE(bufoff, gbase, voff) do { _Pragma("unroll") for (int _i = 0; _i < 2; ++_i) \
;         __builtin_amdgcn_global_load_lds((const unsigned*)((const char*)(gbase) + (voff)[_i]), (PG8_LAS unsigned*)(lds + (bufoff) + ldsw + _i * 8192), 16, 0, 0); } while (0)
; template <class Epi, class Sched, bool ALIGN_EPI = false, bool SP2 = false>
; __device__ __forceinline__ void gemm_phase(PG8_LAS unsigned char* lds, const Gemm g, const Sched& S, const Epi& E) {
;     ...
; #pragma unroll
;     for (int a = 0; a < 2; ++a)
; #pragma unroll
;         for (int b = 0; b < 2; ++b)
; #pragma unroll
;             for (int m = 0; m < 4; ++m)
; #pragma unroll
;                 for (int n = 0; n < 2; ++n) acc[a][b][m][n] = (f32x4){0.f, 0.f, 0.f, 0.f};
;     ...
;         const char* nA = has_next ? (const char*)g.A + (size_t)nxt.pm * tstep : cA; const char* nB = has_next ? (const char*)g.Bt + (size_t)nxt.pn * tstep : cB;
;         for (int t = 0; t < nt; t += 2) {
;             const bool last = (t == nt - 2);
;             const char* a1 = cA + (size_t)(t + 1) * kstep;
;             const char* a2 = last ? nA : cA + (size_t)(t + 2) * kstep; const char* b2 = last ? nB : cB + (size_t)(t + 2) * kstep;
;             const char* a3 = a2 + kstep; const char* b3 = b2 + kstep;
;             if (last && has_next) S.a_ready(nxt);
;             if constexpr (SP2) {
;             PG8_LDB(B0, 0, 0); PG8_LDB(B1, 0, 1); PG8_SCHED; PG8_LDA(At, 0, 0); PG8_STAGE(PG8_SA(1, 1), a1 + hstep, voffA);
;             PG8_WAIT_V(8); PG8_WAIT_L(0); PG8_BAR; PG8_MMA(0, 0, At, B0); PG8_MMA(0, 1, At, B1); PG8_BAR; PG8_SCHED;
;             PG8_LDA(At, 0, 1); PG8_STAGE(PG8_SB(0, 0), b2, voffB); PG8_STAGE(PG8_SB(0, 1), b2 + hstep, voffB); PG8_STAGE(PG8_SA(0, 0), a2, voffA);
;             PG8_WAIT_V(8); PG8_WAIT_L(0); PG8_BAR; PG8_MMA(1, 0, At, B0); PG8_MMA(1, 1, At, B1); PG8_BAR; PG8_SCHED;
;             PG8_LDB(B0, 1, 0); PG8_LDB(B1, 1, 1); PG8_SCHED; PG8_LDA(At, 1, 0); PG8_STAGE(PG8_SA(0, 1), a2 + hstep, voffA);
;             PG8_WAIT_V(8); PG8_WAIT_L(0); PG8_BAR; PG8_MMA(0, 0, At, B0); PG8_MMA(0, 1, At, B1); PG8_BAR; PG8_SCHED;
;             PG8_LDA(At, 1, 1); PG8_STAGE(PG8_SB(1, 0), b3, voffB); PG8_STAGE(PG8_SB(1, 1), b3 + hstep, voffB); PG8_STAGE(PG8_SA(1, 0), a3, voffA);
;             PG8_WAIT_V(8); PG8_WAIT_L(0); PG8_BAR; PG8_MMA(1, 0, At, B0); PG8_MMA(1, 1, At, B1); PG8_BAR; PG8_SCHED;
.LBB0_505:
	s_ashr_i32 s27, s26, 31
	s_lshl_b64 s[4:5], s[26:27], 19
	s_add_u32 s28, s80, s4
	s_addc_u32 s29, s81, s5
	s_and_b64 s[4:5], s[0:1], exec
	s_cselect_b32 s9, s29, s37
	s_cselect_b32 s27, s28, s36
	s_ashr_i32 s25, s24, 31
	s_lshl_b64 s[4:5], s[24:25], 19
	s_add_u32 s30, s2, s4
	s_addc_u32 s31, s3, s5
	s_and_b64 s[4:5], s[0:1], exec
	s_cselect_b32 s25, s31, s35
	s_cselect_b32 s56, s30, s34
	s_add_u32 s4, s36, 0x40080
	s_addc_u32 s5, s37, 0
	s_add_u32 s57, s34, 0x100
	s_addc_u32 s58, s35, 0
	s_mov_b32 s59, -2
	ds_read_b128 v[128:131], v181
	ds_read_b128 v[132:135], v181 offset:1024
	ds_read_b128 v[136:139], v181 offset:2048
	ds_read_b128 v[140:143], v181 offset:3072
	s_waitcnt lgkmcnt(0)
	ds_read_b128 v[162:165], v182
	ds_read_b128 v[166:169], v182 offset:1024
	ds_read_b128 v[170:173], v182 offset:2048
	ds_read_b128 v[188:191], v182 offset:3072
	s_add_u32 s34, s4, 0xfffc0080
	s_addc_u32 s35, s5, -1
	s_cmp_eq_u32 s59, 12
	s_cselect_b32 s37, s9, s35
	s_cselect_b32 s36, s27, s34
	s_cselect_b32 s35, s25, s58
	s_cselect_b32 s34, s56, s57
	v_lshl_add_u64 v[224:225], s[4:5], 0, v[154:155]
	s_add_i32 m0, s38, 0xc000
	ds_read_b128 v[192:195], v183
	ds_read_b128 v[196:199], v183 offset:1024
	ds_read_b128 v[200:203], v183 offset:2048
	ds_read_b128 v[204:207], v183 offset:3072
	ds_read_b128 v[208:211], v183 offset:4096
	ds_read_b128 v[212:215], v183 offset:5120
	ds_read_b128 v[216:219], v183 offset:6144
	ds_read_b128 v[220:223], v183 offset:7168
	global_load_lds_dwordx4 v[224:225], off
	v_lshl_add_u64 v[224:225], s[4:5], 0, v[156:157]
	s_add_i32 m0, s38, 0xe000
	s_nop 0
	global_load_lds_dwordx4 v[224:225], off
	s_waitcnt vmcnt(8)
	s_waitcnt lgkmcnt(0)
	s_barrier
	s_setprio 1
	s_waitcnt lgkmcnt(0)
	v_mfma_f32_16x16x32_bf16 v[124:127], v[128:131], v[192:195], 0
	v_mfma_f32_16x16x32_bf16 v[120:123], v[136:139], v[192:195], 0
	v_mfma_f32_16x16x32_bf16 v[108:111], v[128:131], v[200:203], 0
	v_mfma_f32_16x16x32_bf16 v[104:107], v[136:139], v[200:203], 0
	v_mfma_f32_16x16x32_bf16 v[92:95], v[128:131], v[208:211], 0
	v_mfma_f32_16x16x32_bf16 v[88:91], v[136:139], v[208:211], 0
	v_mfma_f32_16x16x32_bf16 v[76:79], v[128:131], v[216:219], 0
	v_mfma_f32_16x16x32_bf16 v[72:75], v[136:139], v[216:219], 0
	v_mfma_f32_16x16x32_bf16 v[124:127], v[132:135], v[196:199], v[124:127]
	v_mfma_f32_16x16x32_bf16 v[120:123], v[140:143], v[196:199], v[120:123]
	v_mfma_f32_16x16x32_bf16 v[108:111], v[132:135], v[204:207], v[108:111]
	v_mfma_f32_16x16x32_bf16 v[104:107], v[140:143], v[204:207], v[104:107]
	v_mfma_f32_16x16x32_bf16 v[92:95], v[132:135], v[212:215], v[92:95]
	v_mfma_f32_16x16x32_bf16 v[88:91], v[140:143], v[212:215], v[88:91]
	v_mfma_f32_16x16x32_bf16 v[76:79], v[132:135], v[220:223], v[76:79]
	v_mfma_f32_16x16x32_bf16 v[72:75], v[140:143], v[220:223], v[72:75]
	s_setprio 0
	s_setprio 1
	v_mfma_f32_16x16x32_bf16 v[116:119], v[162:165], v[192:195], 0
	v_mfma_f32_16x16x32_bf16 v[112:115], v[170:173], v[192:195], 0
	v_mfma_f32_16x16x32_bf16 v[100:103], v[162:165], v[200:203], 0
	v_mfma_f32_16x16x32_bf16 v[96:99], v[170:173], v[200:203], 0
	v_mfma_f32_16x16x32_bf16 v[84:87], v[162:165], v[208:211], 0
	v_mfma_f32_16x16x32_bf16 v[80:83], v[170:173], v[208:211], 0
	v_mfma_f32_16x16x32_bf16 v[68:71], v[162:165], v[216:219], 0
	v_mfma_f32_16x16x32_bf16 v[64:67], v[170:173], v[216:219], 0
	v_mfma_f32_16x16x32_bf16 v[116:119], v[166:169], v[196:199], v[116:119]
	v_mfma_f32_16x16x32_bf16 v[112:115], v[188:191], v[196:199], v[112:115]
	v_mfma_f32_16x16x32_bf16 v[100:103], v[166:169], v[204:207], v[100:103]
	v_mfma_f32_16x16x32_bf16 v[96:99], v[188:191], v[204:207], v[96:99]
	v_mfma_f32_16x16x32_bf16 v[84:87], v[166:169], v[212:215], v[84:87]
	v_mfma_f32_16x16x32_bf16 v[80:83], v[188:191], v[212:215], v[80:83]
	v_mfma_f32_16x16x32_bf16 v[68:71], v[166:169], v[220:223], v[68:71]
	v_mfma_f32_16x16x32_bf16 v[64:67], v[188:191], v[220:223], v[64:67]
	s_setprio 0
	s_barrier
	s_add_i32 s60, s48, s33
	v_lshl_add_u64 v[224:225], s[34:35], 0, v[146:147]
	s_mov_b32 m0, s60
	ds_read_b128 v[192:195], v183 offset:16384
	ds_read_b128 v[196:199], v183 offset:17408
	ds_read_b128 v[200:203], v183 offset:18432
	ds_read_b128 v[204:207], v183 offset:19456
	ds_read_b128 v[208:211], v183 offset:20480
	ds_read_b128 v[212:215], v183 offset:21504
	ds_read_b128 v[216:219], v183 offset:22528
	ds_read_b128 v[220:223], v183 offset:23552
	global_load_lds_dwordx4 v[224:225], off
	s_add_i32 m0, s60, 0x2000
	s_add_u32 s60, s34, 0x40000
	v_lshl_add_u64 v[226:227], s[34:35], 0, v[150:151]
	s_addc_u32 s61, s35, 0
	s_add_i32 s62, s49, s33
	global_load_lds_dwordx4 v[226:227], off
	v_lshl_add_u64 v[228:229], s[60:61], 0, v[146:147]
	s_mov_b32 m0, s62
	v_lshl_add_u64 v[230:231], s[36:37], 0, v[148:149]
	global_load_lds_dwordx4 v[228:229], off
	v_lshl_add_u64 v[228:229], s[60:61], 0, v[150:151]
	s_add_i32 m0, s62, 0x2000
	s_nop 0
	global_load_lds_dwordx4 v[228:229], off
	v_lshl_add_u64 v[228:229], s[36:37], 0, v[144:145]
	s_mov_b32 m0, s38
	s_nop 0
	global_load_lds_dwordx4 v[228:229], off
	s_mov_b32 m0, s39
	s_nop 0
	global_load_lds_dwordx4 v[230:231], off
	s_waitcnt vmcnt(8)
	s_waitcnt lgkmcnt(0)
	s_barrier
; #define PG8_STAGE(bufoff, gbase, voff) do { _Pragma("unroll") for (int _i = 0; _i < 2; ++_i) \
;         __builtin_amdgcn_global_load_lds((const unsigned*)((const char*)(gbase) + (voff)[_i]), (PG8_LAS unsigned*)(lds + (bufoff) + ldsw + _i * 8192), 16, 0, 0); } while (0)
; #define PG8_LDA(dst, b, h) do { _Pragma("unroll") for (int m = 0; m < 4; ++m) _Pragma("unroll") for (int k = 0; k < 2; ++k) dst[m][k] = *(const PG8_LAS bf16x8*)(lds + PG8_SA(b, h) + aoff + m * 2048 + k * 1024); } while (0)
; #define PG8_LDB(dst, b, h) do { _Pragma("unroll") for (int n = 0; n < 2; ++n) _Pragma("unroll") for (int k = 0; k < 2; ++k) dst[n][k] = *(const PG8_LAS bf16x8*)(lds + PG8_SB(b, h) + boff + n * 2048 + k * 1024); } while (0)
; #define PG8_MMA(ai, bj, At, Bt) do { __builtin_amdgcn_s_setprio(1); _Pragma("unroll") for (int m = 0; m < 4; ++m) _Pragma("unroll") for (int n = 0; n < 2; ++n) _Pragma("unroll") for (int k = 0; k < 2; ++k) \
;         acc[ai][bj][m][n] = __builtin_amdgcn_mfma_f32_16x16x32_bf16(Bt[n][k], At[m][k], acc[ai][bj][m][n], 0, 0, 0); __builtin_amdgcn_s_setprio(0); } while (0)
; #define PG8_WAIT_V(n) asm volatile("s_waitcnt vmcnt(" #n ")" ::: "memory")
; template <class Epi, class Sched, bool ALIGN_EPI = false, bool SP2 = false>
; __device__ __forceinline__ void gemm_phase(PG8_LAS unsigned char* lds, const Gemm g, const Sched& S, const Epi& E) {
;     ...
;             PG8_LDB(B0, 0, 0); PG8_LDB(B1, 0, 1); PG8_SCHED; PG8_LDA(At, 0, 0); PG8_STAGE(PG8_SA(1, 1), a1 + hstep, voffA);
;             PG8_WAIT_V(8); PG8_WAIT_L(0); PG8_BAR; PG8_MMA(0, 0, At, B0); PG8_MMA(0, 1, At, B1); PG8_BAR; PG8_SCHED;
;             PG8_LDA(At, 0, 1); PG8_STAGE(PG8_SB(0, 0), b2, voffB); PG8_STAGE(PG8_SB(0, 1), b2 + hstep, voffB); PG8_STAGE(PG8_SA(0, 0), a2, voffA);
;             PG8_WAIT_V(8); PG8_WAIT_L(0); PG8_BAR; PG8_MMA(1, 0, At, B0); PG8_MMA(1, 1, At, B1); PG8_BAR; PG8_SCHED;
;             PG8_LDB(B0, 1, 0); PG8_LDB(B1, 1, 1); PG8_SCHED; PG8_LDA(At, 1, 0); PG8_STAGE(PG8_SA(0, 1), a2 + hstep, voffA);
;             PG8_WAIT_V(8); PG8_WAIT_L(0); PG8_BAR; PG8_MMA(0, 0, At, B0); PG8_MMA(0, 1, At, B1); PG8_BAR; PG8_SCHED;
;             PG8_LDA(At, 1, 1); PG8_STAGE(PG8_SB(1, 0), b3, voffB); PG8_STAGE(PG8_SB(1, 1), b3 + hstep, voffB); PG8_STAGE(PG8_SA(1, 0), a3, voffA);
;             PG8_WAIT_V(8); PG8_WAIT_L(0); PG8_BAR; PG8_MMA(1, 0, At, B0); PG8_MMA(1, 1, At, B1); PG8_BAR; PG8_SCHED;
	s_setprio 1
	s_waitcnt lgkmcnt(0)
	v_mfma_f32_16x16x32_bf16 v[60:63], v[128:131], v[192:195], 0
	v_mfma_f32_16x16x32_bf16 v[56:59], v[136:139], v[192:195], 0
	v_mfma_f32_16x16x32_bf16 v[44:47], v[128:131], v[200:203], 0
	v_mfma_f32_16x16x32_bf16 v[40:43], v[136:139], v[200:203], 0
	v_mfma_f32_16x16x32_bf16 v[28:31], v[128:131], v[208:211], 0
	v_mfma_f32_16x16x32_bf16 v[24:27], v[136:139], v[208:211], 0
	v_mfma_f32_16x16x32_bf16 v[12:15], v[128:131], v[216:219], 0
	v_mfma_f32_16x16x32_bf16 v[8:11], v[136:139], v[216:219], 0
	v_mfma_f32_16x16x32_bf16 v[60:63], v[132:135], v[196:199], v[60:63]
	v_mfma_f32_16x16x32_bf16 v[56:59], v[140:143], v[196:199], v[56:59]
	v_mfma_f32_16x16x32_bf16 v[44:47], v[132:135], v[204:207], v[44:47]
	v_mfma_f32_16x16x32_bf16 v[40:43], v[140:143], v[204:207], v[40:43]
	v_mfma_f32_16x16x32_bf16 v[28:31], v[132:135], v[212:215], v[28:31]
	v_mfma_f32_16x16x32_bf16 v[24:27], v[140:143], v[212:215], v[24:27]
	v_mfma_f32_16x16x32_bf16 v[12:15], v[132:135], v[220:223], v[12:15]
	v_mfma_f32_16x16x32_bf16 v[8:11], v[140:143], v[220:223], v[8:11]
	s_setprio 0
	s_setprio 1
	v_mfma_f32_16x16x32_bf16 v[52:55], v[162:165], v[192:195], 0
	v_mfma_f32_16x16x32_bf16 v[48:51], v[170:173], v[192:195], 0
	v_mfma_f32_16x16x32_bf16 v[36:39], v[162:165], v[200:203], 0
	v_mfma_f32_16x16x32_bf16 v[32:35], v[170:173], v[200:203], 0
	v_mfma_f32_16x16x32_bf16 v[20:23], v[162:165], v[208:211], 0
	v_mfma_f32_16x16x32_bf16 v[16:19], v[170:173], v[208:211], 0
	v_mfma_f32_16x16x32_bf16 v[4:7], v[162:165], v[216:219], 0
	v_mfma_f32_16x16x32_bf16 v[0:3], v[170:173], v[216:219], 0
	v_mfma_f32_16x16x32_bf16 v[52:55], v[166:169], v[196:199], v[52:55]
	v_mfma_f32_16x16x32_bf16 v[48:51], v[188:191], v[196:199], v[48:51]
	v_mfma_f32_16x16x32_bf16 v[36:39], v[166:169], v[204:207], v[36:39]
	v_mfma_f32_16x16x32_bf16 v[32:35], v[188:191], v[204:207], v[32:35]
	v_mfma_f32_16x16x32_bf16 v[20:23], v[166:169], v[212:215], v[20:23]
	v_mfma_f32_16x16x32_bf16 v[16:19], v[188:191], v[212:215], v[16:19]
	v_mfma_f32_16x16x32_bf16 v[4:7], v[166:169], v[220:223], v[4:7]
	v_mfma_f32_16x16x32_bf16 v[0:3], v[188:191], v[220:223], v[0:3]
	s_setprio 0
	s_barrier
	s_add_i32 s60, 0, 0x18000
	s_add_i32 s61, 0, 0x1c000
	v_add_u32_e32 v140, s60, v175
	v_add_u32_e32 v187, s61, v175
	ds_read_b128 v[128:131], v140
	ds_read_b128 v[132:135], v140 offset:1024
	ds_read_b128 v[136:139], v140 offset:2048
	ds_read_b128 v[140:143], v140 offset:3072
	ds_read_b128 v[162:165], v187
	ds_read_b128 v[166:169], v187 offset:1024
	ds_read_b128 v[170:173], v187 offset:2048
	ds_read_b128 v[188:191], v187 offset:3072
	s_add_u32 s36, s36, 0x40000
	s_addc_u32 s37, s37, 0
	s_mov_b32 m0, s40
	v_lshl_add_u64 v[232:233], s[36:37], 0, v[144:145]
	ds_read_b128 v[192:195], v183 offset:32768
	ds_read_b128 v[196:199], v183 offset:33792
	ds_read_b128 v[200:203], v183 offset:34816
	ds_read_b128 v[204:207], v183 offset:35840
	ds_read_b128 v[208:211], v183 offset:36864
	ds_read_b128 v[212:215], v183 offset:37888
	ds_read_b128 v[216:219], v183 offset:38912
	ds_read_b128 v[220:223], v183 offset:39936
	global_load_lds_dwordx4 v[232:233], off
	v_lshl_add_u64 v[232:233], s[36:37], 0, v[148:149]
	s_mov_b32 m0, s41
	s_nop 0
	global_load_lds_dwordx4 v[232:233], off
	s_waitcnt vmcnt(8)
	s_waitcnt lgkmcnt(0)
	s_barrier
	s_setprio 1
	s_waitcnt lgkmcnt(0)
	v_mfma_f32_16x16x32_bf16 v[124:127], v[128:131], v[192:195], v[124:127]
	v_mfma_f32_16x16x32_bf16 v[120:123], v[136:139], v[192:195], v[120:123]
	v_mfma_f32_16x16x32_bf16 v[108:111], v[128:131], v[200:203], v[108:111]
	v_mfma_f32_16x16x32_bf16 v[104:107], v[136:139], v[200:203], v[104:107]
	v_mfma_f32_16x16x32_bf16 v[92:95], v[128:131], v[208:211], v[92:95]
	v_mfma_f32_16x16x32_bf16 v[88:91], v[136:139], v[208:211], v[88:91]
	v_mfma_f32_16x16x32_bf16 v[76:79], v[128:131], v[216:219], v[76:79]
	v_mfma_f32_16x16x32_bf16 v[72:75], v[136:139], v[216:219], v[72:75]
	v_mfma_f32_16x16x32_bf16 v[124:127], v[132:135], v[196:199], v[124:127]
	v_mfma_f32_16x16x32_bf16 v[120:123], v[140:143], v[196:199], v[120:123]
	v_mfma_f32_16x16x32_bf16 v[108:111], v[132:135], v[204:207], v[108:111]
	v_mfma_f32_16x16x32_bf16 v[104:107], v[140:143], v[204:207], v[104:107]
	v_mfma_f32_16x16x32_bf16 v[92:95], v[132:135], v[212:215], v[92:95]
	v_mfma_f32_16x16x32_bf16 v[88:91], v[140:143], v[212:215], v[88:91]
	v_mfma_f32_16x16x32_bf16 v[76:79], v[132:135], v[220:223], v[76:79]
	v_mfma_f32_16x16x32_bf16 v[72:75], v[140:143], v[220:223], v[72:75]
	s_setprio 0
	s_setprio 1
	v_mfma_f32_16x16x32_bf16 v[116:119], v[162:165], v[192:195], v[116:119]
	v_mfma_f32_16x16x32_bf16 v[112:115], v[170:173], v[192:195], v[112:115]
	v_mfma_f32_16x16x32_bf16 v[100:103], v[162:165], v[200:203], v[100:103]
	v_mfma_f32_16x16x32_bf16 v[96:99], v[170:173], v[200:203], v[96:99]
	v_mfma_f32_16x16x32_bf16 v[84:87], v[162:165], v[208:211], v[84:87]
	v_mfma_f32_16x16x32_bf16 v[80:83], v[170:173], v[208:211], v[80:83]
	v_mfma_f32_16x16x32_bf16 v[68:71], v[162:165], v[216:219], v[68:71]
	v_mfma_f32_16x16x32_bf16 v[64:67], v[170:173], v[216:219], v[64:67]
	v_mfma_f32_16x16x32_bf16 v[116:119], v[166:169], v[196:199], v[116:119]
	v_mfma_f32_16x16x32_bf16 v[112:115], v[188:191], v[196:199], v[112:115]
	v_mfma_f32_16x16x32_bf16 v[100:103], v[166:169], v[204:207], v[100:103]
	v_mfma_f32_16x16x32_bf16 v[96:99], v[188:191], v[204:207], v[96:99]
	v_mfma_f32_16x16x32_bf16 v[84:87], v[166:169], v[212:215], v[84:87]
	v_mfma_f32_16x16x32_bf16 v[80:83], v[188:191], v[212:215], v[80:83]
	v_mfma_f32_16x16x32_bf16 v[68:71], v[166:169], v[220:223], v[68:71]
	v_mfma_f32_16x16x32_bf16 v[64:67], v[188:191], v[220:223], v[64:67]
	s_setprio 0
	s_barrier
; #define PG8_STAGE(bufoff, gbase, voff) do { _Pragma("unroll") for (int _i = 0; _i < 2; ++_i) \
;         __builtin_amdgcn_global_load_lds((const unsigned*)((const char*)(gbase) + (voff)[_i]), (PG8_LAS unsigned*)(lds + (bufoff) + ldsw + _i * 8192), 16, 0, 0); } while (0)
; #define PG8_LDA(dst, b, h) do { _Pragma("unroll") for (int m = 0; m < 4; ++m) _Pragma("unroll") for (int k = 0; k < 2; ++k) dst[m][k] = *(const PG8_LAS bf16x8*)(lds + PG8_SA(b, h) + aoff + m * 2048 + k * 1024); } while (0)
; #define PG8_LDB(dst, b, h) do { _Pragma("unroll") for (int n = 0; n < 2; ++n) _Pragma("unroll") for (int k = 0; k < 2; ++k) dst[n][k] = *(const PG8_LAS bf16x8*)(lds + PG8_SB(b, h) + boff + n * 2048 + k * 1024); } while (0)
; template <class Epi, class Sched, bool ALIGN_EPI = false, bool SP2 = false>
; __device__ __forceinline__ void gemm_phase(PG8_LAS unsigned char* lds, const Gemm g, const Sched& S, const Epi& E) {
;     ...
;         for (int t = 0; t < nt; t += 2) {
;             const bool last = (t == nt - 2);
;             const char* a1 = cA + (size_t)(t + 1) * kstep;
;             const char* a2 = last ? nA : cA + (size_t)(t + 2) * kstep; const char* b2 = last ? nB : cB + (size_t)(t + 2) * kstep;
;             const char* a3 = a2 + kstep; const char* b3 = b2 + kstep;
;             if (last && has_next) S.a_ready(nxt);
;             if constexpr (SP2) {
;             PG8_LDB(B0, 0, 0); PG8_LDB(B1, 0, 1); PG8_SCHED; PG8_LDA(At, 0, 0); PG8_STAGE(PG8_SA(1, 1), a1 + hstep, voffA);
;             PG8_WAIT_V(8); PG8_WAIT_L(0); PG8_BAR; PG8_MMA(0, 0, At, B0); PG8_MMA(0, 1, At, B1); PG8_BAR; PG8_SCHED;
;             PG8_LDA(At, 0, 1); PG8_STAGE(PG8_SB(0, 0), b2, voffB); PG8_STAGE(PG8_SB(0, 1), b2 + hstep, voffB); PG8_STAGE(PG8_SA(0, 0), a2, voffA);
;             PG8_WAIT_V(8); PG8_WAIT_L(0); PG8_BAR; PG8_MMA(1, 0, At, B0); PG8_MMA(1, 1, At, B1); PG8_BAR; PG8_SCHED;
;             PG8_LDB(B0, 1, 0); PG8_LDB(B1, 1, 1); PG8_SCHED; PG8_LDA(At, 1, 0); PG8_STAGE(PG8_SA(0, 1), a2 + hstep, voffA);
;             PG8_WAIT_V(8); PG8_WAIT_L(0); PG8_BAR; PG8_MMA(0, 0, At, B0); PG8_MMA(0, 1, At, B1); PG8_BAR; PG8_SCHED;
;             PG8_LDA(At, 1, 1); PG8_STAGE(PG8_SB(1, 0), b3, voffB); PG8_STAGE(PG8_SB(1, 1), b3 + hstep, voffB); PG8_STAGE(PG8_SA(1, 0), a3, voffA);
;             PG8_WAIT_V(8); PG8_WAIT_L(0); PG8_BAR; PG8_MMA(1, 0, At, B0); PG8_MMA(1, 1, At, B1); PG8_BAR; PG8_SCHED;
	s_add_i32 s36, s60, s33
	v_lshl_add_u64 v[224:225], v[224:225], 0, s[16:17]
	s_mov_b32 m0, s36
	ds_read_b128 v[192:195], v183 offset:49152
	ds_read_b128 v[196:199], v183 offset:50176
	ds_read_b128 v[200:203], v183 offset:51200
	ds_read_b128 v[204:207], v183 offset:52224
	ds_read_b128 v[208:211], v183 offset:53248
	ds_read_b128 v[212:215], v183 offset:54272
	ds_read_b128 v[216:219], v183 offset:55296
	ds_read_b128 v[220:223], v183 offset:56320
	global_load_lds_dwordx4 v[224:225], off
	s_add_i32 m0, s36, 0x2000
	s_add_u32 s34, s34, 0x40080
	v_lshl_add_u64 v[224:225], v[226:227], 0, s[16:17]
	s_addc_u32 s35, s35, 0
	s_add_i32 s36, s61, s33
	global_load_lds_dwordx4 v[224:225], off
	v_lshl_add_u64 v[224:225], s[34:35], 0, v[146:147]
	s_mov_b32 m0, s36
	s_nop 0
	global_load_lds_dwordx4 v[224:225], off
	v_lshl_add_u64 v[224:225], s[34:35], 0, v[150:151]
	s_add_i32 m0, s36, 0x2000
	s_nop 0
	global_load_lds_dwordx4 v[224:225], off
	v_lshl_add_u64 v[224:225], v[228:229], 0, s[16:17]
	s_mov_b32 m0, s46
	s_nop 0
	global_load_lds_dwordx4 v[224:225], off
	v_lshl_add_u64 v[224:225], v[230:231], 0, s[16:17]
	s_mov_b32 m0, s47
	s_nop 0
	global_load_lds_dwordx4 v[224:225], off
	s_waitcnt vmcnt(8)
	s_waitcnt lgkmcnt(0)
	s_barrier
	s_setprio 1
	s_waitcnt lgkmcnt(0)
	v_mfma_f32_16x16x32_bf16 v[60:63], v[128:131], v[192:195], v[60:63]
	v_mfma_f32_16x16x32_bf16 v[56:59], v[136:139], v[192:195], v[56:59]
	v_mfma_f32_16x16x32_bf16 v[44:47], v[128:131], v[200:203], v[44:47]
	v_mfma_f32_16x16x32_bf16 v[40:43], v[136:139], v[200:203], v[40:43]
	v_mfma_f32_16x16x32_bf16 v[28:31], v[128:131], v[208:211], v[28:31]
	v_mfma_f32_16x16x32_bf16 v[24:27], v[136:139], v[208:211], v[24:27]
	v_mfma_f32_16x16x32_bf16 v[12:15], v[128:131], v[216:219], v[12:15]
	v_mfma_f32_16x16x32_bf16 v[8:11], v[136:139], v[216:219], v[8:11]
	v_mfma_f32_16x16x32_bf16 v[60:63], v[132:135], v[196:199], v[60:63]
	v_mfma_f32_16x16x32_bf16 v[56:59], v[140:143], v[196:199], v[56:59]
	v_mfma_f32_16x16x32_bf16 v[44:47], v[132:135], v[204:207], v[44:47]
	v_mfma_f32_16x16x32_bf16 v[40:43], v[140:143], v[204:207], v[40:43]
	v_mfma_f32_16x16x32_bf16 v[28:31], v[132:135], v[212:215], v[28:31]
	v_mfma_f32_16x16x32_bf16 v[24:27], v[140:143], v[212:215], v[24:27]
	v_mfma_f32_16x16x32_bf16 v[12:15], v[132:135], v[220:223], v[12:15]
	v_mfma_f32_16x16x32_bf16 v[8:11], v[140:143], v[220:223], v[8:11]
	s_setprio 0
	s_setprio 1
	v_mfma_f32_16x16x32_bf16 v[52:55], v[162:165], v[192:195], v[52:55]
	v_mfma_f32_16x16x32_bf16 v[48:51], v[170:173], v[192:195], v[48:51]
	v_mfma_f32_16x16x32_bf16 v[36:39], v[162:165], v[200:203], v[36:39]
	v_mfma_f32_16x16x32_bf16 v[32:35], v[170:173], v[200:203], v[32:35]
	v_mfma_f32_16x16x32_bf16 v[20:23], v[162:165], v[208:211], v[20:23]
	v_mfma_f32_16x16x32_bf16 v[16:19], v[170:173], v[208:211], v[16:19]
	v_mfma_f32_16x16x32_bf16 v[4:7], v[162:165], v[216:219], v[4:7]
	v_mfma_f32_16x16x32_bf16 v[0:3], v[170:173], v[216:219], v[0:3]
	v_mfma_f32_16x16x32_bf16 v[52:55], v[166:169], v[196:199], v[52:55]
	v_mfma_f32_16x16x32_bf16 v[48:51], v[188:191], v[196:199], v[48:51]
	v_mfma_f32_16x16x32_bf16 v[36:39], v[166:169], v[204:207], v[36:39]
	v_mfma_f32_16x16x32_bf16 v[32:35], v[188:191], v[204:207], v[32:35]
	v_mfma_f32_16x16x32_bf16 v[20:23], v[166:169], v[212:215], v[20:23]
	v_mfma_f32_16x16x32_bf16 v[16:19], v[188:191], v[212:215], v[16:19]
	v_mfma_f32_16x16x32_bf16 v[4:7], v[166:169], v[220:223], v[4:7]
	v_mfma_f32_16x16x32_bf16 v[0:3], v[188:191], v[220:223], v[0:3]
	s_setprio 0
	s_barrier
	s_add_i32 s59, s59, 2
	s_add_u32 s4, s4, 0x100
	s_addc_u32 s5, s5, 0
	s_add_u32 s57, s57, 0x100
	s_addc_u32 s58, s58, 0
	s_cmp_gt_u32 s59, 13
	s_cbranch_scc0 .LBB0_506

; #define PG8_STAGE(bufoff, gbase, voff) do { _Pragma("unroll") for (int _i = 0; _i < 2; ++_i) \
;         __builtin_amdgcn_global_load_lds((const unsigned*)((const char*)(gbase) + (voff)[_i]), (PG8_LAS unsigned*)(lds + (bufoff) + ldsw + _i * 8192), 16, 0, 0); } while (0)
; #define PG8_LDA(dst, b, h) do { _Pragma("unroll") for (int m = 0; m < 4; ++m) _Pragma("unroll") for (int k = 0; k < 2; ++k) dst[m][k] = *(const PG8_LAS bf16x8*)(lds + PG8_SA(b, h) + aoff + m * 2048 + k * 1024); } while (0)
; #define PG8_LDB(dst, b, h) do { _Pragma("unroll") for (int n = 0; n < 2; ++n) _Pragma("unroll") for (int k = 0; k < 2; ++k) dst[n][k] = *(const PG8_LAS bf16x8*)(lds + PG8_SB(b, h) + boff + n * 2048 + k * 1024); } while (0)
; #define PG8_WAIT_V(n) asm volatile("s_waitcnt vmcnt(" #n ")" ::: "memory")
; template <class Epi, class Sched, bool ALIGN_EPI = false, bool SP2 = false>
; __device__ __forceinline__ void gemm_phase(PG8_LAS unsigned char* lds, const Gemm g, const Sched& S, const Epi& E) {
;     ...
; #pragma unroll
;     for (int a = 0; a < 2; ++a)
; #pragma unroll
;         for (int b = 0; b < 2; ++b)
; #pragma unroll
;             for (int m = 0; m < 4; ++m)
; #pragma unroll
;                 for (int n = 0; n < 2; ++n) acc[a][b][m][n] = (f32x4){0.f, 0.f, 0.f, 0.f};
;     ...
;         const char* nA = has_next ? (const char*)g.A + (size_t)nxt.pm * tstep : cA; const char* nB = has_next ? (const char*)g.Bt + (size_t)nxt.pn * tstep : cB;
;         for (int t = 0; t < nt; t += 2) {
;             const bool last = (t == nt - 2);
;             const char* a1 = cA + (size_t)(t + 1) * kstep;
;             const char* a2 = last ? nA : cA + (size_t)(t + 2) * kstep; const char* b2 = last ? nB : cB + (size_t)(t + 2) * kstep;
;             const char* a3 = a2 + kstep; const char* b3 = b2 + kstep;
;             if (last && has_next) S.a_ready(nxt);
;             if constexpr (SP2) {
;             PG8_LDB(B0, 0, 0); PG8_LDB(B1, 0, 1); PG8_SCHED; PG8_LDA(At, 0, 0); PG8_STAGE(PG8_SA(1, 1), a1 + hstep, voffA);
;             PG8_WAIT_V(8); PG8_WAIT_L(0); PG8_BAR; PG8_MMA(0, 0, At, B0); PG8_MMA(0, 1, At, B1); PG8_BAR; PG8_SCHED;
;             PG8_LDA(At, 0, 1); PG8_STAGE(PG8_SB(0, 0), b2, voffB); PG8_STAGE(PG8_SB(0, 1), b2 + hstep, voffB); PG8_STAGE(PG8_SA(0, 0), a2, voffA);
;             PG8_WAIT_V(8); PG8_WAIT_L(0); PG8_BAR; PG8_MMA(1, 0, At, B0); PG8_MMA(1, 1, At, B1); PG8_BAR; PG8_SCHED;
.LBB0_764:
	s_ashr_i32 s23, s22, 31
	s_lshl_b64 s[0:1], s[22:23], 19
	s_add_u32 s24, s58, s0
	s_addc_u32 s25, s59, s1
	s_and_b64 s[0:1], s[6:7], exec
	s_cselect_b32 s0, s25, s35
	s_cselect_b32 s1, s24, s34
	s_ashr_i32 s21, s20, 31
	s_lshl_b64 s[4:5], s[20:21], 19
	s_add_u32 s26, s36, s4
	s_addc_u32 s27, s37, s5
	s_and_b64 s[4:5], s[6:7], exec
	s_cselect_b32 s21, s27, s31
	s_cselect_b32 s23, s26, s30
	s_add_u32 s4, s34, 0x40080
	s_addc_u32 s5, s35, 0
	s_add_u32 s34, s30, 0x100
	s_addc_u32 s35, s31, 0
	s_mov_b32 s53, -2
	ds_read_b128 v[128:131], v183
	ds_read_b128 v[132:135], v183 offset:1024
	ds_read_b128 v[136:139], v183 offset:2048
	ds_read_b128 v[140:143], v183 offset:3072
	s_waitcnt lgkmcnt(0)
	ds_read_b128 v[162:165], v184
	ds_read_b128 v[166:169], v184 offset:1024
	ds_read_b128 v[170:173], v184 offset:2048
	ds_read_b128 v[190:193], v184 offset:3072
	s_add_u32 s10, s4, 0xfffc0080
	s_addc_u32 s11, s5, -1
	s_cmp_eq_u32 s53, 12
	s_cselect_b32 s31, s0, s11
	s_cselect_b32 s30, s1, s10
	s_cselect_b32 s11, s21, s35
	s_cselect_b32 s10, s23, s34
	v_lshl_add_u64 v[226:227], s[4:5], 0, v[154:155]
	s_add_i32 m0, s29, 0xc000
	ds_read_b128 v[194:197], v185
	ds_read_b128 v[198:201], v185 offset:1024
	ds_read_b128 v[202:205], v185 offset:2048
	ds_read_b128 v[206:209], v185 offset:3072
	ds_read_b128 v[210:213], v185 offset:4096
	ds_read_b128 v[214:217], v185 offset:5120
	ds_read_b128 v[218:221], v185 offset:6144
	ds_read_b128 v[222:225], v185 offset:7168
	global_load_lds_dwordx4 v[226:227], off
	v_lshl_add_u64 v[226:227], s[4:5], 0, v[156:157]
	s_add_i32 m0, s29, 0xe000
	s_nop 0
	global_load_lds_dwordx4 v[226:227], off
	s_waitcnt vmcnt(8)
	s_waitcnt lgkmcnt(0)
	s_barrier
	s_setprio 1
	s_waitcnt lgkmcnt(0)
	v_mfma_f32_16x16x32_bf16 v[124:127], v[128:131], v[194:197], 0
	v_mfma_f32_16x16x32_bf16 v[120:123], v[136:139], v[194:197], 0
	v_mfma_f32_16x16x32_bf16 v[108:111], v[128:131], v[202:205], 0
	v_mfma_f32_16x16x32_bf16 v[104:107], v[136:139], v[202:205], 0
	v_mfma_f32_16x16x32_bf16 v[92:95], v[128:131], v[210:213], 0
	v_mfma_f32_16x16x32_bf16 v[88:91], v[136:139], v[210:213], 0
	v_mfma_f32_16x16x32_bf16 v[76:79], v[128:131], v[218:221], 0
	v_mfma_f32_16x16x32_bf16 v[72:75], v[136:139], v[218:221], 0
	v_mfma_f32_16x16x32_bf16 v[124:127], v[132:135], v[198:201], v[124:127]
	v_mfma_f32_16x16x32_bf16 v[120:123], v[140:143], v[198:201], v[120:123]
	v_mfma_f32_16x16x32_bf16 v[108:111], v[132:135], v[206:209], v[108:111]
	v_mfma_f32_16x16x32_bf16 v[104:107], v[140:143], v[206:209], v[104:107]
	v_mfma_f32_16x16x32_bf16 v[92:95], v[132:135], v[214:217], v[92:95]
	v_mfma_f32_16x16x32_bf16 v[88:91], v[140:143], v[214:217], v[88:91]
	v_mfma_f32_16x16x32_bf16 v[76:79], v[132:135], v[222:225], v[76:79]
	v_mfma_f32_16x16x32_bf16 v[72:75], v[140:143], v[222:225], v[72:75]
	s_setprio 0
	s_setprio 1
	v_mfma_f32_16x16x32_bf16 v[116:119], v[162:165], v[194:197], 0
	v_mfma_f32_16x16x32_bf16 v[112:115], v[170:173], v[194:197], 0
	v_mfma_f32_16x16x32_bf16 v[100:103], v[162:165], v[202:205], 0
	v_mfma_f32_16x16x32_bf16 v[96:99], v[170:173], v[202:205], 0
	v_mfma_f32_16x16x32_bf16 v[84:87], v[162:165], v[210:213], 0
	v_mfma_f32_16x16x32_bf16 v[80:83], v[170:173], v[210:213], 0
	v_mfma_f32_16x16x32_bf16 v[68:71], v[162:165], v[218:221], 0
	v_mfma_f32_16x16x32_bf16 v[64:67], v[170:173], v[218:221], 0
	v_mfma_f32_16x16x32_bf16 v[116:119], v[166:169], v[198:201], v[116:119]
	v_mfma_f32_16x16x32_bf16 v[112:115], v[190:193], v[198:201], v[112:115]
	v_mfma_f32_16x16x32_bf16 v[100:103], v[166:169], v[206:209], v[100:103]
	v_mfma_f32_16x16x32_bf16 v[96:99], v[190:193], v[206:209], v[96:99]
	v_mfma_f32_16x16x32_bf16 v[84:87], v[166:169], v[214:217], v[84:87]
	v_mfma_f32_16x16x32_bf16 v[80:83], v[190:193], v[214:217], v[80:83]
	v_mfma_f32_16x16x32_bf16 v[68:71], v[166:169], v[222:225], v[68:71]
	v_mfma_f32_16x16x32_bf16 v[64:67], v[190:193], v[222:225], v[64:67]
	s_setprio 0
	s_barrier
	s_add_i32 s54, s47, s33
	v_lshl_add_u64 v[226:227], s[10:11], 0, v[146:147]
	s_mov_b32 m0, s54
	ds_read_b128 v[194:197], v185 offset:16384
	ds_read_b128 v[198:201], v185 offset:17408
	ds_read_b128 v[202:205], v185 offset:18432
	ds_read_b128 v[206:209], v185 offset:19456
	ds_read_b128 v[210:213], v185 offset:20480
	ds_read_b128 v[214:217], v185 offset:21504
	ds_read_b128 v[218:221], v185 offset:22528
	ds_read_b128 v[222:225], v185 offset:23552
	global_load_lds_dwordx4 v[226:227], off
	s_add_i32 m0, s54, 0x2000
	s_add_u32 s54, s10, 0x40000
	v_lshl_add_u64 v[228:229], s[10:11], 0, v[150:151]
	s_addc_u32 s55, s11, 0
	s_add_i32 s56, s48, s33
	global_load_lds_dwordx4 v[228:229], off
	v_lshl_add_u64 v[230:231], s[54:55], 0, v[146:147]
	s_mov_b32 m0, s56
	v_lshl_add_u64 v[232:233], s[30:31], 0, v[148:149]
	global_load_lds_dwordx4 v[230:231], off
	v_lshl_add_u64 v[230:231], s[54:55], 0, v[150:151]
	s_add_i32 m0, s56, 0x2000
	s_nop 0
	global_load_lds_dwordx4 v[230:231], off
	v_lshl_add_u64 v[230:231], s[30:31], 0, v[144:145]
	s_mov_b32 m0, s29
	s_nop 0
	global_load_lds_dwordx4 v[230:231], off
	s_mov_b32 m0, s38
	s_nop 0
	global_load_lds_dwordx4 v[232:233], off
	s_waitcnt vmcnt(8)
	s_waitcnt lgkmcnt(0)
	s_barrier
; #define PG8_STAGE(bufoff, gbase, voff) do { _Pragma("unroll") for (int _i = 0; _i < 2; ++_i) \
;         __builtin_amdgcn_global_load_lds((const unsigned*)((const char*)(gbase) + (voff)[_i]), (PG8_LAS unsigned*)(lds + (bufoff) + ldsw + _i * 8192), 16, 0, 0); } while (0)
; #define PG8_LDA(dst, b, h) do { _Pragma("unroll") for (int m = 0; m < 4; ++m) _Pragma("unroll") for (int k = 0; k < 2; ++k) dst[m][k] = *(const PG8_LAS bf16x8*)(lds + PG8_SA(b, h) + aoff + m * 2048 + k * 1024); } while (0)
; #define PG8_LDB(dst, b, h) do { _Pragma("unroll") for (int n = 0; n < 2; ++n) _Pragma("unroll") for (int k = 0; k < 2; ++k) dst[n][k] = *(const PG8_LAS bf16x8*)(lds + PG8_SB(b, h) + boff + n * 2048 + k * 1024); } while (0)
; #define PG8_WAIT_V(n) asm volatile("s_waitcnt vmcnt(" #n ")" ::: "memory")
; #define PG8_WAIT_L(n) asm volatile("s_waitcnt lgkmcnt(" #n ")" ::: "memory")
; template <class Epi, class Sched, bool ALIGN_EPI = false, bool SP2 = false>
; __device__ __forceinline__ void gemm_phase(PG8_LAS unsigned char* lds, const Gemm g, const Sched& S, const Epi& E) {
;     ...
;             PG8_LDB(B0, 0, 0); PG8_LDB(B1, 0, 1); PG8_SCHED; PG8_LDA(At, 0, 0); PG8_STAGE(PG8_SA(1, 1), a1 + hstep, voffA);
;             PG8_WAIT_V(8); PG8_WAIT_L(0); PG8_BAR; PG8_MMA(0, 0, At, B0); PG8_MMA(0, 1, At, B1); PG8_BAR; PG8_SCHED;
;             PG8_LDA(At, 0, 1); PG8_STAGE(PG8_SB(0, 0), b2, voffB); PG8_STAGE(PG8_SB(0, 1), b2 + hstep, voffB); PG8_STAGE(PG8_SA(0, 0), a2, voffA);
;             PG8_WAIT_V(8); PG8_WAIT_L(0); PG8_BAR; PG8_MMA(1, 0, At, B0); PG8_MMA(1, 1, At, B1); PG8_BAR; PG8_SCHED;
;             PG8_LDB(B0, 1, 0); PG8_LDB(B1, 1, 1); PG8_SCHED; PG8_LDA(At, 1, 0); PG8_STAGE(PG8_SA(0, 1), a2 + hstep, voffA);
;             PG8_WAIT_V(8); PG8_WAIT_L(0); PG8_BAR; PG8_MMA(0, 0, At, B0); PG8_MMA(0, 1, At, B1); PG8_BAR; PG8_SCHED;
;             PG8_LDA(At, 1, 1); PG8_STAGE(PG8_SB(1, 0), b3, voffB); PG8_STAGE(PG8_SB(1, 1), b3 + hstep, voffB); PG8_STAGE(PG8_SA(1, 0), a3, voffA);
;             PG8_WAIT_V(8); PG8_WAIT_L(0); PG8_BAR; PG8_MMA(1, 0, At, B0); PG8_MMA(1, 1, At, B1); PG8_BAR; PG8_SCHED;
;     ...
; #pragma unroll
;         for (int a = 0; a < 2; ++a)
; #pragma unroll
;             for (int b = 0; b < 2; ++b)
; #pragma unroll
;                 for (int m = 0; m < 4; ++m)
; #pragma unroll
;                     for (int n = 0; n < 2; ++n) acc[a][b][m][n] = (f32x4){0.f, 0.f, 0.f, 0.f};
	s_setprio 1
	s_waitcnt lgkmcnt(0)
	v_mfma_f32_16x16x32_bf16 v[60:63], v[128:131], v[194:197], 0
	v_mfma_f32_16x16x32_bf16 v[56:59], v[136:139], v[194:197], 0
	v_mfma_f32_16x16x32_bf16 v[44:47], v[128:131], v[202:205], 0
	v_mfma_f32_16x16x32_bf16 v[40:43], v[136:139], v[202:205], 0
	v_mfma_f32_16x16x32_bf16 v[28:31], v[128:131], v[210:213], 0
	v_mfma_f32_16x16x32_bf16 v[24:27], v[136:139], v[210:213], 0
	v_mfma_f32_16x16x32_bf16 v[12:15], v[128:131], v[218:221], 0
	v_mfma_f32_16x16x32_bf16 v[8:11], v[136:139], v[218:221], 0
	v_mfma_f32_16x16x32_bf16 v[60:63], v[132:135], v[198:201], v[60:63]
	v_mfma_f32_16x16x32_bf16 v[56:59], v[140:143], v[198:201], v[56:59]
	v_mfma_f32_16x16x32_bf16 v[44:47], v[132:135], v[206:209], v[44:47]
	v_mfma_f32_16x16x32_bf16 v[40:43], v[140:143], v[206:209], v[40:43]
	v_mfma_f32_16x16x32_bf16 v[28:31], v[132:135], v[214:217], v[28:31]
	v_mfma_f32_16x16x32_bf16 v[24:27], v[140:143], v[214:217], v[24:27]
	v_mfma_f32_16x16x32_bf16 v[12:15], v[132:135], v[222:225], v[12:15]
	v_mfma_f32_16x16x32_bf16 v[8:11], v[140:143], v[222:225], v[8:11]
	s_setprio 0
	s_setprio 1
	v_mfma_f32_16x16x32_bf16 v[52:55], v[162:165], v[194:197], 0
	v_mfma_f32_16x16x32_bf16 v[48:51], v[170:173], v[194:197], 0
	v_mfma_f32_16x16x32_bf16 v[36:39], v[162:165], v[202:205], 0
	v_mfma_f32_16x16x32_bf16 v[32:35], v[170:173], v[202:205], 0
	v_mfma_f32_16x16x32_bf16 v[20:23], v[162:165], v[210:213], 0
	v_mfma_f32_16x16x32_bf16 v[16:19], v[170:173], v[210:213], 0
	v_mfma_f32_16x16x32_bf16 v[4:7], v[162:165], v[218:221], 0
	v_mfma_f32_16x16x32_bf16 v[0:3], v[170:173], v[218:221], 0
	v_mfma_f32_16x16x32_bf16 v[52:55], v[166:169], v[198:201], v[52:55]
	v_mfma_f32_16x16x32_bf16 v[48:51], v[190:193], v[198:201], v[48:51]
	v_mfma_f32_16x16x32_bf16 v[36:39], v[166:169], v[206:209], v[36:39]
	v_mfma_f32_16x16x32_bf16 v[32:35], v[190:193], v[206:209], v[32:35]
	v_mfma_f32_16x16x32_bf16 v[20:23], v[166:169], v[214:217], v[20:23]
	v_mfma_f32_16x16x32_bf16 v[16:19], v[190:193], v[214:217], v[16:19]
	v_mfma_f32_16x16x32_bf16 v[4:7], v[166:169], v[222:225], v[4:7]
	v_mfma_f32_16x16x32_bf16 v[0:3], v[190:193], v[222:225], v[0:3]
	s_setprio 0
	s_barrier
	s_add_i32 s54, 0, 0x18000
	s_add_i32 s55, 0, 0x1c000
	v_add_u32_e32 v140, s54, v177
	v_add_u32_e32 v189, s55, v177
	ds_read_b128 v[128:131], v140
	ds_read_b128 v[132:135], v140 offset:1024
	ds_read_b128 v[136:139], v140 offset:2048
	ds_read_b128 v[140:143], v140 offset:3072
	ds_read_b128 v[162:165], v189
	ds_read_b128 v[166:169], v189 offset:1024
	ds_read_b128 v[170:173], v189 offset:2048
	ds_read_b128 v[190:193], v189 offset:3072
	s_add_u32 s30, s30, 0x40000
	s_addc_u32 s31, s31, 0
	s_mov_b32 m0, s39
	v_lshl_add_u64 v[234:235], s[30:31], 0, v[144:145]
	ds_read_b128 v[194:197], v185 offset:32768
	ds_read_b128 v[198:201], v185 offset:33792
	ds_read_b128 v[202:205], v185 offset:34816
	ds_read_b128 v[206:209], v185 offset:35840
	ds_read_b128 v[210:213], v185 offset:36864
	ds_read_b128 v[214:217], v185 offset:37888
	ds_read_b128 v[218:221], v185 offset:38912
	ds_read_b128 v[222:225], v185 offset:39936
	global_load_lds_dwordx4 v[234:235], off
	v_lshl_add_u64 v[234:235], s[30:31], 0, v[148:149]
	s_mov_b32 m0, s40
	s_nop 0
	global_load_lds_dwordx4 v[234:235], off
	s_waitcnt vmcnt(8)
	s_waitcnt lgkmcnt(0)
	s_barrier
	s_setprio 1
	s_waitcnt lgkmcnt(0)
	v_mfma_f32_16x16x32_bf16 v[124:127], v[128:131], v[194:197], v[124:127]
	v_mfma_f32_16x16x32_bf16 v[120:123], v[136:139], v[194:197], v[120:123]
	v_mfma_f32_16x16x32_bf16 v[108:111], v[128:131], v[202:205], v[108:111]
	v_mfma_f32_16x16x32_bf16 v[104:107], v[136:139], v[202:205], v[104:107]
	v_mfma_f32_16x16x32_bf16 v[92:95], v[128:131], v[210:213], v[92:95]
	v_mfma_f32_16x16x32_bf16 v[88:91], v[136:139], v[210:213], v[88:91]
	v_mfma_f32_16x16x32_bf16 v[76:79], v[128:131], v[218:221], v[76:79]
	v_mfma_f32_16x16x32_bf16 v[72:75], v[136:139], v[218:221], v[72:75]
	v_mfma_f32_16x16x32_bf16 v[124:127], v[132:135], v[198:201], v[124:127]
	v_mfma_f32_16x16x32_bf16 v[120:123], v[140:143], v[198:201], v[120:123]
	v_mfma_f32_16x16x32_bf16 v[108:111], v[132:135], v[206:209], v[108:111]
	v_mfma_f32_16x16x32_bf16 v[104:107], v[140:143], v[206:209], v[104:107]
	v_mfma_f32_16x16x32_bf16 v[92:95], v[132:135], v[214:217], v[92:95]
	v_mfma_f32_16x16x32_bf16 v[88:91], v[140:143], v[214:217], v[88:91]
	v_mfma_f32_16x16x32_bf16 v[76:79], v[132:135], v[222:225], v[76:79]
	v_mfma_f32_16x16x32_bf16 v[72:75], v[140:143], v[222:225], v[72:75]
	s_setprio 0
	s_setprio 1
	v_mfma_f32_16x16x32_bf16 v[116:119], v[162:165], v[194:197], v[116:119]
	v_mfma_f32_16x16x32_bf16 v[112:115], v[170:173], v[194:197], v[112:115]
	v_mfma_f32_16x16x32_bf16 v[100:103], v[162:165], v[202:205], v[100:103]
	v_mfma_f32_16x16x32_bf16 v[96:99], v[170:173], v[202:205], v[96:99]
	v_mfma_f32_16x16x32_bf16 v[84:87], v[162:165], v[210:213], v[84:87]
	v_mfma_f32_16x16x32_bf16 v[80:83], v[170:173], v[210:213], v[80:83]
	v_mfma_f32_16x16x32_bf16 v[68:71], v[162:165], v[218:221], v[68:71]
	v_mfma_f32_16x16x32_bf16 v[64:67], v[170:173], v[218:221], v[64:67]
	v_mfma_f32_16x16x32_bf16 v[116:119], v[166:169], v[198:201], v[116:119]
	v_mfma_f32_16x16x32_bf16 v[112:115], v[190:193], v[198:201], v[112:115]
	v_mfma_f32_16x16x32_bf16 v[100:103], v[166:169], v[206:209], v[100:103]
	v_mfma_f32_16x16x32_bf16 v[96:99], v[190:193], v[206:209], v[96:99]
	v_mfma_f32_16x16x32_bf16 v[84:87], v[166:169], v[214:217], v[84:87]
	v_mfma_f32_16x16x32_bf16 v[80:83], v[190:193], v[214:217], v[80:83]
	v_mfma_f32_16x16x32_bf16 v[68:71], v[166:169], v[222:225], v[68:71]
	v_mfma_f32_16x16x32_bf16 v[64:67], v[190:193], v[222:225], v[64:67]
	s_setprio 0
	s_barrier
; #define PG8_STAGE(bufoff, gbase, voff) do { _Pragma("unroll") for (int _i = 0; _i < 2; ++_i) \
;         __builtin_amdgcn_global_load_lds((const unsigned*)((const char*)(gbase) + (voff)[_i]), (PG8_LAS unsigned*)(lds + (bufoff) + ldsw + _i * 8192), 16, 0, 0); } while (0)
; #define PG8_LDA(dst, b, h) do { _Pragma("unroll") for (int m = 0; m < 4; ++m) _Pragma("unroll") for (int k = 0; k < 2; ++k) dst[m][k] = *(const PG8_LAS bf16x8*)(lds + PG8_SA(b, h) + aoff + m * 2048 + k * 1024); } while (0)
; #define PG8_MMA(ai, bj, At, Bt) do { __builtin_amdgcn_s_setprio(1); _Pragma("unroll") for (int m = 0; m < 4; ++m) _Pragma("unroll") for (int n = 0; n < 2; ++n) _Pragma("unroll") for (int k = 0; k < 2; ++k) \
;         acc[ai][bj][m][n] = __builtin_amdgcn_mfma_f32_16x16x32_bf16(Bt[n][k], At[m][k], acc[ai][bj][m][n], 0, 0, 0); __builtin_amdgcn_s_setprio(0); } while (0)
; #define PG8_WAIT_V(n) asm volatile("s_waitcnt vmcnt(" #n ")" ::: "memory")
; #define PG8_WAIT_L(n) asm volatile("s_waitcnt lgkmcnt(" #n ")" ::: "memory")
; #define PG8_BAR __builtin_amdgcn_s_barrier()
; #define PG8_SCHED __builtin_amdgcn_sched_barrier(0)
; template <class Epi, class Sched, bool ALIGN_EPI = false, bool SP2 = false>
; __device__ __forceinline__ void gemm_phase(PG8_LAS unsigned char* lds, const Gemm g, const Sched& S, const Epi& E) {
;     ...
;             if (last && has_next) S.a_ready(nxt);
;     ...
;             PG8_LDA(At, 1, 1); PG8_STAGE(PG8_SB(1, 0), b3, voffB); PG8_STAGE(PG8_SB(1, 1), b3 + hstep, voffB); PG8_STAGE(PG8_SA(1, 0), a3, voffA);
;             PG8_WAIT_V(8); PG8_WAIT_L(0); PG8_BAR; PG8_MMA(1, 0, At, B0); PG8_MMA(1, 1, At, B1); PG8_BAR; PG8_SCHED;
	s_add_i32 s30, s54, s33
	v_lshl_add_u64 v[226:227], v[226:227], 0, s[14:15]
	s_mov_b32 m0, s30
	ds_read_b128 v[194:197], v185 offset:49152
	ds_read_b128 v[198:201], v185 offset:50176
	ds_read_b128 v[202:205], v185 offset:51200
	ds_read_b128 v[206:209], v185 offset:52224
	ds_read_b128 v[210:213], v185 offset:53248
	ds_read_b128 v[214:217], v185 offset:54272
	ds_read_b128 v[218:221], v185 offset:55296
	ds_read_b128 v[222:225], v185 offset:56320
	global_load_lds_dwordx4 v[226:227], off
	s_add_i32 m0, s30, 0x2000
	s_add_u32 s10, s10, 0x40080
	v_lshl_add_u64 v[226:227], v[228:229], 0, s[14:15]
	s_addc_u32 s11, s11, 0
	s_add_i32 s30, s55, s33
	global_load_lds_dwordx4 v[226:227], off
	v_lshl_add_u64 v[226:227], s[10:11], 0, v[146:147]
	s_mov_b32 m0, s30
	s_nop 0
	global_load_lds_dwordx4 v[226:227], off
	v_lshl_add_u64 v[226:227], s[10:11], 0, v[150:151]
	s_add_i32 m0, s30, 0x2000
	s_nop 0
	global_load_lds_dwordx4 v[226:227], off
	v_lshl_add_u64 v[226:227], v[230:231], 0, s[14:15]
	s_mov_b32 m0, s45
	s_nop 0
	global_load_lds_dwordx4 v[226:227], off
	v_lshl_add_u64 v[226:227], v[232:233], 0, s[14:15]
	s_mov_b32 m0, s46
	s_nop 0
	global_load_lds_dwordx4 v[226:227], off
	s_waitcnt vmcnt(8)
	s_waitcnt lgkmcnt(0)
	s_barrier
	s_setprio 1
	s_waitcnt lgkmcnt(0)
	v_mfma_f32_16x16x32_bf16 v[60:63], v[128:131], v[194:197], v[60:63]
	v_mfma_f32_16x16x32_bf16 v[56:59], v[136:139], v[194:197], v[56:59]
	v_mfma_f32_16x16x32_bf16 v[44:47], v[128:131], v[202:205], v[44:47]
	v_mfma_f32_16x16x32_bf16 v[40:43], v[136:139], v[202:205], v[40:43]
	v_mfma_f32_16x16x32_bf16 v[28:31], v[128:131], v[210:213], v[28:31]
	v_mfma_f32_16x16x32_bf16 v[24:27], v[136:139], v[210:213], v[24:27]
	v_mfma_f32_16x16x32_bf16 v[12:15], v[128:131], v[218:221], v[12:15]
	v_mfma_f32_16x16x32_bf16 v[8:11], v[136:139], v[218:221], v[8:11]
	v_mfma_f32_16x16x32_bf16 v[60:63], v[132:135], v[198:201], v[60:63]
	v_mfma_f32_16x16x32_bf16 v[56:59], v[140:143], v[198:201], v[56:59]
	v_mfma_f32_16x16x32_bf16 v[44:47], v[132:135], v[206:209], v[44:47]
	v_mfma_f32_16x16x32_bf16 v[40:43], v[140:143], v[206:209], v[40:43]
	v_mfma_f32_16x16x32_bf16 v[28:31], v[132:135], v[214:217], v[28:31]
	v_mfma_f32_16x16x32_bf16 v[24:27], v[140:143], v[214:217], v[24:27]
	v_mfma_f32_16x16x32_bf16 v[12:15], v[132:135], v[222:225], v[12:15]
	v_mfma_f32_16x16x32_bf16 v[8:11], v[140:143], v[222:225], v[8:11]
	s_setprio 0
	s_setprio 1
	v_mfma_f32_16x16x32_bf16 v[52:55], v[162:165], v[194:197], v[52:55]
	v_mfma_f32_16x16x32_bf16 v[48:51], v[170:173], v[194:197], v[48:51]
	v_mfma_f32_16x16x32_bf16 v[36:39], v[162:165], v[202:205], v[36:39]
	v_mfma_f32_16x16x32_bf16 v[32:35], v[170:173], v[202:205], v[32:35]
	v_mfma_f32_16x16x32_bf16 v[20:23], v[162:165], v[210:213], v[20:23]
	v_mfma_f32_16x16x32_bf16 v[16:19], v[170:173], v[210:213], v[16:19]
	v_mfma_f32_16x16x32_bf16 v[4:7], v[162:165], v[218:221], v[4:7]
	v_mfma_f32_16x16x32_bf16 v[0:3], v[170:173], v[218:221], v[0:3]
	v_mfma_f32_16x16x32_bf16 v[52:55], v[166:169], v[198:201], v[52:55]
	v_mfma_f32_16x16x32_bf16 v[48:51], v[190:193], v[198:201], v[48:51]
	v_mfma_f32_16x16x32_bf16 v[36:39], v[166:169], v[206:209], v[36:39]
	v_mfma_f32_16x16x32_bf16 v[32:35], v[190:193], v[206:209], v[32:35]
	v_mfma_f32_16x16x32_bf16 v[20:23], v[166:169], v[214:217], v[20:23]
	v_mfma_f32_16x16x32_bf16 v[16:19], v[190:193], v[214:217], v[16:19]
	v_mfma_f32_16x16x32_bf16 v[4:7], v[166:169], v[222:225], v[4:7]
	v_mfma_f32_16x16x32_bf16 v[0:3], v[190:193], v[222:225], v[0:3]
	s_setprio 0
	s_barrier
	s_add_i32 s53, s53, 2
	s_add_u32 s4, s4, 0x100
	s_addc_u32 s5, s5, 0
	s_add_u32 s34, s34, 0x100
	s_addc_u32 s35, s35, 0
	s_cmp_gt_u32 s53, 13
	s_cbranch_scc0 .LBB0_765

; __device__ __forceinline__ unsigned cvt_pk_bf16(float lo, float hi) { unsigned r; asm volatile("v_cvt_pk_bf16_f32 %0, %1, %2" : "=v"(r) : "v"(lo), "v"(hi)); return r; }
; __device__ __forceinline__ float fsilu(float x) { return x * __builtin_amdgcn_rcpf(1.0f + __builtin_amdgcn_exp2f(-1.4426950408889634f * x)); }
;     __device__ __forceinline__ void operator()(const f32x4 (&acc)[2][2][4][2], const Unit& u, int wr, int wc, int fr, int fq) const {
;     ...
;                 for (int bj = 0; bj < 2; ++bj) { f32x4 a = acc[ai][bj][m][0] * rs, b = acc[ai][bj][m][1] * rs; const size_t off = (size_t)row * 512 + colg + bj * HALF;
;                     if (grp == 1) { float* ZF = (float*)(ws + WS_ZF); *(f32x4*)(ZF + off) = a; *(f32x4*)(ZF + off + 4) = b; }
;                     else { if (grp == 0 || grp == 3) { a = (f32x4){fsilu(a[0]), fsilu(a[1]), fsilu(a[2]), fsilu(a[3])}; b = (f32x4){fsilu(b[0]), fsilu(b[1]), fsilu(b[2]), fsilu(b[3])}; }
;                         const size_t doff = grp == 0 ? WS_QH : (grp == 2 ? WS_VH : (grp == 3 ? WS_GH : WS_SV)); bf16_t* dst = (bf16_t*)(ws + doff);
;                         u32x4 w; w.x = cvt_pk_bf16(a[0], a[1]); w.y = cvt_pk_bf16(a[2], a[3]); w.z = cvt_pk_bf16(b[0], b[1]); w.w = cvt_pk_bf16(b[2], b[3]);
;                         *(u32x4*)(dst + off) = w; } } }
.LBB0_771:
	s_cmp_lg_u32 s1, 1
	s_cselect_b64 s[4:5], -1, 0
	s_cmp_eq_u32 s1, 3
	s_cselect_b64 s[10:11], -1, 0
	s_and_b64 s[30:31], s[10:11], exec
	s_mov_b32 s9, 0x7480000
	s_cselect_b32 s9, s9, 0xce80000
	s_cmp_lg_u32 s1, 2
	s_cselect_b32 s21, s9, 0x6440000
	s_cmp_lt_u32 s8, 2
	s_cselect_b64 s[8:9], -1, 0
	s_and_b64 s[30:31], s[8:9], exec
	s_cselect_b32 s21, 0x5400000, s21
	s_cmp_eq_u32 s21, 0xce80000
	s_cselect_b32 s101, 1, 0
	v_readlane_b32 s98, v237, 2
	v_readlane_b32 s99, v237, 3
	s_nop 0
	s_add_u32 s98, s98, 0xce80000
	s_addc_u32 s99, s99, 0
	s_or_b64 s[8:9], s[8:9], s[10:11]
	v_lshl_or_b32 v189, s0, 8, v182
	v_lshlrev_b64 v[172:173], 9, v[166:167]
	v_cndmask_b32_e64 v136, 0, 1, s[8:9]
	v_or_b32_e32 v172, v172, v189
	s_waitcnt lgkmcnt(0)
	v_pk_mul_f32 v[130:131], v[126:127], v[170:171] op_sel_hi:[1,0]
	v_pk_mul_f32 v[128:129], v[124:125], v[170:171] op_sel_hi:[1,0]
	v_pk_mul_f32 v[134:135], v[122:123], v[170:171] op_sel_hi:[1,0]
	v_pk_mul_f32 v[132:133], v[120:121], v[170:171] op_sel_hi:[1,0]
	s_mov_b64 s[10:11], -1
	s_and_b64 vcc, exec, s[4:5]
	v_cmp_ne_u32_e64 s[8:9], 1, v136
	s_cbranch_vccz .LBB0_775
	v_mov_b64_e32 v[138:139], v[130:131]
	v_mov_b64_e32 v[142:143], v[134:135]
	s_and_b64 vcc, exec, s[8:9]
	v_mov_b64_e32 v[136:137], v[128:129]
	v_mov_b64_e32 v[140:141], v[132:133]
	s_cbranch_vccnz .LBB0_774
	v_mul_f32_e32 v136, 0xbfb8aa3b, v128
	v_mul_f32_e32 v137, 0xbfb8aa3b, v129
	v_mul_f32_e32 v138, 0xbfb8aa3b, v130
	v_mul_f32_e32 v139, 0xbfb8aa3b, v131
	v_mul_f32_e32 v140, 0xbfb8aa3b, v132
	v_mul_f32_e32 v141, 0xbfb8aa3b, v133
	v_mul_f32_e32 v142, 0xbfb8aa3b, v134
	v_mul_f32_e32 v143, 0xbfb8aa3b, v135
	v_exp_f32_e32 v136, v136
	v_exp_f32_e32 v137, v137
	v_exp_f32_e32 v138, v138
	v_exp_f32_e32 v139, v139
	v_exp_f32_e32 v140, v140
	v_exp_f32_e32 v141, v141
	v_exp_f32_e32 v142, v142
	v_exp_f32_e32 v143, v143
	v_add_f32_e32 v136, 1.0, v136
	v_add_f32_e32 v137, 1.0, v137
	v_add_f32_e32 v138, 1.0, v138
	v_add_f32_e32 v139, 1.0, v139
	v_add_f32_e32 v140, 1.0, v140
	v_add_f32_e32 v141, 1.0, v141
	v_add_f32_e32 v142, 1.0, v142
	v_add_f32_e32 v143, 1.0, v143
	v_rcp_f32_e32 v136, v136
	v_rcp_f32_e32 v137, v137
	v_rcp_f32_e32 v138, v138
	v_rcp_f32_e32 v139, v139
	v_rcp_f32_e32 v140, v140
	v_rcp_f32_e32 v142, v142
	v_rcp_f32_e32 v143, v143
	v_rcp_f32_e32 v141, v141
	v_pk_mul_f32 v[138:139], v[130:131], v[138:139]
	v_pk_mul_f32 v[136:137], v[128:129], v[136:137]
	v_pk_mul_f32 v[142:143], v[134:135], v[142:143]
	v_pk_mul_f32 v[140:141], v[132:133], v[140:141]
.LBB0_774:
	v_readlane_b32 s10, v237, 2
	v_readlane_b32 s11, v237, 3
	s_add_u32 s10, s10, s21
	s_addc_u32 s11, s11, 0
	v_cvt_pk_bf16_f32 v136, v136, v137
	v_cvt_pk_bf16_f32 v137, v138, v139
	v_cvt_pk_bf16_f32 v138, v140, v141
	v_lshl_add_u64 v[140:141], v[172:173], 1, s[10:11]
	s_mov_b64 s[10:11], 0
	v_cvt_pk_bf16_f32 v139, v142, v143
	v_accvgpr_write_b32 a0, v224
	v_accvgpr_write_b32 a1, v225
	v_accvgpr_write_b32 a2, v226
	v_accvgpr_write_b32 a3, v228
	v_accvgpr_write_b32 a4, v229
	v_subrev_u32_e32 v224, s98, v140
	v_lshrrev_b32_e32 v225, 10, v224
	v_and_b32_e32 v226, 0x3ff, v224
	v_lshrrev_b32_e32 v228, 7, v226
	v_mul_u32_u24_e32 v228, 0x204000, v228
	v_bfe_u32 v229, v226, 4, 2
	v_lshl_add_u32 v228, v229, 10, v228
	v_bfe_u32 v229, v226, 6, 1
	v_lshl_add_u32 v228, v229, 4, v228
	v_add_u32_e32 v229, 0x80, v225
	v_and_b32_e32 v226, 0xff, v225
	v_cmp_gt_u32_e32 vcc, 16, v226
	v_and_b32_e32 v224, 63, v226
	v_add_u32_e32 v226, 0x70, v226
	s_nop 1
	v_cndmask_b32_e32 v224, v224, v226, vcc
	v_cmp_lt_u32_e32 vcc, 0x3fff, v225
	s_nop 2
	v_cndmask_b32_e32 v229, v229, v224, vcc
	v_lshrrev_b32_e32 v224, 5, v229
	v_lshl_add_u32 v228, v224, 12, v228
	v_and_b32_e32 v224, 31, v229
	v_lshl_add_u32 v228, v224, 5, v228
	v_mov_b32_e32 v229, 0
	v_lshl_add_u64 v[224:225], s[98:99], 0, v[228:229]
	v_cmp_eq_u32_e64 vcc, s101, 1
	s_nop 2
	v_cndmask_b32_e32 v224, v140, v224, vcc
	v_cndmask_b32_e32 v225, v141, v225, vcc
	global_store_dwordx4 v[224:225], v[136:139], off
	s_nop 1
	v_accvgpr_read_b32 v224, a0
	v_accvgpr_read_b32 v225, a1
	v_accvgpr_read_b32 v226, a2
	v_accvgpr_read_b32 v228, a3
	v_accvgpr_read_b32 v229, a4

; __device__ __forceinline__ unsigned cvt_pk_bf16(float lo, float hi) { unsigned r; asm volatile("v_cvt_pk_bf16_f32 %0, %1, %2" : "=v"(r) : "v"(lo), "v"(hi)); return r; }
; __device__ __forceinline__ float fsilu(float x) { return x * __builtin_amdgcn_rcpf(1.0f + __builtin_amdgcn_exp2f(-1.4426950408889634f * x)); }
;     __device__ __forceinline__ void operator()(const f32x4 (&acc)[2][2][4][2], const Unit& u, int wr, int wc, int fr, int fq) const {
;     ...
;                 for (int bj = 0; bj < 2; ++bj) { f32x4 a = acc[ai][bj][m][0] * rs, b = acc[ai][bj][m][1] * rs; const size_t off = (size_t)row * 512 + colg + bj * HALF;
;                     if (grp == 1) { float* ZF = (float*)(ws + WS_ZF); *(f32x4*)(ZF + off) = a; *(f32x4*)(ZF + off + 4) = b; }
;                     else { if (grp == 0 || grp == 3) { a = (f32x4){fsilu(a[0]), fsilu(a[1]), fsilu(a[2]), fsilu(a[3])}; b = (f32x4){fsilu(b[0]), fsilu(b[1]), fsilu(b[2]), fsilu(b[3])}; }
;                         const size_t doff = grp == 0 ? WS_QH : (grp == 2 ? WS_VH : (grp == 3 ? WS_GH : WS_SV)); bf16_t* dst = (bf16_t*)(ws + doff);
;                         u32x4 w; w.x = cvt_pk_bf16(a[0], a[1]); w.y = cvt_pk_bf16(a[2], a[3]); w.z = cvt_pk_bf16(b[0], b[1]); w.w = cvt_pk_bf16(b[2], b[3]);
;                         *(u32x4*)(dst + off) = w; } } }
.LBB0_780:
	v_readlane_b32 s4, v237, 2
	v_readlane_b32 s5, v237, 3
	s_add_u32 s4, s4, s21
	s_addc_u32 s5, s5, 0
	v_cvt_pk_bf16_f32 v136, v136, v137
	v_cvt_pk_bf16_f32 v137, v138, v139
	v_cvt_pk_bf16_f32 v138, v140, v141
	v_lshl_add_u64 v[140:141], v[172:173], 1, s[4:5]
	s_mov_b64 s[4:5], 0
	v_cvt_pk_bf16_f32 v139, v142, v143
	v_accvgpr_write_b32 a0, v224
	v_accvgpr_write_b32 a1, v225
	v_accvgpr_write_b32 a2, v226
	v_accvgpr_write_b32 a3, v228
	v_accvgpr_write_b32 a4, v229
	v_subrev_u32_e32 v224, s98, v140
	v_add_u32_e32 v224, 0x100, v224
	v_lshrrev_b32_e32 v225, 10, v224
	v_and_b32_e32 v226, 0x3ff, v224
	v_lshrrev_b32_e32 v228, 7, v226
	v_mul_u32_u24_e32 v228, 0x204000, v228
	v_bfe_u32 v229, v226, 4, 2
	v_lshl_add_u32 v228, v229, 10, v228
	v_bfe_u32 v229, v226, 6, 1
	v_lshl_add_u32 v228, v229, 4, v228
	v_add_u32_e32 v229, 0x80, v225
	v_and_b32_e32 v226, 0xff, v225
	v_cmp_gt_u32_e32 vcc, 16, v226
	v_and_b32_e32 v224, 63, v226
	v_add_u32_e32 v226, 0x70, v226
	s_nop 1
	v_cndmask_b32_e32 v224, v224, v226, vcc
	v_cmp_lt_u32_e32 vcc, 0x3fff, v225
	s_nop 2
	v_cndmask_b32_e32 v229, v229, v224, vcc
	v_lshrrev_b32_e32 v224, 5, v229
	v_lshl_add_u32 v228, v224, 12, v228
	v_and_b32_e32 v224, 31, v229
	v_lshl_add_u32 v228, v224, 5, v228
	v_mov_b32_e32 v229, 0
	v_lshl_add_u64 v[224:225], s[98:99], 0, v[228:229]
	v_mov_b32_e32 v228, 0x100
	v_lshl_add_u64 v[228:229], v[140:141], 0, v[228:229]
	v_cmp_eq_u32_e64 vcc, s101, 1
	s_nop 2
	v_cndmask_b32_e32 v224, v228, v224, vcc
	v_cndmask_b32_e32 v225, v229, v225, vcc
	global_store_dwordx4 v[224:225], v[136:139], off
	s_nop 1
	v_accvgpr_read_b32 v224, a0
	v_accvgpr_read_b32 v225, a1
	v_accvgpr_read_b32 v226, a2
	v_accvgpr_read_b32 v228, a3
	v_accvgpr_read_b32 v229, a4

; __device__ __forceinline__ unsigned cvt_pk_bf16(float lo, float hi) { unsigned r; asm volatile("v_cvt_pk_bf16_f32 %0, %1, %2" : "=v"(r) : "v"(lo), "v"(hi)); return r; }
; __device__ __forceinline__ float fsilu(float x) { return x * __builtin_amdgcn_rcpf(1.0f + __builtin_amdgcn_exp2f(-1.4426950408889634f * x)); }
;     __device__ __forceinline__ void operator()(const f32x4 (&acc)[2][2][4][2], const Unit& u, int wr, int wc, int fr, int fq) const {
;     ...
;                 for (int bj = 0; bj < 2; ++bj) { f32x4 a = acc[ai][bj][m][0] * rs, b = acc[ai][bj][m][1] * rs; const size_t off = (size_t)row * 512 + colg + bj * HALF;
;                     if (grp == 1) { float* ZF = (float*)(ws + WS_ZF); *(f32x4*)(ZF + off) = a; *(f32x4*)(ZF + off + 4) = b; }
;                     else { if (grp == 0 || grp == 3) { a = (f32x4){fsilu(a[0]), fsilu(a[1]), fsilu(a[2]), fsilu(a[3])}; b = (f32x4){fsilu(b[0]), fsilu(b[1]), fsilu(b[2]), fsilu(b[3])}; }
;                         const size_t doff = grp == 0 ? WS_QH : (grp == 2 ? WS_VH : (grp == 3 ? WS_GH : WS_SV)); bf16_t* dst = (bf16_t*)(ws + doff);
;                         u32x4 w; w.x = cvt_pk_bf16(a[0], a[1]); w.y = cvt_pk_bf16(a[2], a[3]); w.z = cvt_pk_bf16(b[0], b[1]); w.w = cvt_pk_bf16(b[2], b[3]);
;                         *(u32x4*)(dst + off) = w; } } }
.LBB0_786:
	v_readlane_b32 s4, v237, 2
	v_readlane_b32 s5, v237, 3
	s_add_u32 s4, s4, s21
	s_addc_u32 s5, s5, 0
	v_cvt_pk_bf16_f32 v136, v136, v137
	v_cvt_pk_bf16_f32 v137, v138, v139
	v_cvt_pk_bf16_f32 v138, v140, v141
	v_lshl_add_u64 v[140:141], v[172:173], 1, s[4:5]
	s_mov_b64 s[4:5], 0
	v_cvt_pk_bf16_f32 v139, v142, v143
	v_accvgpr_write_b32 a0, v224
	v_accvgpr_write_b32 a1, v225
	v_accvgpr_write_b32 a2, v226
	v_accvgpr_write_b32 a3, v228
	v_accvgpr_write_b32 a4, v229
	v_subrev_u32_e32 v224, s98, v140
	v_lshrrev_b32_e32 v225, 10, v224
	v_and_b32_e32 v226, 0x3ff, v224
	v_lshrrev_b32_e32 v228, 7, v226
	v_mul_u32_u24_e32 v228, 0x204000, v228
	v_bfe_u32 v229, v226, 4, 2
	v_lshl_add_u32 v228, v229, 10, v228
	v_bfe_u32 v229, v226, 6, 1
	v_lshl_add_u32 v228, v229, 4, v228
	v_add_u32_e32 v229, 0x80, v225
	v_and_b32_e32 v226, 0xff, v225
	v_cmp_gt_u32_e32 vcc, 16, v226
	v_and_b32_e32 v224, 63, v226
	v_add_u32_e32 v226, 0x70, v226
	s_nop 1
	v_cndmask_b32_e32 v224, v224, v226, vcc
	v_cmp_lt_u32_e32 vcc, 0x3fff, v225
	s_nop 2
	v_cndmask_b32_e32 v229, v229, v224, vcc
	v_lshrrev_b32_e32 v224, 5, v229
	v_lshl_add_u32 v228, v224, 12, v228
	v_and_b32_e32 v224, 31, v229
	v_lshl_add_u32 v228, v224, 5, v228
	v_mov_b32_e32 v229, 0
	v_lshl_add_u64 v[224:225], s[98:99], 0, v[228:229]
	v_cmp_eq_u32_e64 vcc, s101, 1
	s_nop 2
	v_cndmask_b32_e32 v224, v140, v224, vcc
	v_cndmask_b32_e32 v225, v141, v225, vcc
	global_store_dwordx4 v[224:225], v[136:139], off
	s_nop 1
	v_accvgpr_read_b32 v224, a0
	v_accvgpr_read_b32 v225, a1
	v_accvgpr_read_b32 v226, a2
	v_accvgpr_read_b32 v228, a3
	v_accvgpr_read_b32 v229, a4

; #define LAS __attribute__((address_space(3)))
; __device__ __forceinline__ void sb_load(SbTile& t, const bf16* SK, const bf16* SV, int h, int kt, int lane) {
;     const bf16* kp = SK + (size_t)pos2row(kt + (lane & 31)) * 512 + h * 64 + 8 * (lane >> 5);
;     const bf16* vp = SV + (size_t)pos2row(kt + (lane >> 1)) * 512 + h * 64 + 32 * (lane & 1);
; #pragma unroll
;     for (int j = 0; j < 4; ++j) { t.k[j] = *(const bf16x8*)(kp + 16 * j); t.v[j] = *(const u32x4*)(vp + 8 * j); }
; }
; __device__ __forceinline__ void sb_strip(const bf16* SQ, const bf16* SK, const bf16* SV, bf16* OMIX, int h, int qpos0, int lane, LAS unsigned char* vl) {
;     const int l32 = lane & 31, hi = lane >> 5;
;     const int qrow = qpos0 - 128 + l32;
;     SbTile t0, t1, t2;
;     sb_load(t0, SK, SV, h, qpos0, lane); sb_load(t1, SK, SV, h, qpos0 - 32, lane);
;     bf16x8 qf[4];
;     { const bf16* qp = SQ + (size_t)qrow * 512 + h * 64 + 8 * hi;
; #pragma unroll
;       for (int j = 0; j < 4; ++j) qf[j] = *(const bf16x8*)(qp + 16 * j); }
.LBB0_1043:
	s_lshl_b32 s4, s28, 5
	s_and_b32 s6, s4, 0x3fe0
	s_add_i32 s4, s6, 0x80
	v_or_b32_e32 v202, s4, v181
	v_add_u32_e32 v0, 0xffffff80, v202
	s_ashr_i32 s4, s28, 3
	v_lshlrev_b64 v[2:3], 10, v[0:1]
	s_and_b32 s24, s4, 0xffffffc0
	v_or_b32_e32 v0, s6, v193
	s_ashr_i32 s25, s24, 31
	v_lshlrev_b32_e32 v0, 10, v0
	v_lshl_add_u64 v[2:3], s[20:21], 0, v[2:3]
	s_lshl_b64 s[4:5], s[24:25], 1
	v_lshl_add_u64 v[4:5], s[22:23], 0, v[0:1]
	v_or_b32_e32 v192, s6, v181
	v_lshl_add_u64 v[2:3], v[2:3], 0, s[4:5]
	v_lshl_add_u64 v[4:5], v[4:5], 0, s[4:5]
	s_addk_i32 s6, 0x60
	s_mul_i32 s100, s24, 0x8100
	v_lshlrev_b32_e32 v222, 4, v201
	v_add_u32_e32 v222, s100, v222
	v_mov_b32_e32 v223, 0
	v_lshl_add_u64 v[218:219], s[20:21], 0, v[222:223]
	v_lshl_add_u64 v[230:231], s[22:23], 0, v[222:223]
	v_mov_b32_e32 v222, s6
	v_lshlrev_b32_e32 v222, 7, v222
	v_lshl_add_u64 v[226:227], v[218:219], 0, v[222:223]
	v_lshl_add_u64 v[234:235], v[230:231], 0, v[222:223]
	v_add_u32_e32 v222, 0x1000, v222
	v_lshl_add_u64 v[224:225], v[218:219], 0, v[222:223]
	v_lshl_add_u64 v[232:233], v[230:231], 0, v[222:223]
	s_and_b32 s46, s30, 0x3fe0
	v_lshl_add_u64 v[2:3], v[2:3], 0, v[186:187]
	v_lshl_add_u64 v[4:5], v[4:5], 0, v[188:189]
	v_or_b32_e32 v0, s6, v181
	global_load_dwordx4 v[118:121], v[232:233], off offset:3072
	global_load_dwordx4 v[126:129], v[232:233], off offset:2048
	global_load_dwordx4 v[130:133], v[232:233], off offset:1024
	global_load_dwordx4 v[134:137], v[232:233], off
	global_load_dwordx4 v[90:93], v[224:225], off
	global_load_dwordx4 v[94:97], v[224:225], off offset:1024
	global_load_dwordx4 v[86:89], v[224:225], off offset:2048
	global_load_dwordx4 v[82:85], v[224:225], off offset:3072
	s_cmpk_gt_u32 s6, 0x7f
	v_add_u32_e32 v2, 0xffffff80, v0
	v_max_u32_e32 v0, 0x70, v0
	v_add_u32_e32 v0, 0x3f90, v0
	s_cselect_b64 vcc, -1, 0
	v_cndmask_b32_e32 v0, v0, v2, vcc
	v_lshlrev_b64 v[2:3], 10, v[0:1]
	v_or_b32_e32 v0, s6, v193
	v_add_u32_e32 v4, 0xffffff80, v0
	v_max_u32_e32 v0, 0x70, v0
	v_add_u32_e32 v0, 0x3f90, v0
	v_cndmask_b32_e32 v0, v0, v4, vcc
	v_lshlrev_b64 v[4:5], 10, v[0:1]
	v_lshl_add_u64 v[4:5], s[22:23], 0, v[4:5]
	v_lshl_add_u64 v[2:3], s[20:21], 0, v[2:3]
	v_lshl_add_u64 v[4:5], v[4:5], 0, s[4:5]
	v_lshl_add_u64 v[2:3], v[2:3], 0, s[4:5]
	v_lshl_add_u64 v[4:5], v[4:5], 0, v[188:189]
	v_readlane_b32 s6, v237, 35
	v_lshl_add_u64 v[2:3], v[2:3], 0, v[186:187]
	global_load_dwordx4 v[146:149], v[234:235], off offset:3072
	global_load_dwordx4 v[150:153], v[234:235], off offset:2048
	global_load_dwordx4 v[154:157], v[234:235], off offset:1024
	global_load_dwordx4 v[158:161], v[234:235], off
	global_load_dwordx4 v[102:105], v[226:227], off
	global_load_dwordx4 v[110:113], v[226:227], off offset:1024
	global_load_dwordx4 v[106:109], v[226:227], off offset:2048
	global_load_dwordx4 v[98:101], v[226:227], off offset:3072
	v_lshlrev_b32_e32 v0, 10, v192
	v_readlane_b32 s7, v237, 36
	v_mov_b32_e32 v14, v1
	v_mov_b32_e32 v15, v1
	v_lshl_add_u64 v[2:3], s[6:7], 0, v[0:1]
	v_lshl_add_u64 v[2:3], v[2:3], 0, s[4:5]
	v_lshl_add_u64 v[2:3], v[2:3], 0, v[190:191]
	global_load_dwordx4 v[66:69], v[2:3], off
	global_load_dwordx4 v[70:73], v[2:3], off offset:32
	global_load_dwordx4 v[74:77], v[2:3], off offset:64
	global_load_dwordx4 v[78:81], v[2:3], off offset:96
	v_mov_b32_e32 v0, v1
	v_mov_b32_e32 v2, v1
	v_mov_b32_e32 v3, v1
	v_mov_b32_e32 v4, v1
	v_mov_b32_e32 v5, v1
	v_mov_b32_e32 v6, v1
	v_mov_b32_e32 v7, v1
	v_mov_b32_e32 v8, v1
	v_mov_b32_e32 v9, v1
	v_mov_b32_e32 v10, v1
	v_mov_b32_e32 v11, v1
	v_mov_b32_e32 v12, v1
	v_mov_b32_e32 v13, v1
	v_mov_b64_e32 v[32:33], v[14:15]
	v_mov_b64_e32 v[30:31], v[12:13]
	v_mov_b64_e32 v[28:29], v[10:11]
	v_mov_b64_e32 v[26:27], v[8:9]
	v_mov_b64_e32 v[24:25], v[6:7]
	v_mov_b64_e32 v[22:23], v[4:5]
	v_mov_b64_e32 v[20:21], v[2:3]
	v_mov_b64_e32 v[18:19], v[0:1]
	v_mov_b64_e32 v[16:17], v[14:15]
	v_or_b32_e32 v203, s46, v193
	v_or_b32_e32 v204, s46, v181
	v_or_b32_e32 v205, s46, v180
	v_lshl_add_u64 v[194:195], v[182:183], 0, s[4:5]
	v_lshl_add_u64 v[196:197], v[184:185], 0, s[4:5]
	s_mov_b32 s47, 0
	v_mov_b32_e32 v208, v1
	v_mov_b64_e32 v[14:15], v[12:13]
	v_mov_b64_e32 v[12:13], v[10:11]
	v_mov_b64_e32 v[10:11], v[8:9]
	v_mov_b64_e32 v[8:9], v[6:7]
	v_mov_b64_e32 v[6:7], v[4:5]
	v_mov_b64_e32 v[4:5], v[2:3]
	v_mov_b64_e32 v[2:3], v[0:1]
	s_branch .LBB0_1046

; #define SB_STEP(CUR, LD) { sb_load(LD, SK, SV, h, kt - 64, lane);     \
;         if (kt == qpos0 || kt < 128) sb_tile<true>(CUR, qf, o0, o1, carry, kt, qpos, hi, vw, vr); else sb_tile<false>(CUR, qf, o0, o1, carry, kt, qpos, hi, vw, vr); \
;         if (__all(carry > 152.0f)) break;     \
;         kt -= 32; if (kt < 96) break; }
; __device__ __forceinline__ void sb_load(SbTile& t, const bf16* SK, const bf16* SV, int h, int kt, int lane) {
;     const bf16* kp = SK + (size_t)pos2row(kt + (lane & 31)) * 512 + h * 64 + 8 * (lane >> 5);
;     const bf16* vp = SV + (size_t)pos2row(kt + (lane >> 1)) * 512 + h * 64 + 32 * (lane & 1);
; #pragma unroll
;     for (int j = 0; j < 4; ++j) { t.k[j] = *(const bf16x8*)(kp + 16 * j); t.v[j] = *(const u32x4*)(vp + 8 * j); }
; }
; __device__ __forceinline__ void sb_strip(const bf16* SQ, const bf16* SK, const bf16* SV, bf16* OMIX, int h, int qpos0, int lane, LAS unsigned char* vl) {
;     ...
;     for (int kt = qpos0;;) { SB_STEP(t0, t2) SB_STEP(t1, t0) SB_STEP(t2, t1) }
.LBB0_1046:
	s_add_i32 s49, s46, s47
	v_add_u32_e32 v206, s47, v204
	s_add_i32 s48, s49, 64
	v_add_u32_e32 v0, 64, v206
	s_cmpk_gt_u32 s48, 0x7f
	v_max_u32_e32 v0, 0x70, v0
	v_subrev_u32_e32 v34, 64, v206
	v_add_u32_e32 v0, 0x3f90, v0
	s_cselect_b64 vcc, -1, 0
	v_cndmask_b32_e32 v0, v0, v34, vcc
	v_add_u32_e32 v207, s47, v203
	v_lshlrev_b64 v[34:35], 10, v[0:1]
	v_add_u32_e32 v0, 64, v207
	v_max_u32_e32 v0, 0x70, v0
	v_subrev_u32_e32 v36, 64, v207
	v_add_u32_e32 v0, 0x3f90, v0
	v_cndmask_b32_e32 v0, v0, v36, vcc
	v_lshlrev_b64 v[36:37], 10, v[0:1]
	v_lshl_add_u64 v[36:37], v[196:197], 0, v[36:37]
	v_lshl_add_u64 v[34:35], v[194:195], 0, v[34:35]
	v_mov_b32_e32 v222, s48
	v_lshlrev_b32_e32 v222, 7, v222
	v_mov_b32_e32 v223, 0
	v_lshl_add_u64 v[220:221], v[218:219], 0, v[222:223]
	v_lshl_add_u64 v[228:229], v[230:231], 0, v[222:223]
	global_load_dwordx4 v[162:165], v[228:229], off offset:3072
	global_load_dwordx4 v[166:169], v[228:229], off offset:2048
	global_load_dwordx4 v[170:173], v[228:229], off offset:1024
	global_load_dwordx4 v[174:177], v[228:229], off
	global_load_dwordx4 v[142:145], v[220:221], off
	global_load_dwordx4 v[138:141], v[220:221], off offset:1024
	global_load_dwordx4 v[122:125], v[220:221], off offset:2048
	global_load_dwordx4 v[114:117], v[220:221], off offset:3072
	v_add_co_u32_e64 v0, s[6:7], s49, v198
	s_nop 0
	v_readfirstlane_b32 s50, v0
	s_cmp_eq_u32 s47, 0
	v_exp_f32_e64 v0, -v208
	s_cselect_b64 s[4:5], -1, 0
	s_or_b64 s[4:5], s[4:5], s[6:7]
	s_andn2_b64 vcc, exec, s[4:5]
	s_mov_b64 s[4:5], -1
	s_waitcnt vmcnt(12)
	ds_write_b128 v199, v[134:137]
	ds_write_b128 v199, v[130:133] offset:16
	ds_write_b128 v199, v[126:129] offset:32
	ds_write_b128 v199, v[118:121] offset:48
	s_cbranch_vccz .LBB0_1048
; #define LAS __attribute__((address_space(3)))
; __device__ __forceinline__ unsigned cvtpk_s(float lo, float hi) { f32x2_t v = {lo, hi}; bf16x2_t b = __builtin_convertvector(v, bf16x2_t); return __builtin_bit_cast(unsigned, b); }
; template <bool MASK> __device__ __forceinline__ void sb_tile(const SbTile& t0, const bf16x8 (&qf)[4], f32x16& o0, f32x16& o1, float& carry, int kt, int qpos, int hi, LAS unsigned char* vw, const LAS unsigned char* vr) {
; #pragma unroll
;     for (int j = 0; j < 4; ++j) *(LAS u32x4*)(vw + 16 * j) = t0.v[j];
;     f32x16 z;
; #pragma unroll
;     for (int r = 0; r < 16; ++r) z[r] = 0.f;
; #pragma unroll
;     for (int j = 0; j < 4; ++j) z = MFMA32(t0.k[j], qf[j], z);
;     float kp[16], bt[16];
; #pragma unroll
;     for (int r = 0; r < 16; ++r) { const float e = __builtin_amdgcn_exp2f(z[r]); const float k = __builtin_amdgcn_rcpf(1.0f + e); const float b = e * k;
;         if (MASK) { const int kpos = kt + crow(r, hi); const bool okr = (kpos < qpos) && (kpos >= 112); kp[r] = okr ? k : 1.0f; bt[r] = okr ? b : 0.f; } else { kp[r] = k; bt[r] = b; } }
;     float G[4], Go[4];
; #pragma unroll
;     for (int g = 0; g < 4; ++g) { G[g] = (kp[4 * g] * kp[4 * g + 1]) * (kp[4 * g + 2] * kp[4 * g + 3]); Go[g] = __shfl_xor(G[g], 32); }
;     const float c0 = __builtin_amdgcn_exp2f(-carry);
;     float offs[4]; float T = 1.0f;
; #pragma unroll
;     for (int g = 3; g >= 0; --g) { offs[g] = c0 * T * (hi == 0 ? Go[g] : 1.0f); T *= G[g] * Go[g]; }
;     f32x16 w;
; #pragma unroll
;     for (int g = 0; g < 4; ++g) { float run = offs[g];
; #pragma unroll
;         for (int i = 3; i >= 0; --i) { const int r = 4 * g + i; w[r] = bt[r] * run; run *= kp[r]; } }
;     carry -= __builtin_amdgcn_logf(T);
; #pragma unroll
;     for (int s = 0; s < 2; ++s) { u32x4 wp;
; #pragma unroll
;         for (int i = 0; i < 4; ++i) wp[i] = cvtpk_s(w[8 * s + 2 * i], w[8 * s + 2 * i + 1]);
;         const bf16x8 wb = __builtin_bit_cast(bf16x8, wp);
;         const s16x4 a0 = vtr(vr + (16 * s) * 144), a1 = vtr(vr + (16 * s + 8) * 144), b0 = vtr(vr + (16 * s) * 144 + 64), b1 = vtr(vr + (16 * s + 8) * 144 + 64);
;         const bf16x8 v0 = __builtin_shufflevector(a0, a1, 0, 1, 2, 3, 4, 5, 6, 7), v1 = __builtin_shufflevector(b0, b1, 0, 1, 2, 3, 4, 5, 6, 7);
;         o0 = MFMA32(v0, wb, o0); o1 = MFMA32(v1, wb, o1); }
; }
	s_waitcnt vmcnt(11)
	v_mfma_f32_32x32x16_bf16 v[34:49], v[90:93], v[66:69], 0
	s_mov_b64 s[4:5], 0
	s_waitcnt vmcnt(10)
	v_mfma_f32_32x32x16_bf16 v[34:49], v[94:97], v[70:73], v[34:49]
	s_waitcnt vmcnt(9)
	v_mfma_f32_32x32x16_bf16 v[34:49], v[86:89], v[74:77], v[34:49]
	s_waitcnt vmcnt(8)
	v_mfma_f32_32x32x16_bf16 v[34:49], v[82:85], v[78:81], v[34:49]
	s_nop 11
	v_exp_f32_e32 v39, v39
	v_exp_f32_e32 v40, v40
	v_exp_f32_e32 v41, v41
	v_exp_f32_e32 v42, v42
	v_exp_f32_e32 v44, v44
	v_exp_f32_e32 v45, v45
	v_exp_f32_e32 v62, v46
	v_add_f32_e32 v55, 1.0, v39
	v_add_f32_e32 v57, 1.0, v40
	v_add_f32_e32 v58, 1.0, v41
	v_add_f32_e32 v59, 1.0, v42
	v_add_f32_e32 v61, 1.0, v44
	v_add_f32_e32 v46, 1.0, v45
	v_rcp_f32_e32 v56, v55
	v_rcp_f32_e32 v55, v57
	v_rcp_f32_e32 v57, v58
	v_rcp_f32_e32 v58, v59
	v_rcp_f32_e32 v59, v61
	v_rcp_f32_e32 v61, v46
	v_exp_f32_e32 v63, v47
	v_add_f32_e32 v46, 1.0, v62
	v_rcp_f32_e32 v64, v46
	v_exp_f32_e32 v46, v48
	v_exp_f32_e32 v47, v49
	v_exp_f32_e32 v43, v43
	v_add_f32_e32 v48, 1.0, v63
	v_exp_f32_e32 v38, v38
	v_rcp_f32_e32 v130, v48
	v_add_f32_e32 v48, 1.0, v46
	v_rcp_f32_e32 v65, v48
	v_add_f32_e32 v48, 1.0, v47
	v_add_f32_e32 v60, 1.0, v43
	v_rcp_f32_e32 v131, v48
	v_rcp_f32_e32 v60, v60
	v_add_f32_e32 v54, 1.0, v38
	v_and_b32_e32 v49, 64, v201
	v_exp_f32_e32 v36, v36
	v_exp_f32_e32 v37, v37
	v_rcp_f32_e32 v54, v54
	v_xor_b32_e32 v48, 32, v201
	v_add_u32_e32 v49, 64, v49
	v_exp_f32_e32 v34, v34
	v_exp_f32_e32 v35, v35
	v_cmp_lt_i32_e32 vcc, v48, v49
	v_pk_mul_f32 v[118:119], v[64:65], v[130:131]
	v_add_f32_e32 v52, 1.0, v36
	v_cndmask_b32_e32 v48, v201, v48, vcc
	v_mul_f32_e32 v120, v118, v119
	v_pk_mul_f32 v[118:119], v[58:59], v[60:61]
	v_lshlrev_b32_e32 v126, 2, v48
	v_mul_f32_e32 v118, v118, v119
	v_add_f32_e32 v53, 1.0, v37
	v_pk_mul_f32 v[48:49], v[54:55], v[56:57]
	ds_bpermute_b32 v121, v126, v120
	ds_bpermute_b32 v127, v126, v118
	v_add_f32_e32 v50, 1.0, v34
	v_add_f32_e32 v51, 1.0, v35
	v_rcp_f32_e32 v52, v52
	v_rcp_f32_e32 v53, v53
	v_pk_mul_f32 v[48:49], v[48:49], v[48:49] op_sel:[0,1] op_sel_hi:[1,0]
	v_rcp_f32_e32 v50, v50
	v_rcp_f32_e32 v51, v51
	ds_bpermute_b32 v49, v126, v48
	s_waitcnt lgkmcnt(2)
	v_cndmask_b32_e64 v128, 1.0, v121, s[0:1]
	v_mul_f32_e32 v119, v120, v121
	s_waitcnt lgkmcnt(1)
	v_mul_f32_e32 v121, v118, v127
	v_mov_b32_e32 v118, v52
	v_mov_b32_e32 v120, v53
	v_mul_f32_e32 v129, v0, v119
	v_pk_mul_f32 v[118:119], v[118:119], v[120:121]
	v_mov_b32_e32 v120, v50
	v_mov_b32_e32 v121, v48
	v_mov_b32_e32 v48, v51
	v_cndmask_b32_e64 v132, 1.0, v127, s[0:1]
	s_waitcnt lgkmcnt(0)
	v_cndmask_b32_e64 v127, 1.0, v49, s[0:1]
	v_pk_mul_f32 v[48:49], v[120:121], v[48:49]
	v_pk_mul_f32 v[36:37], v[36:37], v[52:53]
	v_pk_mul_f32 v[210:211], v[48:49], v[118:119]
	ds_bpermute_b32 v209, v126, v210
	v_mul_f32_e32 v48, v0, v211
	v_pk_mul_f32 v[34:35], v[34:35], v[50:51]
	v_mul_f32_e32 v118, v0, v119
	v_mov_b32_e32 v50, v54
	s_waitcnt lgkmcnt(0)
	v_cndmask_b32_e64 v49, 1.0, v209, s[0:1]
	v_mul_f32_e32 v49, v49, v48
	v_mul_f32_e32 v48, v53, v49
	v_pk_mul_f32 v[36:37], v[36:37], v[48:49]
	v_mul_f32_e32 v49, v52, v48
	v_mul_f32_e32 v48, v51, v49
	v_pk_mul_f32 v[34:35], v[34:35], v[48:49]
	v_mov_b32_e32 v48, v55
	v_mov_b32_e32 v49, v57
	v_pk_mul_f32 v[40:41], v[40:41], v[48:49]
	v_mul_f32_e32 v49, v127, v118
	v_mul_f32_e32 v48, v57, v49
	v_pk_mul_f32 v[40:41], v[40:41], v[48:49]
	v_mov_b32_e32 v51, v56
	v_mul_f32_e32 v49, v55, v48
	v_pk_mul_f32 v[38:39], v[38:39], v[50:51]
	v_mul_f32_e32 v48, v56, v49
	v_pk_mul_f32 v[38:39], v[38:39], v[48:49]
	v_mov_b32_e32 v48, v59
	v_mov_b32_e32 v49, v61
	v_pk_mul_f32 v[44:45], v[44:45], v[48:49]
	v_mul_f32_e32 v49, v132, v129
	v_mul_f32_e32 v48, v61, v49
	v_pk_mul_f32 v[134:135], v[44:45], v[48:49]
	v_mov_b32_e32 v44, v58
	v_mov_b32_e32 v45, v60
	ds_read_b64_tr_b16 v[50:51], v200
	ds_read_b64_tr_b16 v[52:53], v200 offset:1152
	v_pk_mul_f32 v[42:43], v[42:43], v[44:45]
	v_mul_f32_e32 v45, v59, v48
	v_mul_f32_e32 v55, v0, v128
	ds_read_b64_tr_b16 v[128:129], v200 offset:1216
	ds_read_b64_tr_b16 v[126:127], v200 offset:64
	v_mul_f32_e32 v44, v60, v45
	v_pk_mul_f32 v[136:137], v[42:43], v[44:45]
	v_mov_b32_e32 v42, v65
	v_mov_b32_e32 v43, v131
	v_pk_mul_f32 v[42:43], v[46:47], v[42:43]
	v_mul_f32_e32 v54, v131, v55
	v_cvt_pk_bf16_f32 v118, v34, v35
	v_cvt_pk_bf16_f32 v119, v36, v37
	v_cvt_pk_bf16_f32 v120, v38, v39
	v_cvt_pk_bf16_f32 v121, v40, v41
	v_pk_mul_f32 v[212:213], v[42:43], v[54:55]
	v_mul_f32_e32 v217, v65, v54
	s_waitcnt lgkmcnt(2)
	v_mfma_f32_32x32x16_bf16 v[34:49], v[50:53], v[118:121], v[2:17]
	v_mov_b32_e32 v50, v64
	v_mov_b32_e32 v51, v130
	v_mul_f32_e64 v214, v62, v50
	v_mul_f32_e64 v215, v63, v51
	v_mul_f32_e32 v216, v130, v217
	ds_read_b64_tr_b16 v[130:131], v200 offset:2304
	ds_read_b64_tr_b16 v[132:133], v200 offset:3456
	s_waitcnt lgkmcnt(2)
	v_mfma_f32_32x32x16_bf16 v[50:65], v[126:129], v[118:121], v[18:33]
	v_cvt_pk_bf16_f32 v126, v136, v137
	v_cvt_pk_bf16_f32 v127, v134, v135
	ds_read_b64_tr_b16 v[136:137], v200 offset:3520
	ds_read_b64_tr_b16 v[134:135], v200 offset:2368
	v_mul_f32_e64 v118, v214, v216
	v_mul_f32_e64 v119, v215, v217
	v_cvt_pk_bf16_f32 v129, v212, v213
	v_cvt_pk_bf16_f32 v128, v118, v119
	v_mul_f32_e32 v118, v210, v209
	v_mul_f32_e32 v118, v118, v211
	s_waitcnt lgkmcnt(2)
	v_mfma_f32_32x32x16_bf16 v[34:49], v[130:133], v[126:129], v[34:49]
	v_log_f32_e32 v118, v118
	s_waitcnt lgkmcnt(0)
	v_mfma_f32_32x32x16_bf16 v[50:65], v[134:137], v[126:129], v[50:65]

; #define SB_STEP(CUR, LD) { sb_load(LD, SK, SV, h, kt - 64, lane);     \
;         if (kt == qpos0 || kt < 128) sb_tile<true>(CUR, qf, o0, o1, carry, kt, qpos, hi, vw, vr); else sb_tile<false>(CUR, qf, o0, o1, carry, kt, qpos, hi, vw, vr); \
;         if (__all(carry > 152.0f)) break;     \
;         kt -= 32; if (kt < 96) break; }
; __device__ __forceinline__ void sb_load(SbTile& t, const bf16* SK, const bf16* SV, int h, int kt, int lane) {
;     const bf16* kp = SK + (size_t)pos2row(kt + (lane & 31)) * 512 + h * 64 + 8 * (lane >> 5);
;     const bf16* vp = SV + (size_t)pos2row(kt + (lane >> 1)) * 512 + h * 64 + 32 * (lane & 1);
; #pragma unroll
;     for (int j = 0; j < 4; ++j) { t.k[j] = *(const bf16x8*)(kp + 16 * j); t.v[j] = *(const u32x4*)(vp + 8 * j); }
; }
; __device__ __forceinline__ void sb_strip(const bf16* SQ, const bf16* SK, const bf16* SV, bf16* OMIX, int h, int qpos0, int lane, LAS unsigned char* vl) {
;     ...
;     for (int kt = qpos0;;) { SB_STEP(t0, t2) SB_STEP(t1, t0) SB_STEP(t2, t1) }
.LBB0_1050:
	v_sub_f32_e32 v208, v208, v118
	v_cmp_lt_f32_e32 vcc, s45, v208
	s_cmp_eq_u64 vcc, exec
	s_cselect_b64 s[4:5], -1, 0
	s_or_b64 s[6:7], s[4:5], s[6:7]
	s_mov_b64 s[4:5], -1
	s_and_b64 vcc, exec, s[6:7]
	s_cbranch_vccnz .LBB0_1044
	s_add_i32 s4, s49, 32
	v_add_u32_e32 v0, 32, v206
	s_cmpk_gt_u32 s4, 0x7f
	v_max_u32_e32 v0, 0x70, v0
	v_add_u32_e32 v2, 0xffffffa0, v206
	v_add_u32_e32 v0, 0x3f90, v0
	s_cselect_b64 vcc, -1, 0
	v_cndmask_b32_e32 v0, v0, v2, vcc
	v_lshlrev_b64 v[2:3], 10, v[0:1]
	v_add_u32_e32 v0, 32, v207
	v_max_u32_e32 v0, 0x70, v0
	v_add_u32_e32 v4, 0xffffffa0, v207
	v_add_u32_e32 v0, 0x3f90, v0
	v_cndmask_b32_e32 v0, v0, v4, vcc
	v_lshlrev_b64 v[4:5], 10, v[0:1]
	v_lshl_add_u64 v[4:5], v[196:197], 0, v[4:5]
	v_lshl_add_u64 v[2:3], v[194:195], 0, v[2:3]
	v_mov_b32_e32 v222, s4
	v_lshlrev_b32_e32 v222, 7, v222
	v_mov_b32_e32 v223, 0
	v_lshl_add_u64 v[220:221], v[218:219], 0, v[222:223]
	v_lshl_add_u64 v[228:229], v[230:231], 0, v[222:223]
	global_load_dwordx4 v[118:121], v[228:229], off offset:3072
	global_load_dwordx4 v[126:129], v[228:229], off offset:2048
	global_load_dwordx4 v[130:133], v[228:229], off offset:1024
	global_load_dwordx4 v[134:137], v[228:229], off
	global_load_dwordx4 v[90:93], v[220:221], off
	global_load_dwordx4 v[94:97], v[220:221], off offset:1024
	global_load_dwordx4 v[86:89], v[220:221], off offset:2048
	global_load_dwordx4 v[82:85], v[220:221], off offset:3072
	v_exp_f32_e64 v0, -v208
	s_cmpk_lt_u32 s50, 0xa0
	s_cselect_b64 s[26:27], -1, 0
	s_cmpk_gt_u32 s50, 0x9f
	s_mov_b64 s[4:5], -1
	s_waitcnt vmcnt(24)
	ds_write_b128 v199, v[158:161]
	ds_write_b128 v199, v[154:157] offset:16
	ds_write_b128 v199, v[150:153] offset:32
	ds_write_b128 v199, v[146:149] offset:48
	s_cbranch_scc0 .LBB0_1053
; #define LAS __attribute__((address_space(3)))
; __device__ __forceinline__ unsigned cvtpk_s(float lo, float hi) { f32x2_t v = {lo, hi}; bf16x2_t b = __builtin_convertvector(v, bf16x2_t); return __builtin_bit_cast(unsigned, b); }
; template <bool MASK> __device__ __forceinline__ void sb_tile(const SbTile& t0, const bf16x8 (&qf)[4], f32x16& o0, f32x16& o1, float& carry, int kt, int qpos, int hi, LAS unsigned char* vw, const LAS unsigned char* vr) {
; #pragma unroll
;     for (int j = 0; j < 4; ++j) *(LAS u32x4*)(vw + 16 * j) = t0.v[j];
;     f32x16 z;
; #pragma unroll
;     for (int r = 0; r < 16; ++r) z[r] = 0.f;
; #pragma unroll
;     for (int j = 0; j < 4; ++j) z = MFMA32(t0.k[j], qf[j], z);
;     float kp[16], bt[16];
; #pragma unroll
;     for (int r = 0; r < 16; ++r) { const float e = __builtin_amdgcn_exp2f(z[r]); const float k = __builtin_amdgcn_rcpf(1.0f + e); const float b = e * k;
;         if (MASK) { const int kpos = kt + crow(r, hi); const bool okr = (kpos < qpos) && (kpos >= 112); kp[r] = okr ? k : 1.0f; bt[r] = okr ? b : 0.f; } else { kp[r] = k; bt[r] = b; } }
;     float G[4], Go[4];
; #pragma unroll
;     for (int g = 0; g < 4; ++g) { G[g] = (kp[4 * g] * kp[4 * g + 1]) * (kp[4 * g + 2] * kp[4 * g + 3]); Go[g] = __shfl_xor(G[g], 32); }
;     const float c0 = __builtin_amdgcn_exp2f(-carry);
;     float offs[4]; float T = 1.0f;
; #pragma unroll
;     for (int g = 3; g >= 0; --g) { offs[g] = c0 * T * (hi == 0 ? Go[g] : 1.0f); T *= G[g] * Go[g]; }
;     f32x16 w;
; #pragma unroll
;     for (int g = 0; g < 4; ++g) { float run = offs[g];
; #pragma unroll
;         for (int i = 3; i >= 0; --i) { const int r = 4 * g + i; w[r] = bt[r] * run; run *= kp[r]; } }
;     carry -= __builtin_amdgcn_logf(T);
; #pragma unroll
;     for (int s = 0; s < 2; ++s) { u32x4 wp;
; #pragma unroll
;         for (int i = 0; i < 4; ++i) wp[i] = cvtpk_s(w[8 * s + 2 * i], w[8 * s + 2 * i + 1]);
;         const bf16x8 wb = __builtin_bit_cast(bf16x8, wp);
;         const s16x4 a0 = vtr(vr + (16 * s) * 144), a1 = vtr(vr + (16 * s + 8) * 144), b0 = vtr(vr + (16 * s) * 144 + 64), b1 = vtr(vr + (16 * s + 8) * 144 + 64);
;         const bf16x8 v0 = __builtin_shufflevector(a0, a1, 0, 1, 2, 3, 4, 5, 6, 7), v1 = __builtin_shufflevector(b0, b1, 0, 1, 2, 3, 4, 5, 6, 7);
;         o0 = MFMA32(v0, wb, o0); o1 = MFMA32(v1, wb, o1); }
; }
	s_waitcnt vmcnt(19)
	v_mfma_f32_32x32x16_bf16 v[2:17], v[102:105], v[66:69], 0
	s_mov_b64 s[4:5], 0
	s_waitcnt vmcnt(18)
	v_mfma_f32_32x32x16_bf16 v[2:17], v[110:113], v[70:73], v[2:17]
	s_waitcnt vmcnt(17)
	v_mfma_f32_32x32x16_bf16 v[2:17], v[106:109], v[74:77], v[2:17]
	s_waitcnt vmcnt(16)
	v_mfma_f32_32x32x16_bf16 v[2:17], v[98:101], v[78:81], v[2:17]
	s_nop 11
	v_exp_f32_e32 v7, v7
	v_exp_f32_e32 v8, v8
	v_exp_f32_e32 v9, v9
	v_exp_f32_e32 v10, v10
	v_exp_f32_e32 v12, v12
	v_exp_f32_e32 v13, v13
	v_exp_f32_e32 v30, v14
	v_add_f32_e32 v23, 1.0, v7
	v_add_f32_e32 v25, 1.0, v8
	v_add_f32_e32 v26, 1.0, v9
	v_add_f32_e32 v27, 1.0, v10
	v_add_f32_e32 v29, 1.0, v12
	v_add_f32_e32 v14, 1.0, v13
	v_rcp_f32_e32 v24, v23
	v_rcp_f32_e32 v23, v25
	v_rcp_f32_e32 v25, v26
	v_rcp_f32_e32 v26, v27
	v_rcp_f32_e32 v27, v29
	v_rcp_f32_e32 v29, v14
	v_exp_f32_e32 v31, v15
	v_add_f32_e32 v14, 1.0, v30
	v_rcp_f32_e32 v32, v14
	v_exp_f32_e32 v14, v16
	v_exp_f32_e32 v15, v17
	v_exp_f32_e32 v11, v11
	v_add_f32_e32 v16, 1.0, v31
	v_exp_f32_e32 v6, v6
	v_rcp_f32_e32 v154, v16
	v_add_f32_e32 v16, 1.0, v14
	v_rcp_f32_e32 v33, v16
	v_add_f32_e32 v16, 1.0, v15
	v_add_f32_e32 v28, 1.0, v11
	v_rcp_f32_e32 v155, v16
	v_rcp_f32_e32 v28, v28
	v_add_f32_e32 v22, 1.0, v6
	v_and_b32_e32 v17, 64, v201
	v_exp_f32_e32 v4, v4
	v_exp_f32_e32 v5, v5
	v_rcp_f32_e32 v22, v22
	v_xor_b32_e32 v16, 32, v201
	v_add_u32_e32 v17, 64, v17
	v_exp_f32_e32 v2, v2
	v_exp_f32_e32 v3, v3
	v_cmp_lt_i32_e32 vcc, v16, v17
	v_pk_mul_f32 v[146:147], v[32:33], v[154:155]
	v_add_f32_e32 v20, 1.0, v4
	v_cndmask_b32_e32 v16, v201, v16, vcc
	v_mul_f32_e32 v148, v146, v147
	v_pk_mul_f32 v[146:147], v[26:27], v[28:29]
	v_lshlrev_b32_e32 v150, 2, v16
	v_mul_f32_e32 v146, v146, v147
	v_add_f32_e32 v21, 1.0, v5
	v_pk_mul_f32 v[16:17], v[22:23], v[24:25]
	ds_bpermute_b32 v149, v150, v148
	ds_bpermute_b32 v151, v150, v146
	v_add_f32_e32 v18, 1.0, v2
	v_add_f32_e32 v19, 1.0, v3
	v_rcp_f32_e32 v20, v20
	v_rcp_f32_e32 v21, v21
	v_pk_mul_f32 v[16:17], v[16:17], v[16:17] op_sel:[0,1] op_sel_hi:[1,0]
	v_rcp_f32_e32 v18, v18
	v_rcp_f32_e32 v19, v19
	ds_bpermute_b32 v17, v150, v16
	s_waitcnt lgkmcnt(2)
	v_cndmask_b32_e64 v152, 1.0, v149, s[0:1]
	v_mul_f32_e32 v147, v148, v149
	s_waitcnt lgkmcnt(1)
	v_mul_f32_e32 v149, v146, v151
	v_mov_b32_e32 v146, v20
	v_mov_b32_e32 v148, v21
	v_mul_f32_e32 v153, v0, v147
	v_pk_mul_f32 v[146:147], v[146:147], v[148:149]
	v_mov_b32_e32 v148, v18
	v_mov_b32_e32 v149, v16
	v_mov_b32_e32 v16, v19
	v_cndmask_b32_e64 v156, 1.0, v151, s[0:1]
	s_waitcnt lgkmcnt(0)
	v_cndmask_b32_e64 v151, 1.0, v17, s[0:1]
	v_pk_mul_f32 v[16:17], v[148:149], v[16:17]
	v_pk_mul_f32 v[4:5], v[4:5], v[20:21]
	v_pk_mul_f32 v[210:211], v[16:17], v[146:147]
	ds_bpermute_b32 v209, v150, v210
	v_mul_f32_e32 v16, v0, v211
	v_pk_mul_f32 v[2:3], v[2:3], v[18:19]
	v_mul_f32_e32 v146, v0, v147
	v_mov_b32_e32 v18, v22
	s_waitcnt lgkmcnt(0)
	v_cndmask_b32_e64 v17, 1.0, v209, s[0:1]
	v_mul_f32_e32 v17, v17, v16
	v_mul_f32_e32 v16, v21, v17
	v_pk_mul_f32 v[4:5], v[4:5], v[16:17]
	v_mul_f32_e32 v17, v20, v16
	v_mul_f32_e32 v16, v19, v17
	v_pk_mul_f32 v[2:3], v[2:3], v[16:17]
	v_mov_b32_e32 v16, v23
	v_mov_b32_e32 v17, v25
	v_pk_mul_f32 v[8:9], v[8:9], v[16:17]
	v_mul_f32_e32 v17, v151, v146
	v_mul_f32_e32 v16, v25, v17
	v_pk_mul_f32 v[8:9], v[8:9], v[16:17]
	v_mov_b32_e32 v19, v24
	v_mul_f32_e32 v17, v23, v16
	v_pk_mul_f32 v[6:7], v[6:7], v[18:19]
	v_mul_f32_e32 v16, v24, v17
	v_pk_mul_f32 v[6:7], v[6:7], v[16:17]
	v_mov_b32_e32 v16, v27
	v_mov_b32_e32 v17, v29
	v_pk_mul_f32 v[12:13], v[12:13], v[16:17]
	v_mul_f32_e32 v17, v156, v153
	v_mul_f32_e32 v16, v29, v17
	v_pk_mul_f32 v[158:159], v[12:13], v[16:17]
	v_mov_b32_e32 v12, v26
	v_mov_b32_e32 v13, v28
	ds_read_b64_tr_b16 v[18:19], v200
	ds_read_b64_tr_b16 v[20:21], v200 offset:1152
	v_pk_mul_f32 v[10:11], v[10:11], v[12:13]
	v_mul_f32_e32 v13, v27, v16
	v_mul_f32_e32 v23, v0, v152
	ds_read_b64_tr_b16 v[152:153], v200 offset:1216
	ds_read_b64_tr_b16 v[150:151], v200 offset:64
	v_mul_f32_e32 v12, v28, v13
	v_pk_mul_f32 v[160:161], v[10:11], v[12:13]
	v_mov_b32_e32 v10, v33
	v_mov_b32_e32 v11, v155
	v_pk_mul_f32 v[10:11], v[14:15], v[10:11]
	v_mul_f32_e32 v22, v155, v23
	v_cvt_pk_bf16_f32 v146, v2, v3
	v_cvt_pk_bf16_f32 v147, v4, v5
	v_cvt_pk_bf16_f32 v148, v6, v7
	v_cvt_pk_bf16_f32 v149, v8, v9
	v_pk_mul_f32 v[212:213], v[10:11], v[22:23]
	v_mul_f32_e32 v217, v33, v22
	s_waitcnt lgkmcnt(2)
	v_mfma_f32_32x32x16_bf16 v[2:17], v[18:21], v[146:149], v[34:49]
	v_mov_b32_e32 v18, v32
	v_mov_b32_e32 v19, v154
	v_mul_f32_e64 v214, v30, v18
	v_mul_f32_e64 v215, v31, v19
	v_mul_f32_e32 v216, v154, v217
	ds_read_b64_tr_b16 v[154:155], v200 offset:2304
	ds_read_b64_tr_b16 v[156:157], v200 offset:3456
	s_waitcnt lgkmcnt(2)
	v_mfma_f32_32x32x16_bf16 v[18:33], v[150:153], v[146:149], v[50:65]
	v_cvt_pk_bf16_f32 v148, v160, v161
	v_cvt_pk_bf16_f32 v149, v158, v159
	ds_read_b64_tr_b16 v[160:161], v200 offset:3520
	ds_read_b64_tr_b16 v[158:159], v200 offset:2368
	v_mul_f32_e64 v146, v214, v216
	v_mul_f32_e64 v147, v215, v217
	v_cvt_pk_bf16_f32 v151, v212, v213
	v_cvt_pk_bf16_f32 v150, v146, v147
	v_mul_f32_e32 v146, v210, v209
	v_mul_f32_e32 v146, v146, v211
	s_waitcnt lgkmcnt(2)
	v_mfma_f32_32x32x16_bf16 v[2:17], v[154:157], v[148:151], v[2:17]
	v_log_f32_e32 v146, v146
	s_waitcnt lgkmcnt(0)
	v_mfma_f32_32x32x16_bf16 v[18:33], v[158:161], v[148:151], v[18:33]

; #define SB_STEP(CUR, LD) { sb_load(LD, SK, SV, h, kt - 64, lane);     \
;         if (kt == qpos0 || kt < 128) sb_tile<true>(CUR, qf, o0, o1, carry, kt, qpos, hi, vw, vr); else sb_tile<false>(CUR, qf, o0, o1, carry, kt, qpos, hi, vw, vr); \
;         if (__all(carry > 152.0f)) break;     \
;         kt -= 32; if (kt < 96) break; }
; __device__ __forceinline__ void sb_load(SbTile& t, const bf16* SK, const bf16* SV, int h, int kt, int lane) {
;     const bf16* kp = SK + (size_t)pos2row(kt + (lane & 31)) * 512 + h * 64 + 8 * (lane >> 5);
;     const bf16* vp = SV + (size_t)pos2row(kt + (lane >> 1)) * 512 + h * 64 + 32 * (lane & 1);
; #pragma unroll
;     for (int j = 0; j < 4; ++j) { t.k[j] = *(const bf16x8*)(kp + 16 * j); t.v[j] = *(const u32x4*)(vp + 8 * j); }
; }
; __device__ __forceinline__ void sb_strip(const bf16* SQ, const bf16* SK, const bf16* SV, bf16* OMIX, int h, int qpos0, int lane, LAS unsigned char* vl) {
;     ...
;     for (int kt = qpos0;;) { SB_STEP(t0, t2) SB_STEP(t1, t0) SB_STEP(t2, t1) }
.LBB0_1055:
	v_sub_f32_e32 v208, v208, v146
	v_cmp_lt_f32_e32 vcc, s45, v208
	s_cmp_eq_u64 vcc, exec
	s_cselect_b64 s[4:5], -1, 0
	s_or_b64 s[6:7], s[26:27], s[4:5]
	s_mov_b64 s[4:5], -1
	s_and_b64 vcc, exec, s[6:7]
	s_cbranch_vccnz .LBB0_1061
	s_cmpk_gt_u32 s49, 0x7f
	v_max_u32_e32 v34, 0x70, v206
	v_add_u32_e32 v0, 0xffffff80, v206
	v_add_u32_e32 v34, 0x3f90, v34
	s_cselect_b64 vcc, -1, 0
	v_cndmask_b32_e32 v0, v34, v0, vcc
	v_max_u32_e32 v36, 0x70, v207
	v_lshlrev_b64 v[34:35], 10, v[0:1]
	v_add_u32_e32 v0, 0xffffff80, v207
	v_add_u32_e32 v36, 0x3f90, v36
	v_cndmask_b32_e32 v0, v36, v0, vcc
	v_lshlrev_b64 v[36:37], 10, v[0:1]
	v_lshl_add_u64 v[36:37], v[196:197], 0, v[36:37]
	v_lshl_add_u64 v[34:35], v[194:195], 0, v[34:35]
	v_mov_b32_e32 v222, s49
	v_lshlrev_b32_e32 v222, 7, v222
	v_mov_b32_e32 v223, 0
	v_lshl_add_u64 v[220:221], v[218:219], 0, v[222:223]
	v_lshl_add_u64 v[228:229], v[230:231], 0, v[222:223]
	global_load_dwordx4 v[146:149], v[228:229], off offset:3072
	global_load_dwordx4 v[150:153], v[228:229], off offset:2048
	global_load_dwordx4 v[154:157], v[228:229], off offset:1024
	global_load_dwordx4 v[158:161], v[228:229], off
	global_load_dwordx4 v[102:105], v[220:221], off
	global_load_dwordx4 v[110:113], v[220:221], off offset:1024
	global_load_dwordx4 v[106:109], v[220:221], off offset:2048
	global_load_dwordx4 v[98:101], v[220:221], off offset:3072
	v_exp_f32_e64 v0, -v208
	s_cmpk_lt_u32 s50, 0xc0
	s_cselect_b64 s[14:15], -1, 0
	s_cmpk_gt_u32 s50, 0xbf
	s_waitcnt vmcnt(20)
	ds_write_b128 v199, v[174:177]
	ds_write_b128 v199, v[170:173] offset:16
	ds_write_b128 v199, v[166:169] offset:32
	ds_write_b128 v199, v[162:165] offset:48
	s_cbranch_scc0 .LBB0_1058
; #define LAS __attribute__((address_space(3)))
; __device__ __forceinline__ unsigned cvtpk_s(float lo, float hi) { f32x2_t v = {lo, hi}; bf16x2_t b = __builtin_convertvector(v, bf16x2_t); return __builtin_bit_cast(unsigned, b); }
; template <bool MASK> __device__ __forceinline__ void sb_tile(const SbTile& t0, const bf16x8 (&qf)[4], f32x16& o0, f32x16& o1, float& carry, int kt, int qpos, int hi, LAS unsigned char* vw, const LAS unsigned char* vr) {
; #pragma unroll
;     for (int j = 0; j < 4; ++j) *(LAS u32x4*)(vw + 16 * j) = t0.v[j];
;     f32x16 z;
; #pragma unroll
;     for (int r = 0; r < 16; ++r) z[r] = 0.f;
; #pragma unroll
;     for (int j = 0; j < 4; ++j) z = MFMA32(t0.k[j], qf[j], z);
;     float kp[16], bt[16];
; #pragma unroll
;     for (int r = 0; r < 16; ++r) { const float e = __builtin_amdgcn_exp2f(z[r]); const float k = __builtin_amdgcn_rcpf(1.0f + e); const float b = e * k;
;         if (MASK) { const int kpos = kt + crow(r, hi); const bool okr = (kpos < qpos) && (kpos >= 112); kp[r] = okr ? k : 1.0f; bt[r] = okr ? b : 0.f; } else { kp[r] = k; bt[r] = b; } }
;     float G[4], Go[4];
; #pragma unroll
;     for (int g = 0; g < 4; ++g) { G[g] = (kp[4 * g] * kp[4 * g + 1]) * (kp[4 * g + 2] * kp[4 * g + 3]); Go[g] = __shfl_xor(G[g], 32); }
;     const float c0 = __builtin_amdgcn_exp2f(-carry);
;     float offs[4]; float T = 1.0f;
; #pragma unroll
;     for (int g = 3; g >= 0; --g) { offs[g] = c0 * T * (hi == 0 ? Go[g] : 1.0f); T *= G[g] * Go[g]; }
;     f32x16 w;
; #pragma unroll
;     for (int g = 0; g < 4; ++g) { float run = offs[g];
; #pragma unroll
;         for (int i = 3; i >= 0; --i) { const int r = 4 * g + i; w[r] = bt[r] * run; run *= kp[r]; } }
;     carry -= __builtin_amdgcn_logf(T);
; #pragma unroll
;     for (int s = 0; s < 2; ++s) { u32x4 wp;
; #pragma unroll
;         for (int i = 0; i < 4; ++i) wp[i] = cvtpk_s(w[8 * s + 2 * i], w[8 * s + 2 * i + 1]);
;         const bf16x8 wb = __builtin_bit_cast(bf16x8, wp);
;         const s16x4 a0 = vtr(vr + (16 * s) * 144), a1 = vtr(vr + (16 * s + 8) * 144), b0 = vtr(vr + (16 * s) * 144 + 64), b1 = vtr(vr + (16 * s + 8) * 144 + 64);
;         const bf16x8 v0 = __builtin_shufflevector(a0, a1, 0, 1, 2, 3, 4, 5, 6, 7), v1 = __builtin_shufflevector(b0, b1, 0, 1, 2, 3, 4, 5, 6, 7);
;         o0 = MFMA32(v0, wb, o0); o1 = MFMA32(v1, wb, o1); }
; }
	s_waitcnt vmcnt(19)
	v_mfma_f32_32x32x16_bf16 v[34:49], v[142:145], v[66:69], 0
	s_mov_b64 s[4:5], 0
	s_waitcnt vmcnt(18)
	v_mfma_f32_32x32x16_bf16 v[34:49], v[138:141], v[70:73], v[34:49]
	s_waitcnt vmcnt(17)
	v_mfma_f32_32x32x16_bf16 v[34:49], v[122:125], v[74:77], v[34:49]
	s_waitcnt vmcnt(16)
	v_mfma_f32_32x32x16_bf16 v[34:49], v[114:117], v[78:81], v[34:49]
	s_nop 11
	v_exp_f32_e32 v39, v39
	v_exp_f32_e32 v40, v40
	v_exp_f32_e32 v41, v41
	v_exp_f32_e32 v42, v42
	v_exp_f32_e32 v44, v44
	v_exp_f32_e32 v45, v45
	v_exp_f32_e32 v62, v46
	v_add_f32_e32 v55, 1.0, v39
	v_add_f32_e32 v57, 1.0, v40
	v_add_f32_e32 v58, 1.0, v41
	v_add_f32_e32 v59, 1.0, v42
	v_add_f32_e32 v61, 1.0, v44
	v_add_f32_e32 v46, 1.0, v45
	v_rcp_f32_e32 v56, v55
	v_rcp_f32_e32 v55, v57
	v_rcp_f32_e32 v57, v58
	v_rcp_f32_e32 v58, v59
	v_rcp_f32_e32 v59, v61
	v_rcp_f32_e32 v61, v46
	v_exp_f32_e32 v63, v47
	v_add_f32_e32 v46, 1.0, v62
	v_rcp_f32_e32 v64, v46
	v_exp_f32_e32 v46, v48
	v_exp_f32_e32 v47, v49
	v_exp_f32_e32 v43, v43
	v_add_f32_e32 v48, 1.0, v63
	v_exp_f32_e32 v38, v38
	v_rcp_f32_e32 v170, v48
	v_add_f32_e32 v48, 1.0, v46
	v_rcp_f32_e32 v65, v48
	v_add_f32_e32 v48, 1.0, v47
	v_add_f32_e32 v60, 1.0, v43
	v_rcp_f32_e32 v171, v48
	v_rcp_f32_e32 v60, v60
	v_add_f32_e32 v54, 1.0, v38
	v_and_b32_e32 v49, 64, v201
	v_exp_f32_e32 v36, v36
	v_exp_f32_e32 v37, v37
	v_rcp_f32_e32 v54, v54
	v_xor_b32_e32 v48, 32, v201
	v_add_u32_e32 v49, 64, v49
	v_exp_f32_e32 v34, v34
	v_exp_f32_e32 v35, v35
	v_cmp_lt_i32_e32 vcc, v48, v49
	v_pk_mul_f32 v[162:163], v[64:65], v[170:171]
	v_add_f32_e32 v52, 1.0, v36
	v_cndmask_b32_e32 v48, v201, v48, vcc
	v_mul_f32_e32 v164, v162, v163
	v_pk_mul_f32 v[162:163], v[58:59], v[60:61]
	v_lshlrev_b32_e32 v166, 2, v48
	v_mul_f32_e32 v162, v162, v163
	v_add_f32_e32 v53, 1.0, v37
	v_pk_mul_f32 v[48:49], v[54:55], v[56:57]
	ds_bpermute_b32 v165, v166, v164
	ds_bpermute_b32 v167, v166, v162
	v_add_f32_e32 v50, 1.0, v34
	v_add_f32_e32 v51, 1.0, v35
	v_rcp_f32_e32 v52, v52
	v_rcp_f32_e32 v53, v53
	v_pk_mul_f32 v[48:49], v[48:49], v[48:49] op_sel:[0,1] op_sel_hi:[1,0]
	v_rcp_f32_e32 v50, v50
	v_rcp_f32_e32 v51, v51
	ds_bpermute_b32 v49, v166, v48
	s_waitcnt lgkmcnt(2)
	v_cndmask_b32_e64 v168, 1.0, v165, s[0:1]
	v_mul_f32_e32 v163, v164, v165
	s_waitcnt lgkmcnt(1)
	v_mul_f32_e32 v165, v162, v167
	v_mov_b32_e32 v162, v52
	v_mov_b32_e32 v164, v53
	v_mul_f32_e32 v169, v0, v163
	v_pk_mul_f32 v[162:163], v[162:163], v[164:165]
	v_mov_b32_e32 v164, v50
	v_mov_b32_e32 v165, v48
	v_mov_b32_e32 v48, v51
	v_cndmask_b32_e64 v172, 1.0, v167, s[0:1]
	s_waitcnt lgkmcnt(0)
	v_cndmask_b32_e64 v167, 1.0, v49, s[0:1]
	v_pk_mul_f32 v[48:49], v[164:165], v[48:49]
	v_pk_mul_f32 v[36:37], v[36:37], v[52:53]
	v_pk_mul_f32 v[206:207], v[48:49], v[162:163]
	ds_bpermute_b32 v209, v166, v206
	v_mul_f32_e32 v48, v0, v207
	v_pk_mul_f32 v[34:35], v[34:35], v[50:51]
	v_mul_f32_e32 v162, v0, v163
	v_mov_b32_e32 v50, v54
	s_waitcnt lgkmcnt(0)
	v_cndmask_b32_e64 v49, 1.0, v209, s[0:1]
	v_mul_f32_e32 v49, v49, v48
	v_mul_f32_e32 v48, v53, v49
	v_pk_mul_f32 v[36:37], v[36:37], v[48:49]
	v_mul_f32_e32 v49, v52, v48
	v_mul_f32_e32 v48, v51, v49
	v_pk_mul_f32 v[34:35], v[34:35], v[48:49]
	v_mov_b32_e32 v48, v55
	v_mov_b32_e32 v49, v57
	v_pk_mul_f32 v[40:41], v[40:41], v[48:49]
	v_mul_f32_e32 v49, v167, v162
	v_mul_f32_e32 v48, v57, v49
	v_pk_mul_f32 v[40:41], v[40:41], v[48:49]
	v_mov_b32_e32 v51, v56
	v_mul_f32_e32 v49, v55, v48
	v_pk_mul_f32 v[38:39], v[38:39], v[50:51]
	v_mul_f32_e32 v48, v56, v49
	v_pk_mul_f32 v[38:39], v[38:39], v[48:49]
	v_mov_b32_e32 v48, v59
	v_mov_b32_e32 v49, v61
	v_pk_mul_f32 v[44:45], v[44:45], v[48:49]
	v_mul_f32_e32 v49, v172, v169
	v_mul_f32_e32 v48, v61, v49
	v_pk_mul_f32 v[174:175], v[44:45], v[48:49]
	v_mov_b32_e32 v44, v58
	v_mov_b32_e32 v45, v60
	ds_read_b64_tr_b16 v[50:51], v200
	ds_read_b64_tr_b16 v[52:53], v200 offset:1152
	v_pk_mul_f32 v[42:43], v[42:43], v[44:45]
	v_mul_f32_e32 v45, v59, v48
	v_mul_f32_e32 v55, v0, v168
	ds_read_b64_tr_b16 v[168:169], v200 offset:1216
	ds_read_b64_tr_b16 v[166:167], v200 offset:64
	v_mul_f32_e32 v44, v60, v45
	v_pk_mul_f32 v[176:177], v[42:43], v[44:45]
	v_mov_b32_e32 v42, v65
	v_mov_b32_e32 v43, v171
	v_pk_mul_f32 v[42:43], v[46:47], v[42:43]
	v_mul_f32_e32 v54, v171, v55
	v_cvt_pk_bf16_f32 v162, v34, v35
	v_cvt_pk_bf16_f32 v163, v36, v37
	v_cvt_pk_bf16_f32 v164, v38, v39
	v_cvt_pk_bf16_f32 v165, v40, v41
	v_pk_mul_f32 v[210:211], v[42:43], v[54:55]
	v_mul_f32_e32 v215, v65, v54
	s_waitcnt lgkmcnt(2)
	v_mfma_f32_32x32x16_bf16 v[34:49], v[50:53], v[162:165], v[2:17]
	v_mov_b32_e32 v50, v64
	v_mov_b32_e32 v51, v170
	v_mul_f32_e64 v212, v62, v50
	v_mul_f32_e64 v213, v63, v51
	v_mul_f32_e32 v214, v170, v215
	ds_read_b64_tr_b16 v[170:171], v200 offset:2304
	ds_read_b64_tr_b16 v[172:173], v200 offset:3456
	s_waitcnt lgkmcnt(2)
	v_mfma_f32_32x32x16_bf16 v[50:65], v[166:169], v[162:165], v[18:33]
	v_cvt_pk_bf16_f32 v164, v176, v177
	v_cvt_pk_bf16_f32 v165, v174, v175
	ds_read_b64_tr_b16 v[176:177], v200 offset:3520
	ds_read_b64_tr_b16 v[174:175], v200 offset:2368
	v_mul_f32_e64 v162, v212, v214
	v_mul_f32_e64 v163, v213, v215
	v_cvt_pk_bf16_f32 v167, v210, v211
	v_cvt_pk_bf16_f32 v166, v162, v163
	v_mul_f32_e32 v162, v206, v209
	v_mul_f32_e32 v162, v162, v207
	s_waitcnt lgkmcnt(2)
	v_mfma_f32_32x32x16_bf16 v[34:49], v[170:173], v[164:167], v[34:49]
	v_log_f32_e32 v162, v162
	s_waitcnt lgkmcnt(0)
	v_mfma_f32_32x32x16_bf16 v[50:65], v[174:177], v[164:167], v[50:65]

; #define PG8_STAGE(bufoff, gbase, voff) do { _Pragma("unroll") for (int _i = 0; _i < 2; ++_i) \
;         __builtin_amdgcn_global_load_lds((const unsigned*)((const char*)(gbase) + (voff)[_i]), (PG8_LAS unsigned*)(lds + (bufoff) + ldsw + _i * 8192), 16, 0, 0); } while (0)
; #define PG8_LDA(dst, b, h) do { _Pragma("unroll") for (int m = 0; m < 4; ++m) _Pragma("unroll") for (int k = 0; k < 2; ++k) dst[m][k] = *(const PG8_LAS bf16x8*)(lds + PG8_SA(b, h) + aoff + m * 2048 + k * 1024); } while (0)
; #define PG8_LDB(dst, b, h) do { _Pragma("unroll") for (int n = 0; n < 2; ++n) _Pragma("unroll") for (int k = 0; k < 2; ++k) dst[n][k] = *(const PG8_LAS bf16x8*)(lds + PG8_SB(b, h) + boff + n * 2048 + k * 1024); } while (0)
; #define PG8_MMA(ai, bj, At, Bt) do { __builtin_amdgcn_s_setprio(1); _Pragma("unroll") for (int m = 0; m < 4; ++m) _Pragma("unroll") for (int n = 0; n < 2; ++n) _Pragma("unroll") for (int k = 0; k < 2; ++k) \
;         acc[ai][bj][m][n] = __builtin_amdgcn_mfma_f32_16x16x32_bf16(Bt[n][k], At[m][k], acc[ai][bj][m][n], 0, 0, 0); __builtin_amdgcn_s_setprio(0); } while (0)
; #define PG8_WAIT_V(n) asm volatile("s_waitcnt vmcnt(" #n ")" ::: "memory")
; #define PG8_WAIT_L(n) asm volatile("s_waitcnt lgkmcnt(" #n ")" ::: "memory")
; #define PG8_BAR __builtin_amdgcn_s_barrier()
; #define PG8_SCHED __builtin_amdgcn_sched_barrier(0)
; template <class Epi, class Sched, bool ALIGN_EPI = false, bool SP2 = false>
; __device__ __forceinline__ void gemm_phase(PG8_LAS unsigned char* lds, const Gemm g, const Sched& S, const Epi& E) {
;     ...
;             PG8_LDB(B0, 0, 0); PG8_LDB(B1, 0, 1); PG8_SCHED; PG8_LDA(At, 0, 0); PG8_STAGE(PG8_SA(1, 1), a1 + hstep, voffA);
;             PG8_WAIT_V(8); PG8_WAIT_L(0); PG8_BAR; PG8_MMA(0, 0, At, B0); PG8_MMA(0, 1, At, B1); PG8_BAR; PG8_SCHED;
;             PG8_LDA(At, 0, 1); PG8_STAGE(PG8_SB(0, 0), b2, voffB); PG8_STAGE(PG8_SB(0, 1), b2 + hstep, voffB); PG8_STAGE(PG8_SA(0, 0), a2, voffA);
;             PG8_WAIT_V(8); PG8_WAIT_L(0); PG8_BAR; PG8_MMA(1, 0, At, B0); PG8_MMA(1, 1, At, B1); PG8_BAR; PG8_SCHED;
;     ...
; #pragma unroll
;         for (int a = 0; a < 2; ++a)
; #pragma unroll
;             for (int b = 0; b < 2; ++b)
; #pragma unroll
;                 for (int m = 0; m < 4; ++m)
; #pragma unroll
;                     for (int n = 0; n < 2; ++n) acc[a][b][m][n] = (f32x4){0.f, 0.f, 0.f, 0.f};
.LBB0_1360:
	s_ashr_i32 s15, s14, 31
	s_lshl_b64 s[16:17], s[14:15], 19
	v_readlane_b32 s18, v237, 35
	v_readlane_b32 s19, v237, 36
	s_add_u32 s16, s18, s16
	s_addc_u32 s17, s19, s17
	s_and_b64 s[18:19], s[0:1], exec
	s_cselect_b32 s15, s17, s23
	s_cselect_b32 s48, s16, s22
	s_ashr_i32 s13, s12, 31
	s_lshl_b64 s[18:19], s[12:13], 19
	s_add_u32 s18, s88, s18
	s_addc_u32 s19, s89, s19
	s_and_b64 s[26:27], s[0:1], exec
	s_cselect_b32 s13, s19, s25
	s_cselect_b32 s49, s18, s24
	s_add_u32 s22, s22, 0x40080
	s_addc_u32 s23, s23, 0
	s_add_u32 s50, s24, 0x100
	s_addc_u32 s51, s25, 0
	s_mov_b32 s52, -2
	ds_read_b128 v[144:147], v154
	ds_read_b128 v[158:161], v154 offset:1024
	ds_read_b128 v[162:165], v154 offset:2048
	ds_read_b128 v[166:169], v154 offset:3072
	ds_read_b128 v[170:173], v155
	ds_read_b128 v[174:177], v155 offset:1024
	ds_read_b128 v[180:183], v155 offset:2048
	ds_read_b128 v[184:187], v155 offset:3072
	s_add_u32 s24, s22, 0xfffc0080
	s_addc_u32 s25, s23, -1
	s_cmp_eq_u32 s52, 12
	s_cselect_b32 s27, s15, s25
	s_cselect_b32 s26, s48, s24
	s_cselect_b32 s25, s13, s51
	s_cselect_b32 s24, s49, s50
	v_lshl_add_u64 v[148:149], s[22:23], 0, v[136:137]
	s_add_i32 m0, s21, 0xc000
	ds_read_b128 v[188:191], v156
	ds_read_b128 v[192:195], v156 offset:1024
	ds_read_b128 v[196:199], v156 offset:2048
	ds_read_b128 v[200:203], v156 offset:3072
	ds_read_b128 v[204:207], v156 offset:4096
	ds_read_b128 v[208:211], v156 offset:5120
	ds_read_b128 v[212:215], v156 offset:6144
	ds_read_b128 v[216:219], v156 offset:7168
	global_load_lds_dwordx4 v[148:149], off
	v_lshl_add_u64 v[148:149], s[22:23], 0, v[138:139]
	s_add_i32 m0, s21, 0xe000
	s_nop 0
	global_load_lds_dwordx4 v[148:149], off
	s_waitcnt vmcnt(8)
	s_waitcnt lgkmcnt(0)
	s_barrier
	s_setprio 1
	s_waitcnt lgkmcnt(0)
	v_mfma_f32_16x16x32_bf16 v[124:127], v[144:147], v[188:191], 0
	v_mfma_f32_16x16x32_bf16 v[116:119], v[162:165], v[188:191], 0
	v_mfma_f32_16x16x32_bf16 v[108:111], v[144:147], v[196:199], 0
	v_mfma_f32_16x16x32_bf16 v[100:103], v[162:165], v[196:199], 0
	v_mfma_f32_16x16x32_bf16 v[92:95], v[144:147], v[204:207], 0
	v_mfma_f32_16x16x32_bf16 v[84:87], v[162:165], v[204:207], 0
	v_mfma_f32_16x16x32_bf16 v[76:79], v[144:147], v[212:215], 0
	v_mfma_f32_16x16x32_bf16 v[68:71], v[162:165], v[212:215], 0
	v_mfma_f32_16x16x32_bf16 v[124:127], v[158:161], v[192:195], v[124:127]
	v_mfma_f32_16x16x32_bf16 v[116:119], v[166:169], v[192:195], v[116:119]
	v_mfma_f32_16x16x32_bf16 v[108:111], v[158:161], v[200:203], v[108:111]
	v_mfma_f32_16x16x32_bf16 v[100:103], v[166:169], v[200:203], v[100:103]
	v_mfma_f32_16x16x32_bf16 v[92:95], v[158:161], v[208:211], v[92:95]
	v_mfma_f32_16x16x32_bf16 v[84:87], v[166:169], v[208:211], v[84:87]
	v_mfma_f32_16x16x32_bf16 v[76:79], v[158:161], v[216:219], v[76:79]
	v_mfma_f32_16x16x32_bf16 v[68:71], v[166:169], v[216:219], v[68:71]
	s_setprio 0
	s_setprio 1
	v_mfma_f32_16x16x32_bf16 v[120:123], v[170:173], v[188:191], 0
	v_mfma_f32_16x16x32_bf16 v[112:115], v[180:183], v[188:191], 0
	v_mfma_f32_16x16x32_bf16 v[104:107], v[170:173], v[196:199], 0
	v_mfma_f32_16x16x32_bf16 v[96:99], v[180:183], v[196:199], 0
	v_mfma_f32_16x16x32_bf16 v[88:91], v[170:173], v[204:207], 0
	v_mfma_f32_16x16x32_bf16 v[80:83], v[180:183], v[204:207], 0
	v_mfma_f32_16x16x32_bf16 v[72:75], v[170:173], v[212:215], 0
	v_mfma_f32_16x16x32_bf16 v[64:67], v[180:183], v[212:215], 0
	v_mfma_f32_16x16x32_bf16 v[120:123], v[174:177], v[192:195], v[120:123]
	v_mfma_f32_16x16x32_bf16 v[112:115], v[184:187], v[192:195], v[112:115]
	v_mfma_f32_16x16x32_bf16 v[104:107], v[174:177], v[200:203], v[104:107]
	v_mfma_f32_16x16x32_bf16 v[96:99], v[184:187], v[200:203], v[96:99]
	v_mfma_f32_16x16x32_bf16 v[88:91], v[174:177], v[208:211], v[88:91]
	v_mfma_f32_16x16x32_bf16 v[80:83], v[184:187], v[208:211], v[80:83]
	v_mfma_f32_16x16x32_bf16 v[72:75], v[174:177], v[216:219], v[72:75]
	v_mfma_f32_16x16x32_bf16 v[64:67], v[184:187], v[216:219], v[64:67]
	s_setprio 0
	s_barrier
	s_add_i32 s53, s38, s28
	v_lshl_add_u64 v[148:149], s[24:25], 0, v[132:133]
	s_mov_b32 m0, s53
	ds_read_b128 v[188:191], v156 offset:16384
	ds_read_b128 v[192:195], v156 offset:17408
	ds_read_b128 v[196:199], v156 offset:18432
	ds_read_b128 v[200:203], v156 offset:19456
	ds_read_b128 v[204:207], v156 offset:20480
	ds_read_b128 v[208:211], v156 offset:21504
	ds_read_b128 v[212:215], v156 offset:22528
	ds_read_b128 v[216:219], v156 offset:23552
	global_load_lds_dwordx4 v[148:149], off
	s_add_i32 m0, s53, 0x2000
	s_add_u32 s54, s24, 0x40000
	v_lshl_add_u64 v[220:221], s[24:25], 0, v[128:129]
	s_addc_u32 s55, s25, 0
	s_add_i32 s53, s39, s28
	global_load_lds_dwordx4 v[220:221], off
	v_lshl_add_u64 v[222:223], s[54:55], 0, v[132:133]
	s_mov_b32 m0, s53
	v_lshl_add_u64 v[224:225], s[26:27], 0, v[130:131]
	global_load_lds_dwordx4 v[222:223], off
	v_lshl_add_u64 v[222:223], s[54:55], 0, v[128:129]
	s_add_i32 m0, s53, 0x2000
	s_nop 0
	global_load_lds_dwordx4 v[222:223], off
	v_lshl_add_u64 v[222:223], s[26:27], 0, v[134:135]
	s_mov_b32 m0, s21
	s_nop 0
	global_load_lds_dwordx4 v[222:223], off
	s_mov_b32 m0, s29
	s_nop 0
	global_load_lds_dwordx4 v[224:225], off
	s_waitcnt vmcnt(8)
	s_waitcnt lgkmcnt(0)
	s_barrier
; #define PG8_STAGE(bufoff, gbase, voff) do { _Pragma("unroll") for (int _i = 0; _i < 2; ++_i) \
;         __builtin_amdgcn_global_load_lds((const unsigned*)((const char*)(gbase) + (voff)[_i]), (PG8_LAS unsigned*)(lds + (bufoff) + ldsw + _i * 8192), 16, 0, 0); } while (0)
; #define PG8_LDA(dst, b, h) do { _Pragma("unroll") for (int m = 0; m < 4; ++m) _Pragma("unroll") for (int k = 0; k < 2; ++k) dst[m][k] = *(const PG8_LAS bf16x8*)(lds + PG8_SA(b, h) + aoff + m * 2048 + k * 1024); } while (0)
; #define PG8_LDB(dst, b, h) do { _Pragma("unroll") for (int n = 0; n < 2; ++n) _Pragma("unroll") for (int k = 0; k < 2; ++k) dst[n][k] = *(const PG8_LAS bf16x8*)(lds + PG8_SB(b, h) + boff + n * 2048 + k * 1024); } while (0)
; #define PG8_MMA(ai, bj, At, Bt) do { __builtin_amdgcn_s_setprio(1); _Pragma("unroll") for (int m = 0; m < 4; ++m) _Pragma("unroll") for (int n = 0; n < 2; ++n) _Pragma("unroll") for (int k = 0; k < 2; ++k) \
;         acc[ai][bj][m][n] = __builtin_amdgcn_mfma_f32_16x16x32_bf16(Bt[n][k], At[m][k], acc[ai][bj][m][n], 0, 0, 0); __builtin_amdgcn_s_setprio(0); } while (0)
; #define PG8_WAIT_V(n) asm volatile("s_waitcnt vmcnt(" #n ")" ::: "memory")
; #define PG8_WAIT_L(n) asm volatile("s_waitcnt lgkmcnt(" #n ")" ::: "memory")
; #define PG8_BAR __builtin_amdgcn_s_barrier()
; #define PG8_SCHED __builtin_amdgcn_sched_barrier(0)
; template <class Epi, class Sched, bool ALIGN_EPI = false, bool SP2 = false>
; __device__ __forceinline__ void gemm_phase(PG8_LAS unsigned char* lds, const Gemm g, const Sched& S, const Epi& E) {
;     ...
;             PG8_WAIT_V(8); PG8_WAIT_L(0); PG8_BAR; PG8_MMA(1, 0, At, B0); PG8_MMA(1, 1, At, B1); PG8_BAR; PG8_SCHED;
;             PG8_LDB(B0, 1, 0); PG8_LDB(B1, 1, 1); PG8_SCHED; PG8_LDA(At, 1, 0); PG8_STAGE(PG8_SA(0, 1), a2 + hstep, voffA);
;             PG8_WAIT_V(8); PG8_WAIT_L(0); PG8_BAR; PG8_MMA(0, 0, At, B0); PG8_MMA(0, 1, At, B1); PG8_BAR; PG8_SCHED;
;             PG8_LDA(At, 1, 1); PG8_STAGE(PG8_SB(1, 0), b3, voffB); PG8_STAGE(PG8_SB(1, 1), b3 + hstep, voffB); PG8_STAGE(PG8_SA(1, 0), a3, voffA);
;             PG8_WAIT_V(8); PG8_WAIT_L(0); PG8_BAR; PG8_MMA(1, 0, At, B0); PG8_MMA(1, 1, At, B1); PG8_BAR; PG8_SCHED;
	s_setprio 1
	s_waitcnt lgkmcnt(0)
	v_mfma_f32_16x16x32_bf16 v[60:63], v[144:147], v[188:191], 0
	v_mfma_f32_16x16x32_bf16 v[52:55], v[162:165], v[188:191], 0
	v_mfma_f32_16x16x32_bf16 v[44:47], v[144:147], v[196:199], 0
	v_mfma_f32_16x16x32_bf16 v[36:39], v[162:165], v[196:199], 0
	v_mfma_f32_16x16x32_bf16 v[28:31], v[144:147], v[204:207], 0
	v_mfma_f32_16x16x32_bf16 v[20:23], v[162:165], v[204:207], 0
	v_mfma_f32_16x16x32_bf16 v[12:15], v[144:147], v[212:215], 0
	v_mfma_f32_16x16x32_bf16 v[4:7], v[162:165], v[212:215], 0
	v_mfma_f32_16x16x32_bf16 v[60:63], v[158:161], v[192:195], v[60:63]
	v_mfma_f32_16x16x32_bf16 v[52:55], v[166:169], v[192:195], v[52:55]
	v_mfma_f32_16x16x32_bf16 v[44:47], v[158:161], v[200:203], v[44:47]
	v_mfma_f32_16x16x32_bf16 v[36:39], v[166:169], v[200:203], v[36:39]
	v_mfma_f32_16x16x32_bf16 v[28:31], v[158:161], v[208:211], v[28:31]
	v_mfma_f32_16x16x32_bf16 v[20:23], v[166:169], v[208:211], v[20:23]
	v_mfma_f32_16x16x32_bf16 v[12:15], v[158:161], v[216:219], v[12:15]
	v_mfma_f32_16x16x32_bf16 v[4:7], v[166:169], v[216:219], v[4:7]
	s_setprio 0
	s_setprio 1
	v_mfma_f32_16x16x32_bf16 v[56:59], v[170:173], v[188:191], 0
	v_mfma_f32_16x16x32_bf16 v[48:51], v[180:183], v[188:191], 0
	v_mfma_f32_16x16x32_bf16 v[40:43], v[170:173], v[196:199], 0
	v_mfma_f32_16x16x32_bf16 v[32:35], v[180:183], v[196:199], 0
	v_mfma_f32_16x16x32_bf16 v[24:27], v[170:173], v[204:207], 0
	v_mfma_f32_16x16x32_bf16 v[16:19], v[180:183], v[204:207], 0
	v_mfma_f32_16x16x32_bf16 v[8:11], v[170:173], v[212:215], 0
	v_mfma_f32_16x16x32_bf16 v[0:3], v[180:183], v[212:215], 0
	v_mfma_f32_16x16x32_bf16 v[56:59], v[174:177], v[192:195], v[56:59]
	v_mfma_f32_16x16x32_bf16 v[48:51], v[184:187], v[192:195], v[48:51]
	v_mfma_f32_16x16x32_bf16 v[40:43], v[174:177], v[200:203], v[40:43]
	v_mfma_f32_16x16x32_bf16 v[32:35], v[184:187], v[200:203], v[32:35]
	v_mfma_f32_16x16x32_bf16 v[24:27], v[174:177], v[208:211], v[24:27]
	v_mfma_f32_16x16x32_bf16 v[16:19], v[184:187], v[208:211], v[16:19]
	v_mfma_f32_16x16x32_bf16 v[8:11], v[174:177], v[216:219], v[8:11]
	v_mfma_f32_16x16x32_bf16 v[0:3], v[184:187], v[216:219], v[0:3]
	s_setprio 0
	s_barrier
	s_add_i32 s53, 0, 0x18000
	v_add_u32_e32 v157, s53, v151
	s_add_i32 s54, 0, 0x1c000
	ds_read_b128 v[144:147], v157
	ds_read_b128 v[158:161], v157 offset:1024
	ds_read_b128 v[162:165], v157 offset:2048
	ds_read_b128 v[166:169], v157 offset:3072
	v_add_u32_e32 v157, s54, v151
	ds_read_b128 v[170:173], v157
	ds_read_b128 v[174:177], v157 offset:1024
	ds_read_b128 v[180:183], v157 offset:2048
	ds_read_b128 v[184:187], v157 offset:3072
	s_add_u32 s26, s26, 0x40000
	s_addc_u32 s27, s27, 0
	s_mov_b32 m0, s30
	v_lshl_add_u64 v[226:227], s[26:27], 0, v[134:135]
	ds_read_b128 v[188:191], v156 offset:32768
	ds_read_b128 v[192:195], v156 offset:33792
	ds_read_b128 v[196:199], v156 offset:34816
	ds_read_b128 v[200:203], v156 offset:35840
	ds_read_b128 v[204:207], v156 offset:36864
	ds_read_b128 v[208:211], v156 offset:37888
	ds_read_b128 v[212:215], v156 offset:38912
	ds_read_b128 v[216:219], v156 offset:39936
	global_load_lds_dwordx4 v[226:227], off
	v_lshl_add_u64 v[226:227], s[26:27], 0, v[130:131]
	s_mov_b32 m0, s31
	s_nop 0
	global_load_lds_dwordx4 v[226:227], off
	s_waitcnt vmcnt(8)
	s_waitcnt lgkmcnt(0)
	s_barrier
	s_setprio 1
	s_waitcnt lgkmcnt(0)
	v_mfma_f32_16x16x32_bf16 v[124:127], v[144:147], v[188:191], v[124:127]
	v_mfma_f32_16x16x32_bf16 v[116:119], v[162:165], v[188:191], v[116:119]
	v_mfma_f32_16x16x32_bf16 v[108:111], v[144:147], v[196:199], v[108:111]
	v_mfma_f32_16x16x32_bf16 v[100:103], v[162:165], v[196:199], v[100:103]
	v_mfma_f32_16x16x32_bf16 v[92:95], v[144:147], v[204:207], v[92:95]
	v_mfma_f32_16x16x32_bf16 v[84:87], v[162:165], v[204:207], v[84:87]
	v_mfma_f32_16x16x32_bf16 v[76:79], v[144:147], v[212:215], v[76:79]
	v_mfma_f32_16x16x32_bf16 v[68:71], v[162:165], v[212:215], v[68:71]
	v_mfma_f32_16x16x32_bf16 v[124:127], v[158:161], v[192:195], v[124:127]
	v_mfma_f32_16x16x32_bf16 v[116:119], v[166:169], v[192:195], v[116:119]
	v_mfma_f32_16x16x32_bf16 v[108:111], v[158:161], v[200:203], v[108:111]
	v_mfma_f32_16x16x32_bf16 v[100:103], v[166:169], v[200:203], v[100:103]
	v_mfma_f32_16x16x32_bf16 v[92:95], v[158:161], v[208:211], v[92:95]
	v_mfma_f32_16x16x32_bf16 v[84:87], v[166:169], v[208:211], v[84:87]
	v_mfma_f32_16x16x32_bf16 v[76:79], v[158:161], v[216:219], v[76:79]
	v_mfma_f32_16x16x32_bf16 v[68:71], v[166:169], v[216:219], v[68:71]
	s_setprio 0
	s_setprio 1
	v_mfma_f32_16x16x32_bf16 v[120:123], v[170:173], v[188:191], v[120:123]
	v_mfma_f32_16x16x32_bf16 v[112:115], v[180:183], v[188:191], v[112:115]
	v_mfma_f32_16x16x32_bf16 v[104:107], v[170:173], v[196:199], v[104:107]
	v_mfma_f32_16x16x32_bf16 v[96:99], v[180:183], v[196:199], v[96:99]
	v_mfma_f32_16x16x32_bf16 v[88:91], v[170:173], v[204:207], v[88:91]
	v_mfma_f32_16x16x32_bf16 v[80:83], v[180:183], v[204:207], v[80:83]
	v_mfma_f32_16x16x32_bf16 v[72:75], v[170:173], v[212:215], v[72:75]
	v_mfma_f32_16x16x32_bf16 v[64:67], v[180:183], v[212:215], v[64:67]
	v_mfma_f32_16x16x32_bf16 v[120:123], v[174:177], v[192:195], v[120:123]
	v_mfma_f32_16x16x32_bf16 v[112:115], v[184:187], v[192:195], v[112:115]
	v_mfma_f32_16x16x32_bf16 v[104:107], v[174:177], v[200:203], v[104:107]
	v_mfma_f32_16x16x32_bf16 v[96:99], v[184:187], v[200:203], v[96:99]
	v_mfma_f32_16x16x32_bf16 v[88:91], v[174:177], v[208:211], v[88:91]
	v_mfma_f32_16x16x32_bf16 v[80:83], v[184:187], v[208:211], v[80:83]
	v_mfma_f32_16x16x32_bf16 v[72:75], v[174:177], v[216:219], v[72:75]
	v_mfma_f32_16x16x32_bf16 v[64:67], v[184:187], v[216:219], v[64:67]
	s_setprio 0
	s_barrier
; #define PG8_STAGE(bufoff, gbase, voff) do { _Pragma("unroll") for (int _i = 0; _i < 2; ++_i) \
;         __builtin_amdgcn_global_load_lds((const unsigned*)((const char*)(gbase) + (voff)[_i]), (PG8_LAS unsigned*)(lds + (bufoff) + ldsw + _i * 8192), 16, 0, 0); } while (0)
; #define PG8_LDA(dst, b, h) do { _Pragma("unroll") for (int m = 0; m < 4; ++m) _Pragma("unroll") for (int k = 0; k < 2; ++k) dst[m][k] = *(const PG8_LAS bf16x8*)(lds + PG8_SA(b, h) + aoff + m * 2048 + k * 1024); } while (0)
; #define PG8_MMA(ai, bj, At, Bt) do { __builtin_amdgcn_s_setprio(1); _Pragma("unroll") for (int m = 0; m < 4; ++m) _Pragma("unroll") for (int n = 0; n < 2; ++n) _Pragma("unroll") for (int k = 0; k < 2; ++k) \
;         acc[ai][bj][m][n] = __builtin_amdgcn_mfma_f32_16x16x32_bf16(Bt[n][k], At[m][k], acc[ai][bj][m][n], 0, 0, 0); __builtin_amdgcn_s_setprio(0); } while (0)
; #define PG8_WAIT_V(n) asm volatile("s_waitcnt vmcnt(" #n ")" ::: "memory")
; #define PG8_WAIT_L(n) asm volatile("s_waitcnt lgkmcnt(" #n ")" ::: "memory")
; #define PG8_BAR __builtin_amdgcn_s_barrier()
; #define PG8_SCHED __builtin_amdgcn_sched_barrier(0)
; template <class Epi, class Sched, bool ALIGN_EPI = false, bool SP2 = false>
; __device__ __forceinline__ void gemm_phase(PG8_LAS unsigned char* lds, const Gemm g, const Sched& S, const Epi& E) {
;     ...
;             PG8_LDA(At, 1, 1); PG8_STAGE(PG8_SB(1, 0), b3, voffB); PG8_STAGE(PG8_SB(1, 1), b3 + hstep, voffB); PG8_STAGE(PG8_SA(1, 0), a3, voffA);
;             PG8_WAIT_V(8); PG8_WAIT_L(0); PG8_BAR; PG8_MMA(1, 0, At, B0); PG8_MMA(1, 1, At, B1); PG8_BAR; PG8_SCHED;
	s_add_i32 s26, s53, s28
	v_lshl_add_u64 v[148:149], v[148:149], 0, s[8:9]
	s_mov_b32 m0, s26
	ds_read_b128 v[188:191], v156 offset:49152
	ds_read_b128 v[192:195], v156 offset:50176
	ds_read_b128 v[196:199], v156 offset:51200
	ds_read_b128 v[200:203], v156 offset:52224
	ds_read_b128 v[204:207], v156 offset:53248
	ds_read_b128 v[208:211], v156 offset:54272
	ds_read_b128 v[212:215], v156 offset:55296
	ds_read_b128 v[216:219], v156 offset:56320
	global_load_lds_dwordx4 v[148:149], off
	s_add_i32 m0, s26, 0x2000
	s_add_u32 s24, s24, 0x40080
	v_lshl_add_u64 v[148:149], v[220:221], 0, s[8:9]
	s_addc_u32 s25, s25, 0
	s_add_i32 s26, s54, s28
	global_load_lds_dwordx4 v[148:149], off
	v_lshl_add_u64 v[148:149], s[24:25], 0, v[132:133]
	s_mov_b32 m0, s26
	s_nop 0
	global_load_lds_dwordx4 v[148:149], off
	v_lshl_add_u64 v[148:149], s[24:25], 0, v[128:129]
	s_add_i32 m0, s26, 0x2000
	s_nop 0
	global_load_lds_dwordx4 v[148:149], off
	v_lshl_add_u64 v[148:149], v[222:223], 0, s[8:9]
	s_mov_b32 m0, s35
	s_nop 0
	global_load_lds_dwordx4 v[148:149], off
	v_lshl_add_u64 v[148:149], v[224:225], 0, s[8:9]
	s_mov_b32 m0, s36
	s_nop 0
	global_load_lds_dwordx4 v[148:149], off
	s_waitcnt vmcnt(8)
	s_waitcnt lgkmcnt(0)
	s_barrier
	s_setprio 1
	s_waitcnt lgkmcnt(0)
	v_mfma_f32_16x16x32_bf16 v[60:63], v[144:147], v[188:191], v[60:63]
	v_mfma_f32_16x16x32_bf16 v[52:55], v[162:165], v[188:191], v[52:55]
	v_mfma_f32_16x16x32_bf16 v[44:47], v[144:147], v[196:199], v[44:47]
	v_mfma_f32_16x16x32_bf16 v[36:39], v[162:165], v[196:199], v[36:39]
	v_mfma_f32_16x16x32_bf16 v[28:31], v[144:147], v[204:207], v[28:31]
	v_mfma_f32_16x16x32_bf16 v[20:23], v[162:165], v[204:207], v[20:23]
	v_mfma_f32_16x16x32_bf16 v[12:15], v[144:147], v[212:215], v[12:15]
	v_mfma_f32_16x16x32_bf16 v[4:7], v[162:165], v[212:215], v[4:7]
	v_mfma_f32_16x16x32_bf16 v[60:63], v[158:161], v[192:195], v[60:63]
	v_mfma_f32_16x16x32_bf16 v[52:55], v[166:169], v[192:195], v[52:55]
	v_mfma_f32_16x16x32_bf16 v[44:47], v[158:161], v[200:203], v[44:47]
	v_mfma_f32_16x16x32_bf16 v[36:39], v[166:169], v[200:203], v[36:39]
	v_mfma_f32_16x16x32_bf16 v[28:31], v[158:161], v[208:211], v[28:31]
	v_mfma_f32_16x16x32_bf16 v[20:23], v[166:169], v[208:211], v[20:23]
	v_mfma_f32_16x16x32_bf16 v[12:15], v[158:161], v[216:219], v[12:15]
	v_mfma_f32_16x16x32_bf16 v[4:7], v[166:169], v[216:219], v[4:7]
	s_setprio 0
	s_setprio 1
	v_mfma_f32_16x16x32_bf16 v[56:59], v[170:173], v[188:191], v[56:59]
	v_mfma_f32_16x16x32_bf16 v[48:51], v[180:183], v[188:191], v[48:51]
	v_mfma_f32_16x16x32_bf16 v[40:43], v[170:173], v[196:199], v[40:43]
	v_mfma_f32_16x16x32_bf16 v[32:35], v[180:183], v[196:199], v[32:35]
	v_mfma_f32_16x16x32_bf16 v[24:27], v[170:173], v[204:207], v[24:27]
	v_mfma_f32_16x16x32_bf16 v[16:19], v[180:183], v[204:207], v[16:19]
	v_mfma_f32_16x16x32_bf16 v[8:11], v[170:173], v[212:215], v[8:11]
	v_mfma_f32_16x16x32_bf16 v[0:3], v[180:183], v[212:215], v[0:3]
	v_mfma_f32_16x16x32_bf16 v[56:59], v[174:177], v[192:195], v[56:59]
	v_mfma_f32_16x16x32_bf16 v[48:51], v[184:187], v[192:195], v[48:51]
	v_mfma_f32_16x16x32_bf16 v[40:43], v[174:177], v[200:203], v[40:43]
	v_mfma_f32_16x16x32_bf16 v[32:35], v[184:187], v[200:203], v[32:35]
	v_mfma_f32_16x16x32_bf16 v[24:27], v[174:177], v[208:211], v[24:27]
	v_mfma_f32_16x16x32_bf16 v[16:19], v[184:187], v[208:211], v[16:19]
	v_mfma_f32_16x16x32_bf16 v[8:11], v[174:177], v[216:219], v[8:11]
	v_mfma_f32_16x16x32_bf16 v[0:3], v[184:187], v[216:219], v[0:3]
	s_setprio 0
	s_barrier
	s_add_i32 s52, s52, 2
	s_add_u32 s22, s22, 0x100
	s_addc_u32 s23, s23, 0
	s_add_u32 s50, s50, 0x100
	s_addc_u32 s51, s51, 0
	s_cmp_gt_u32 s52, 13
	s_cbranch_scc0 .LBB0_1361
